# v16 + redundant lgkmcnt(0) after each loop barrier dropped and the vmcnt(8)/lgkmcnt(0) wait pair merged into one s_waitcnt
# baseline (speedup 1.0000x reference)
; #define PG8_STAGE(bufoff, gbase, voff) do { _Pragma("unroll") for (int _i = 0; _i < 2; ++_i) \
;         __builtin_amdgcn_global_load_lds((const unsigned*)((const char*)(gbase) + (voff)[_i]), (PG8_LAS unsigned*)(lds + (bufoff) + ldsw + _i * 8192), 16, 0, 0); } while (0)
; #define PG8_LDA(dst, b, h) do { _Pragma("unroll") for (int m = 0; m < 4; ++m) _Pragma("unroll") for (int k = 0; k < 2; ++k) dst[m][k] = *(const PG8_LAS bf16x8*)(lds + PG8_SA(b, h) + aoff + m * 2048 + k * 1024); } while (0)
; #define PG8_LDB(dst, b, h) do { _Pragma("unroll") for (int n = 0; n < 2; ++n) _Pragma("unroll") for (int k = 0; k < 2; ++k) dst[n][k] = *(const PG8_LAS bf16x8*)(lds + PG8_SB(b, h) + boff + n * 2048 + k * 1024); } while (0)
; #define PG8_MMA(ai, bj, At, Bt) do { __builtin_amdgcn_s_setprio(1); _Pragma("unroll") for (int m = 0; m < 4; ++m) _Pragma("unroll") for (int n = 0; n < 2; ++n) _Pragma("unroll") for (int k = 0; k < 2; ++k) \
;         acc[ai][bj][m][n] = __builtin_amdgcn_mfma_f32_16x16x32_bf16(Bt[n][k], At[m][k], acc[ai][bj][m][n], 0, 0, 0); __builtin_amdgcn_s_setprio(0); } while (0)
; #define PG8_WAIT_V(n) asm volatile("s_waitcnt vmcnt(" #n ")" ::: "memory")
; #define PG8_WAIT_L(n) asm volatile("s_waitcnt lgkmcnt(" #n ")" ::: "memory")
; template <class Epi, class Sched, bool ALIGN_EPI = false, bool SP2 = false>
; __device__ __forceinline__ void gemm_phase(PG8_LAS unsigned char* lds, const Gemm g, const Sched& S, const Epi& E) {
;     ...
;             const bool last = (t == nt - 2);
;             const char* a1 = cA + (size_t)(t + 1) * kstep;
;             const char* a2 = last ? nA : cA + (size_t)(t + 2) * kstep; const char* b2 = last ? nB : cB + (size_t)(t + 2) * kstep;
;             const char* a3 = a2 + kstep; const char* b3 = b2 + kstep;
;             if (last && has_next) S.a_ready(nxt);
;             if constexpr (SP2) {
;             PG8_LDB(B0, 0, 0); PG8_LDB(B1, 0, 1); PG8_SCHED; PG8_LDA(At, 0, 0); PG8_STAGE(PG8_SA(1, 1), a1 + hstep, voffA);
;             PG8_WAIT_V(8); PG8_WAIT_L(0); PG8_BAR; PG8_MMA(0, 0, At, B0); PG8_MMA(0, 1, At, B1); PG8_BAR; PG8_SCHED;
;             PG8_LDA(At, 0, 1); PG8_STAGE(PG8_SB(0, 0), b2, voffB); PG8_STAGE(PG8_SB(0, 1), b2 + hstep, voffB); PG8_STAGE(PG8_SA(0, 0), a2, voffA);
;             PG8_WAIT_V(8); PG8_WAIT_L(0); PG8_BAR; PG8_MMA(1, 0, At, B0); PG8_MMA(1, 1, At, B1); PG8_BAR; PG8_SCHED;
.LBB0_673:
	ds_read_b128 v[148:151], v241 offset:0
	ds_read_b128 v[156:159], v241 offset:1024
	ds_read_b128 v[166:169], v241 offset:2048
	ds_read_b128 v[170:173], v241 offset:3072
	ds_read_b128 v[174:177], v241 offset:16384
	ds_read_b128 v[178:181], v241 offset:17408
	ds_read_b128 v[182:185], v241 offset:18432
	ds_read_b128 v[186:189], v241 offset:19456
	s_add_u32 s20, s22, 0xfff00080
	s_addc_u32 s21, s23, -1
	s_cmp_eq_u32 s35, 60
	s_cselect_b32 s25, s11, s21
	s_cselect_b32 s24, s52, s20
	s_cselect_b32 s21, s13, s34
	s_cselect_b32 s20, s53, s62
	s_add_i32 m0, s19, 0xc000
	ds_read_b128 v[190:193], v161
	ds_read_b128 v[194:197], v161 offset:1024
	ds_read_b128 v[198:201], v161 offset:2048
	ds_read_b128 v[202:205], v161 offset:3072
	ds_read_b128 v[206:209], v161 offset:4096
	ds_read_b128 v[210:213], v161 offset:5120
	ds_read_b128 v[214:217], v161 offset:6144
	ds_read_b128 v[218:221], v161 offset:7168
	global_load_lds_dwordx4 v138, s[22:23]
	s_add_i32 m0, s19, 0xe000
	s_nop 0
	global_load_lds_dwordx4 v140, s[22:23]
	s_waitcnt vmcnt(8) lgkmcnt(0)
	s_barrier
	v_mfma_f32_16x16x32_bf16 v[118:121], v[148:151], v[190:193], v[118:121]
	v_mfma_f32_16x16x32_bf16 v[118:121], v[156:159], v[194:197], v[118:121]
	v_mfma_f32_16x16x32_bf16 v[102:105], v[156:159], v[202:205], v[102:105]
	v_mfma_f32_16x16x32_bf16 v[102:105], v[148:151], v[198:201], v[102:105]
	v_mfma_f32_16x16x32_bf16 v[86:89], v[148:151], v[206:209], v[86:89]
	v_mfma_f32_16x16x32_bf16 v[86:89], v[156:159], v[210:213], v[86:89]
	v_mfma_f32_16x16x32_bf16 v[70:73], v[156:159], v[218:221], v[70:73]
	v_mfma_f32_16x16x32_bf16 v[70:73], v[148:151], v[214:217], v[70:73]
	v_mfma_f32_16x16x32_bf16 v[66:69], v[166:169], v[214:217], v[66:69]
	v_mfma_f32_16x16x32_bf16 v[66:69], v[170:173], v[218:221], v[66:69]
	v_mfma_f32_16x16x32_bf16 v[82:85], v[170:173], v[210:213], v[82:85]
	v_mfma_f32_16x16x32_bf16 v[82:85], v[166:169], v[206:209], v[82:85]
	v_mfma_f32_16x16x32_bf16 v[98:101], v[166:169], v[198:201], v[98:101]
	v_mfma_f32_16x16x32_bf16 v[98:101], v[170:173], v[202:205], v[98:101]
	v_mfma_f32_16x16x32_bf16 v[114:117], v[170:173], v[194:197], v[114:117]
	v_mfma_f32_16x16x32_bf16 v[114:117], v[166:169], v[190:193], v[114:117]
	v_mfma_f32_16x16x32_bf16 v[126:129], v[174:177], v[190:193], v[126:129]
	v_mfma_f32_16x16x32_bf16 v[126:129], v[178:181], v[194:197], v[126:129]
	v_mfma_f32_16x16x32_bf16 v[110:113], v[178:181], v[202:205], v[110:113]
	v_mfma_f32_16x16x32_bf16 v[110:113], v[174:177], v[198:201], v[110:113]
	v_mfma_f32_16x16x32_bf16 v[94:97], v[174:177], v[206:209], v[94:97]
	v_mfma_f32_16x16x32_bf16 v[94:97], v[178:181], v[210:213], v[94:97]
	v_mfma_f32_16x16x32_bf16 v[78:81], v[178:181], v[218:221], v[78:81]
	v_mfma_f32_16x16x32_bf16 v[78:81], v[174:177], v[214:217], v[78:81]
	v_mfma_f32_16x16x32_bf16 v[74:77], v[182:185], v[214:217], v[74:77]
	v_mfma_f32_16x16x32_bf16 v[74:77], v[186:189], v[218:221], v[74:77]
	v_mfma_f32_16x16x32_bf16 v[90:93], v[186:189], v[210:213], v[90:93]
	v_mfma_f32_16x16x32_bf16 v[90:93], v[182:185], v[206:209], v[90:93]
	v_mfma_f32_16x16x32_bf16 v[106:109], v[182:185], v[198:201], v[106:109]
	v_mfma_f32_16x16x32_bf16 v[106:109], v[186:189], v[202:205], v[106:109]
	v_mfma_f32_16x16x32_bf16 v[122:125], v[186:189], v[194:197], v[122:125]
	v_mfma_f32_16x16x32_bf16 v[122:125], v[182:185], v[190:193], v[122:125]
	s_barrier
	s_add_i32 s63, s43, s26
	s_mov_b32 m0, s63
	ds_read_b128 v[190:193], v161 offset:16384
	ds_read_b128 v[194:197], v161 offset:17408
	ds_read_b128 v[198:201], v161 offset:18432
	ds_read_b128 v[202:205], v161 offset:19456
	ds_read_b128 v[206:209], v161 offset:20480
	ds_read_b128 v[210:213], v161 offset:21504
	ds_read_b128 v[214:217], v161 offset:22528
	ds_read_b128 v[218:221], v161 offset:23552
	global_load_lds_dwordx4 v132, s[20:21]
	s_add_i32 m0, s63, 0x2000
	s_add_u32 s64, s20, 0x100000
	s_addc_u32 s65, s21, 0
	s_add_i32 s63, s46, s26
	global_load_lds_dwordx4 v136, s[20:21]
	s_mov_b32 m0, s63
	s_add_u32 s100, s24, 0x80
	s_addc_u32 s101, s25, 0
	global_load_lds_dwordx4 v132, s[64:65]
	s_add_i32 m0, s63, 0x2000
	s_nop 0
	global_load_lds_dwordx4 v136, s[64:65]
	s_mov_b32 m0, s19
	s_nop 0
	global_load_lds_dwordx4 v130, s[24:25]
	s_mov_b32 m0, s29
	s_nop 0
	global_load_lds_dwordx4 v134, s[24:25]
	s_waitcnt vmcnt(8) lgkmcnt(0)
	s_barrier
	v_mfma_f32_16x16x32_bf16 v[54:57], v[148:151], v[190:193], v[54:57]
	v_mfma_f32_16x16x32_bf16 v[54:57], v[156:159], v[194:197], v[54:57]
	v_mfma_f32_16x16x32_bf16 v[38:41], v[156:159], v[202:205], v[38:41]
	v_mfma_f32_16x16x32_bf16 v[38:41], v[148:151], v[198:201], v[38:41]
	v_mfma_f32_16x16x32_bf16 v[22:25], v[148:151], v[206:209], v[22:25]
	v_mfma_f32_16x16x32_bf16 v[22:25], v[156:159], v[210:213], v[22:25]
	v_mfma_f32_16x16x32_bf16 v[6:9], v[156:159], v[218:221], v[6:9]
	v_mfma_f32_16x16x32_bf16 v[6:9], v[148:151], v[214:217], v[6:9]
	v_mfma_f32_16x16x32_bf16 v[2:5], v[166:169], v[214:217], v[2:5]
	v_mfma_f32_16x16x32_bf16 v[2:5], v[170:173], v[218:221], v[2:5]
	v_mfma_f32_16x16x32_bf16 v[18:21], v[170:173], v[210:213], v[18:21]
	v_mfma_f32_16x16x32_bf16 v[18:21], v[166:169], v[206:209], v[18:21]
	v_mfma_f32_16x16x32_bf16 v[34:37], v[166:169], v[198:201], v[34:37]
	v_mfma_f32_16x16x32_bf16 v[34:37], v[170:173], v[202:205], v[34:37]
	v_mfma_f32_16x16x32_bf16 v[50:53], v[170:173], v[194:197], v[50:53]
	v_mfma_f32_16x16x32_bf16 v[50:53], v[166:169], v[190:193], v[50:53]
	v_mfma_f32_16x16x32_bf16 v[62:65], v[174:177], v[190:193], v[62:65]
	v_mfma_f32_16x16x32_bf16 v[62:65], v[178:181], v[194:197], v[62:65]
	v_mfma_f32_16x16x32_bf16 v[46:49], v[178:181], v[202:205], v[46:49]
	v_mfma_f32_16x16x32_bf16 v[46:49], v[174:177], v[198:201], v[46:49]
	v_mfma_f32_16x16x32_bf16 v[30:33], v[174:177], v[206:209], v[30:33]
	v_mfma_f32_16x16x32_bf16 v[30:33], v[178:181], v[210:213], v[30:33]
	v_mfma_f32_16x16x32_bf16 v[10:13], v[178:181], v[218:221], v[10:13]
	v_mfma_f32_16x16x32_bf16 v[10:13], v[174:177], v[214:217], v[10:13]
	v_mfma_f32_16x16x32_bf16 v[14:17], v[182:185], v[214:217], v[14:17]
	v_mfma_f32_16x16x32_bf16 v[14:17], v[186:189], v[218:221], v[14:17]
	v_mfma_f32_16x16x32_bf16 v[26:29], v[186:189], v[210:213], v[26:29]
	v_mfma_f32_16x16x32_bf16 v[26:29], v[182:185], v[206:209], v[26:29]
	v_mfma_f32_16x16x32_bf16 v[42:45], v[182:185], v[198:201], v[42:45]
	v_mfma_f32_16x16x32_bf16 v[42:45], v[186:189], v[202:205], v[42:45]
	v_mfma_f32_16x16x32_bf16 v[58:61], v[186:189], v[194:197], v[58:61]
	v_mfma_f32_16x16x32_bf16 v[58:61], v[182:185], v[190:193], v[58:61]
	s_barrier
; #define PG8_STAGE(bufoff, gbase, voff) do { _Pragma("unroll") for (int _i = 0; _i < 2; ++_i) \
;         __builtin_amdgcn_global_load_lds((const unsigned*)((const char*)(gbase) + (voff)[_i]), (PG8_LAS unsigned*)(lds + (bufoff) + ldsw + _i * 8192), 16, 0, 0); } while (0)
; #define PG8_LDA(dst, b, h) do { _Pragma("unroll") for (int m = 0; m < 4; ++m) _Pragma("unroll") for (int k = 0; k < 2; ++k) dst[m][k] = *(const PG8_LAS bf16x8*)(lds + PG8_SA(b, h) + aoff + m * 2048 + k * 1024); } while (0)
; #define PG8_LDB(dst, b, h) do { _Pragma("unroll") for (int n = 0; n < 2; ++n) _Pragma("unroll") for (int k = 0; k < 2; ++k) dst[n][k] = *(const PG8_LAS bf16x8*)(lds + PG8_SB(b, h) + boff + n * 2048 + k * 1024); } while (0)
; #define PG8_MMA(ai, bj, At, Bt) do { __builtin_amdgcn_s_setprio(1); _Pragma("unroll") for (int m = 0; m < 4; ++m) _Pragma("unroll") for (int n = 0; n < 2; ++n) _Pragma("unroll") for (int k = 0; k < 2; ++k) \
;         acc[ai][bj][m][n] = __builtin_amdgcn_mfma_f32_16x16x32_bf16(Bt[n][k], At[m][k], acc[ai][bj][m][n], 0, 0, 0); __builtin_amdgcn_s_setprio(0); } while (0)
; #define PG8_WAIT_V(n) asm volatile("s_waitcnt vmcnt(" #n ")" ::: "memory")
; #define PG8_WAIT_L(n) asm volatile("s_waitcnt lgkmcnt(" #n ")" ::: "memory")
; #define PG8_BAR __builtin_amdgcn_s_barrier()
; #define PG8_SCHED __builtin_amdgcn_sched_barrier(0)
; template <class Epi, class Sched, bool ALIGN_EPI = false, bool SP2 = false>
; __device__ __forceinline__ void gemm_phase(PG8_LAS unsigned char* lds, const Gemm g, const Sched& S, const Epi& E) {
;     ...
;             PG8_LDB(B0, 1, 0); PG8_LDB(B1, 1, 1); PG8_SCHED; PG8_LDA(At, 1, 0); PG8_STAGE(PG8_SA(0, 1), a2 + hstep, voffA);
;             PG8_WAIT_V(8); PG8_WAIT_L(0); PG8_BAR; PG8_MMA(0, 0, At, B0); PG8_MMA(0, 1, At, B1); PG8_BAR; PG8_SCHED;
;             PG8_LDA(At, 1, 1); PG8_STAGE(PG8_SB(1, 0), b3, voffB); PG8_STAGE(PG8_SB(1, 1), b3 + hstep, voffB); PG8_STAGE(PG8_SA(1, 0), a3, voffA);
;             PG8_WAIT_V(8); PG8_WAIT_L(0); PG8_BAR; PG8_MMA(1, 0, At, B0); PG8_MMA(1, 1, At, B1); PG8_BAR; PG8_SCHED;
;     ...
;         if constexpr (ALIGN_EPI) { if (wr == 0) PG8_BAR; }
	s_add_i32 s63, 0, 0x18000
	s_add_i32 s64, 0, 0x1c000
	ds_read_b128 v[148:151], v241 offset:32768
	ds_read_b128 v[156:159], v241 offset:33792
	ds_read_b128 v[166:169], v241 offset:34816
	ds_read_b128 v[170:173], v241 offset:35840
	ds_read_b128 v[174:177], v241 offset:49152
	ds_read_b128 v[178:181], v241 offset:50176
	ds_read_b128 v[182:185], v241 offset:51200
	ds_read_b128 v[186:189], v241 offset:52224
	s_add_u32 s24, s24, 0x100000
	s_addc_u32 s25, s25, 0
	s_mov_b32 m0, s30
	ds_read_b128 v[190:193], v161 offset:32768
	ds_read_b128 v[194:197], v161 offset:33792
	ds_read_b128 v[198:201], v161 offset:34816
	ds_read_b128 v[202:205], v161 offset:35840
	ds_read_b128 v[206:209], v161 offset:36864
	ds_read_b128 v[210:213], v161 offset:37888
	ds_read_b128 v[214:217], v161 offset:38912
	ds_read_b128 v[218:221], v161 offset:39936
	global_load_lds_dwordx4 v130, s[24:25]
	s_mov_b32 m0, s31
	s_nop 0
	global_load_lds_dwordx4 v134, s[24:25]
	s_waitcnt vmcnt(8) lgkmcnt(0)
	s_barrier
	v_mfma_f32_16x16x32_bf16 v[118:121], v[148:151], v[190:193], v[118:121]
	v_mfma_f32_16x16x32_bf16 v[118:121], v[156:159], v[194:197], v[118:121]
	v_mfma_f32_16x16x32_bf16 v[102:105], v[156:159], v[202:205], v[102:105]
	v_mfma_f32_16x16x32_bf16 v[102:105], v[148:151], v[198:201], v[102:105]
	v_mfma_f32_16x16x32_bf16 v[86:89], v[148:151], v[206:209], v[86:89]
	v_mfma_f32_16x16x32_bf16 v[86:89], v[156:159], v[210:213], v[86:89]
	v_mfma_f32_16x16x32_bf16 v[70:73], v[156:159], v[218:221], v[70:73]
	v_mfma_f32_16x16x32_bf16 v[70:73], v[148:151], v[214:217], v[70:73]
	v_mfma_f32_16x16x32_bf16 v[66:69], v[166:169], v[214:217], v[66:69]
	v_mfma_f32_16x16x32_bf16 v[66:69], v[170:173], v[218:221], v[66:69]
	v_mfma_f32_16x16x32_bf16 v[82:85], v[170:173], v[210:213], v[82:85]
	v_mfma_f32_16x16x32_bf16 v[82:85], v[166:169], v[206:209], v[82:85]
	v_mfma_f32_16x16x32_bf16 v[98:101], v[166:169], v[198:201], v[98:101]
	v_mfma_f32_16x16x32_bf16 v[98:101], v[170:173], v[202:205], v[98:101]
	v_mfma_f32_16x16x32_bf16 v[114:117], v[170:173], v[194:197], v[114:117]
	v_mfma_f32_16x16x32_bf16 v[114:117], v[166:169], v[190:193], v[114:117]
	v_mfma_f32_16x16x32_bf16 v[126:129], v[174:177], v[190:193], v[126:129]
	v_mfma_f32_16x16x32_bf16 v[126:129], v[178:181], v[194:197], v[126:129]
	v_mfma_f32_16x16x32_bf16 v[110:113], v[178:181], v[202:205], v[110:113]
	v_mfma_f32_16x16x32_bf16 v[110:113], v[174:177], v[198:201], v[110:113]
	v_mfma_f32_16x16x32_bf16 v[94:97], v[174:177], v[206:209], v[94:97]
	v_mfma_f32_16x16x32_bf16 v[94:97], v[178:181], v[210:213], v[94:97]
	v_mfma_f32_16x16x32_bf16 v[78:81], v[178:181], v[218:221], v[78:81]
	v_mfma_f32_16x16x32_bf16 v[78:81], v[174:177], v[214:217], v[78:81]
	v_mfma_f32_16x16x32_bf16 v[74:77], v[182:185], v[214:217], v[74:77]
	v_mfma_f32_16x16x32_bf16 v[74:77], v[186:189], v[218:221], v[74:77]
	v_mfma_f32_16x16x32_bf16 v[90:93], v[186:189], v[210:213], v[90:93]
	v_mfma_f32_16x16x32_bf16 v[90:93], v[182:185], v[206:209], v[90:93]
	v_mfma_f32_16x16x32_bf16 v[106:109], v[182:185], v[198:201], v[106:109]
	v_mfma_f32_16x16x32_bf16 v[106:109], v[186:189], v[202:205], v[106:109]
	v_mfma_f32_16x16x32_bf16 v[122:125], v[186:189], v[194:197], v[122:125]
	v_mfma_f32_16x16x32_bf16 v[122:125], v[182:185], v[190:193], v[122:125]
	s_barrier
	s_add_i32 s24, s63, s26
	s_add_i32 m0, s24, 0xffffff80
	ds_read_b128 v[190:193], v161 offset:49152
	ds_read_b128 v[194:197], v161 offset:50176
	ds_read_b128 v[198:201], v161 offset:51200
	ds_read_b128 v[202:205], v161 offset:52224
	ds_read_b128 v[206:209], v161 offset:53248
	ds_read_b128 v[210:213], v161 offset:54272
	ds_read_b128 v[214:217], v161 offset:55296
	ds_read_b128 v[218:221], v161 offset:56320
	global_load_lds_dwordx4 v132, s[20:21] offset:128
	s_add_i32 m0, s24, 0x1f80
	s_add_i32 s24, s64, s26
	global_load_lds_dwordx4 v136, s[20:21] offset:128
	s_add_u32 s20, s20, 0x100080
	s_addc_u32 s21, s21, 0
	s_mov_b32 m0, s24
	s_nop 0
	global_load_lds_dwordx4 v132, s[20:21]
	s_add_i32 m0, s24, 0x2000
	s_nop 0
	global_load_lds_dwordx4 v136, s[20:21]
	s_mov_b32 m0, s40
	s_nop 0
	global_load_lds_dwordx4 v130, s[100:101]
	s_mov_b32 m0, s41
	s_nop 0
	global_load_lds_dwordx4 v134, s[100:101]
	s_waitcnt vmcnt(8) lgkmcnt(0)
	s_barrier
	v_mfma_f32_16x16x32_bf16 v[54:57], v[148:151], v[190:193], v[54:57]
	v_mfma_f32_16x16x32_bf16 v[54:57], v[156:159], v[194:197], v[54:57]
	v_mfma_f32_16x16x32_bf16 v[38:41], v[156:159], v[202:205], v[38:41]
	v_mfma_f32_16x16x32_bf16 v[38:41], v[148:151], v[198:201], v[38:41]
	v_mfma_f32_16x16x32_bf16 v[22:25], v[148:151], v[206:209], v[22:25]
	v_mfma_f32_16x16x32_bf16 v[22:25], v[156:159], v[210:213], v[22:25]
	v_mfma_f32_16x16x32_bf16 v[6:9], v[156:159], v[218:221], v[6:9]
	v_mfma_f32_16x16x32_bf16 v[6:9], v[148:151], v[214:217], v[6:9]
	v_mfma_f32_16x16x32_bf16 v[2:5], v[166:169], v[214:217], v[2:5]
	v_mfma_f32_16x16x32_bf16 v[2:5], v[170:173], v[218:221], v[2:5]
	v_mfma_f32_16x16x32_bf16 v[18:21], v[170:173], v[210:213], v[18:21]
	v_mfma_f32_16x16x32_bf16 v[18:21], v[166:169], v[206:209], v[18:21]
	v_mfma_f32_16x16x32_bf16 v[34:37], v[166:169], v[198:201], v[34:37]
	v_mfma_f32_16x16x32_bf16 v[34:37], v[170:173], v[202:205], v[34:37]
	v_mfma_f32_16x16x32_bf16 v[50:53], v[170:173], v[194:197], v[50:53]
	v_mfma_f32_16x16x32_bf16 v[50:53], v[166:169], v[190:193], v[50:53]
	v_mfma_f32_16x16x32_bf16 v[62:65], v[174:177], v[190:193], v[62:65]
	v_mfma_f32_16x16x32_bf16 v[62:65], v[178:181], v[194:197], v[62:65]
	v_mfma_f32_16x16x32_bf16 v[46:49], v[178:181], v[202:205], v[46:49]
	v_mfma_f32_16x16x32_bf16 v[46:49], v[174:177], v[198:201], v[46:49]
	v_mfma_f32_16x16x32_bf16 v[30:33], v[174:177], v[206:209], v[30:33]
	v_mfma_f32_16x16x32_bf16 v[30:33], v[178:181], v[210:213], v[30:33]
	v_mfma_f32_16x16x32_bf16 v[10:13], v[178:181], v[218:221], v[10:13]
	v_mfma_f32_16x16x32_bf16 v[10:13], v[174:177], v[214:217], v[10:13]
	v_mfma_f32_16x16x32_bf16 v[14:17], v[182:185], v[214:217], v[14:17]
	v_mfma_f32_16x16x32_bf16 v[14:17], v[186:189], v[218:221], v[14:17]
	v_mfma_f32_16x16x32_bf16 v[26:29], v[186:189], v[210:213], v[26:29]
	v_mfma_f32_16x16x32_bf16 v[26:29], v[182:185], v[206:209], v[26:29]
	v_mfma_f32_16x16x32_bf16 v[42:45], v[182:185], v[198:201], v[42:45]
	v_mfma_f32_16x16x32_bf16 v[42:45], v[186:189], v[202:205], v[42:45]
	v_mfma_f32_16x16x32_bf16 v[58:61], v[186:189], v[194:197], v[58:61]
	v_mfma_f32_16x16x32_bf16 v[58:61], v[182:185], v[190:193], v[58:61]
	s_barrier
	s_add_i32 s35, s35, 2
	s_add_u32 s22, s22, 0x100
	s_addc_u32 s23, s23, 0
	s_add_u32 s62, s62, 0x100
	s_addc_u32 s34, s34, 0
	s_cmp_gt_u32 s35, 61
	s_cbranch_scc0 .LBB0_673
	s_and_b64 vcc, exec, s[8:9]
	s_cbranch_vccz .LBB0_676
	s_barrier

; #define PG8_STAGE(bufoff, gbase, voff) do { _Pragma("unroll") for (int _i = 0; _i < 2; ++_i) \
;         __builtin_amdgcn_global_load_lds((const unsigned*)((const char*)(gbase) + (voff)[_i]), (PG8_LAS unsigned*)(lds + (bufoff) + ldsw + _i * 8192), 16, 0, 0); } while (0)
; #define PG8_LDA(dst, b, h) do { _Pragma("unroll") for (int m = 0; m < 4; ++m) _Pragma("unroll") for (int k = 0; k < 2; ++k) dst[m][k] = *(const PG8_LAS bf16x8*)(lds + PG8_SA(b, h) + aoff + m * 2048 + k * 1024); } while (0)
; #define PG8_LDB(dst, b, h) do { _Pragma("unroll") for (int n = 0; n < 2; ++n) _Pragma("unroll") for (int k = 0; k < 2; ++k) dst[n][k] = *(const PG8_LAS bf16x8*)(lds + PG8_SB(b, h) + boff + n * 2048 + k * 1024); } while (0)
; #define PG8_MMA(ai, bj, At, Bt) do { __builtin_amdgcn_s_setprio(1); _Pragma("unroll") for (int m = 0; m < 4; ++m) _Pragma("unroll") for (int n = 0; n < 2; ++n) _Pragma("unroll") for (int k = 0; k < 2; ++k) \
;         acc[ai][bj][m][n] = __builtin_amdgcn_mfma_f32_16x16x32_bf16(Bt[n][k], At[m][k], acc[ai][bj][m][n], 0, 0, 0); __builtin_amdgcn_s_setprio(0); } while (0)
; #define PG8_WAIT_V(n) asm volatile("s_waitcnt vmcnt(" #n ")" ::: "memory")
; #define PG8_WAIT_L(n) asm volatile("s_waitcnt lgkmcnt(" #n ")" ::: "memory")
; template <class Epi, class Sched, bool ALIGN_EPI = false, bool SP2 = false>
; __device__ __forceinline__ void gemm_phase(PG8_LAS unsigned char* lds, const Gemm g, const Sched& S, const Epi& E) {
;     ...
;             const bool last = (t == nt - 2);
;             const char* a1 = cA + (size_t)(t + 1) * kstep;
;             const char* a2 = last ? nA : cA + (size_t)(t + 2) * kstep; const char* b2 = last ? nB : cB + (size_t)(t + 2) * kstep;
;             const char* a3 = a2 + kstep; const char* b3 = b2 + kstep;
;             if (last && has_next) S.a_ready(nxt);
;             if constexpr (SP2) {
;             PG8_LDB(B0, 0, 0); PG8_LDB(B1, 0, 1); PG8_SCHED; PG8_LDA(At, 0, 0); PG8_STAGE(PG8_SA(1, 1), a1 + hstep, voffA);
;             PG8_WAIT_V(8); PG8_WAIT_L(0); PG8_BAR; PG8_MMA(0, 0, At, B0); PG8_MMA(0, 1, At, B1); PG8_BAR; PG8_SCHED;
;             PG8_LDA(At, 0, 1); PG8_STAGE(PG8_SB(0, 0), b2, voffB); PG8_STAGE(PG8_SB(0, 1), b2 + hstep, voffB); PG8_STAGE(PG8_SA(0, 0), a2, voffA);
;             PG8_WAIT_V(8); PG8_WAIT_L(0); PG8_BAR; PG8_MMA(1, 0, At, B0); PG8_MMA(1, 1, At, B1); PG8_BAR; PG8_SCHED;
.LBB0_1039:
	ds_read_b128 v[130:133], v241 offset:0
	ds_read_b128 v[134:137], v241 offset:1024
	ds_read_b128 v[138:141], v241 offset:2048
	ds_read_b128 v[142:145], v241 offset:3072
	ds_read_b128 v[146:149], v241 offset:16384
	ds_read_b128 v[150:153], v241 offset:17408
	ds_read_b128 v[172:175], v241 offset:18432
	ds_read_b128 v[176:179], v241 offset:19456
	s_add_u32 s24, s26, 0xfff00080
	s_addc_u32 s25, s27, -1
	s_cmp_eq_u32 s68, 60
	s_cselect_b32 s29, s15, s25
	s_cselect_b32 s28, s21, s24
	s_cselect_b32 s25, s13, s67
	s_cselect_b32 s24, s65, s66
	s_add_i32 m0, s23, 0xc000
	ds_read_b128 v[180:183], v185
	ds_read_b128 v[188:191], v185 offset:1024
	ds_read_b128 v[192:195], v185 offset:2048
	ds_read_b128 v[196:199], v185 offset:3072
	ds_read_b128 v[200:203], v185 offset:4096
	ds_read_b128 v[204:207], v185 offset:5120
	ds_read_b128 v[208:211], v185 offset:6144
	ds_read_b128 v[212:215], v185 offset:7168
	global_load_lds_dwordx4 v162, s[26:27]
	s_add_i32 m0, s23, 0xe000
	s_nop 0
	global_load_lds_dwordx4 v166, s[26:27]
	s_waitcnt vmcnt(8) lgkmcnt(0)
	s_barrier
	v_mfma_f32_16x16x32_bf16 v[114:117], v[130:133], v[180:183], v[114:117]
	v_mfma_f32_16x16x32_bf16 v[114:117], v[134:137], v[188:191], v[114:117]
	v_mfma_f32_16x16x32_bf16 v[106:109], v[134:137], v[196:199], v[106:109]
	v_mfma_f32_16x16x32_bf16 v[106:109], v[130:133], v[192:195], v[106:109]
	v_mfma_f32_16x16x32_bf16 v[90:93], v[130:133], v[200:203], v[90:93]
	v_mfma_f32_16x16x32_bf16 v[90:93], v[134:137], v[204:207], v[90:93]
	v_mfma_f32_16x16x32_bf16 v[74:77], v[134:137], v[212:215], v[74:77]
	v_mfma_f32_16x16x32_bf16 v[74:77], v[130:133], v[208:211], v[74:77]
	v_mfma_f32_16x16x32_bf16 v[66:69], v[138:141], v[208:211], v[66:69]
	v_mfma_f32_16x16x32_bf16 v[66:69], v[142:145], v[212:215], v[66:69]
	v_mfma_f32_16x16x32_bf16 v[82:85], v[142:145], v[204:207], v[82:85]
	v_mfma_f32_16x16x32_bf16 v[82:85], v[138:141], v[200:203], v[82:85]
	v_mfma_f32_16x16x32_bf16 v[98:101], v[138:141], v[192:195], v[98:101]
	v_mfma_f32_16x16x32_bf16 v[98:101], v[142:145], v[196:199], v[98:101]
	v_mfma_f32_16x16x32_bf16 v[118:121], v[142:145], v[188:191], v[118:121]
	v_mfma_f32_16x16x32_bf16 v[118:121], v[138:141], v[180:183], v[118:121]
	v_mfma_f32_16x16x32_bf16 v[122:125], v[146:149], v[180:183], v[122:125]
	v_mfma_f32_16x16x32_bf16 v[122:125], v[150:153], v[188:191], v[122:125]
	v_mfma_f32_16x16x32_bf16 v[110:113], v[150:153], v[196:199], v[110:113]
	v_mfma_f32_16x16x32_bf16 v[110:113], v[146:149], v[192:195], v[110:113]
	v_mfma_f32_16x16x32_bf16 v[94:97], v[146:149], v[200:203], v[94:97]
	v_mfma_f32_16x16x32_bf16 v[94:97], v[150:153], v[204:207], v[94:97]
	v_mfma_f32_16x16x32_bf16 v[78:81], v[150:153], v[212:215], v[78:81]
	v_mfma_f32_16x16x32_bf16 v[78:81], v[146:149], v[208:211], v[78:81]
	v_mfma_f32_16x16x32_bf16 v[70:73], v[172:175], v[208:211], v[70:73]
	v_mfma_f32_16x16x32_bf16 v[70:73], v[176:179], v[212:215], v[70:73]
	v_mfma_f32_16x16x32_bf16 v[86:89], v[176:179], v[204:207], v[86:89]
	v_mfma_f32_16x16x32_bf16 v[86:89], v[172:175], v[200:203], v[86:89]
	v_mfma_f32_16x16x32_bf16 v[102:105], v[172:175], v[192:195], v[102:105]
	v_mfma_f32_16x16x32_bf16 v[102:105], v[176:179], v[196:199], v[102:105]
	v_mfma_f32_16x16x32_bf16 v[126:129], v[176:179], v[188:191], v[126:129]
	v_mfma_f32_16x16x32_bf16 v[126:129], v[172:175], v[180:183], v[126:129]
	s_barrier
	s_add_i32 s33, s62, s36
	s_mov_b32 m0, s33
	ds_read_b128 v[180:183], v185 offset:16384
	ds_read_b128 v[188:191], v185 offset:17408
	ds_read_b128 v[192:195], v185 offset:18432
	ds_read_b128 v[196:199], v185 offset:19456
	ds_read_b128 v[200:203], v185 offset:20480
	ds_read_b128 v[204:207], v185 offset:21504
	ds_read_b128 v[208:211], v185 offset:22528
	ds_read_b128 v[212:215], v185 offset:23552
	global_load_lds_dwordx4 v156, s[24:25]
	s_add_i32 m0, s33, 0x2000
	s_add_u32 s72, s24, 0x100000
	s_addc_u32 s73, s25, 0
	s_add_i32 s33, s63, s36
	global_load_lds_dwordx4 v160, s[24:25]
	s_mov_b32 m0, s33
	s_add_u32 s100, s28, 0x80
	s_addc_u32 s101, s29, 0
	global_load_lds_dwordx4 v156, s[72:73]
	s_add_i32 m0, s33, 0x2000
	s_nop 0
	global_load_lds_dwordx4 v160, s[72:73]
	s_mov_b32 m0, s23
	s_nop 0
	global_load_lds_dwordx4 v154, s[28:29]
	s_mov_b32 m0, s37
	s_nop 0
	global_load_lds_dwordx4 v158, s[28:29]
	s_waitcnt vmcnt(8) lgkmcnt(0)
	s_barrier
	v_mfma_f32_16x16x32_bf16 v[58:61], v[130:133], v[180:183], v[58:61]
	v_mfma_f32_16x16x32_bf16 v[58:61], v[134:137], v[188:191], v[58:61]
	v_mfma_f32_16x16x32_bf16 v[42:45], v[134:137], v[196:199], v[42:45]
	v_mfma_f32_16x16x32_bf16 v[42:45], v[130:133], v[192:195], v[42:45]
	v_mfma_f32_16x16x32_bf16 v[26:29], v[130:133], v[200:203], v[26:29]
	v_mfma_f32_16x16x32_bf16 v[26:29], v[134:137], v[204:207], v[26:29]
	v_mfma_f32_16x16x32_bf16 v[6:9], v[134:137], v[212:215], v[6:9]
	v_mfma_f32_16x16x32_bf16 v[6:9], v[130:133], v[208:211], v[6:9]
	v_mfma_f32_16x16x32_bf16 v[2:5], v[138:141], v[208:211], v[2:5]
	v_mfma_f32_16x16x32_bf16 v[2:5], v[142:145], v[212:215], v[2:5]
	v_mfma_f32_16x16x32_bf16 v[18:21], v[142:145], v[204:207], v[18:21]
	v_mfma_f32_16x16x32_bf16 v[18:21], v[138:141], v[200:203], v[18:21]
	v_mfma_f32_16x16x32_bf16 v[34:37], v[138:141], v[192:195], v[34:37]
	v_mfma_f32_16x16x32_bf16 v[34:37], v[142:145], v[196:199], v[34:37]
	v_mfma_f32_16x16x32_bf16 v[54:57], v[142:145], v[188:191], v[54:57]
	v_mfma_f32_16x16x32_bf16 v[54:57], v[138:141], v[180:183], v[54:57]
	v_mfma_f32_16x16x32_bf16 v[62:65], v[146:149], v[180:183], v[62:65]
	v_mfma_f32_16x16x32_bf16 v[62:65], v[150:153], v[188:191], v[62:65]
	v_mfma_f32_16x16x32_bf16 v[46:49], v[150:153], v[196:199], v[46:49]
	v_mfma_f32_16x16x32_bf16 v[46:49], v[146:149], v[192:195], v[46:49]
	v_mfma_f32_16x16x32_bf16 v[30:33], v[146:149], v[200:203], v[30:33]
	v_mfma_f32_16x16x32_bf16 v[30:33], v[150:153], v[204:207], v[30:33]
	v_mfma_f32_16x16x32_bf16 v[10:13], v[150:153], v[212:215], v[10:13]
	v_mfma_f32_16x16x32_bf16 v[10:13], v[146:149], v[208:211], v[10:13]
	v_mfma_f32_16x16x32_bf16 v[14:17], v[172:175], v[208:211], v[14:17]
	v_mfma_f32_16x16x32_bf16 v[14:17], v[176:179], v[212:215], v[14:17]
	v_mfma_f32_16x16x32_bf16 v[22:25], v[176:179], v[204:207], v[22:25]
	v_mfma_f32_16x16x32_bf16 v[22:25], v[172:175], v[200:203], v[22:25]
	v_mfma_f32_16x16x32_bf16 v[38:41], v[172:175], v[192:195], v[38:41]
	v_mfma_f32_16x16x32_bf16 v[38:41], v[176:179], v[196:199], v[38:41]
	v_mfma_f32_16x16x32_bf16 v[50:53], v[176:179], v[188:191], v[50:53]
	v_mfma_f32_16x16x32_bf16 v[50:53], v[172:175], v[180:183], v[50:53]
	s_barrier
; #define PG8_STAGE(bufoff, gbase, voff) do { _Pragma("unroll") for (int _i = 0; _i < 2; ++_i) \
;         __builtin_amdgcn_global_load_lds((const unsigned*)((const char*)(gbase) + (voff)[_i]), (PG8_LAS unsigned*)(lds + (bufoff) + ldsw + _i * 8192), 16, 0, 0); } while (0)
; #define PG8_LDA(dst, b, h) do { _Pragma("unroll") for (int m = 0; m < 4; ++m) _Pragma("unroll") for (int k = 0; k < 2; ++k) dst[m][k] = *(const PG8_LAS bf16x8*)(lds + PG8_SA(b, h) + aoff + m * 2048 + k * 1024); } while (0)
; #define PG8_LDB(dst, b, h) do { _Pragma("unroll") for (int n = 0; n < 2; ++n) _Pragma("unroll") for (int k = 0; k < 2; ++k) dst[n][k] = *(const PG8_LAS bf16x8*)(lds + PG8_SB(b, h) + boff + n * 2048 + k * 1024); } while (0)
; #define PG8_MMA(ai, bj, At, Bt) do { __builtin_amdgcn_s_setprio(1); _Pragma("unroll") for (int m = 0; m < 4; ++m) _Pragma("unroll") for (int n = 0; n < 2; ++n) _Pragma("unroll") for (int k = 0; k < 2; ++k) \
;         acc[ai][bj][m][n] = __builtin_amdgcn_mfma_f32_16x16x32_bf16(Bt[n][k], At[m][k], acc[ai][bj][m][n], 0, 0, 0); __builtin_amdgcn_s_setprio(0); } while (0)
; #define PG8_WAIT_V(n) asm volatile("s_waitcnt vmcnt(" #n ")" ::: "memory")
; #define PG8_WAIT_L(n) asm volatile("s_waitcnt lgkmcnt(" #n ")" ::: "memory")
; #define PG8_BAR __builtin_amdgcn_s_barrier()
; #define PG8_SCHED __builtin_amdgcn_sched_barrier(0)
; template <class Epi, class Sched, bool ALIGN_EPI = false, bool SP2 = false>
; __device__ __forceinline__ void gemm_phase(PG8_LAS unsigned char* lds, const Gemm g, const Sched& S, const Epi& E) {
;     ...
;             PG8_LDB(B0, 1, 0); PG8_LDB(B1, 1, 1); PG8_SCHED; PG8_LDA(At, 1, 0); PG8_STAGE(PG8_SA(0, 1), a2 + hstep, voffA);
;             PG8_WAIT_V(8); PG8_WAIT_L(0); PG8_BAR; PG8_MMA(0, 0, At, B0); PG8_MMA(0, 1, At, B1); PG8_BAR; PG8_SCHED;
;             PG8_LDA(At, 1, 1); PG8_STAGE(PG8_SB(1, 0), b3, voffB); PG8_STAGE(PG8_SB(1, 1), b3 + hstep, voffB); PG8_STAGE(PG8_SA(1, 0), a3, voffA);
;             PG8_WAIT_V(8); PG8_WAIT_L(0); PG8_BAR; PG8_MMA(1, 0, At, B0); PG8_MMA(1, 1, At, B1); PG8_BAR; PG8_SCHED;
;     ...
;         if constexpr (ALIGN_EPI) { if (wr == 0) PG8_BAR; }
	s_add_i32 s33, 0, 0x18000
	s_add_i32 s42, 0, 0x1c000
	ds_read_b128 v[130:133], v241 offset:32768
	ds_read_b128 v[134:137], v241 offset:33792
	ds_read_b128 v[138:141], v241 offset:34816
	ds_read_b128 v[142:145], v241 offset:35840
	ds_read_b128 v[146:149], v241 offset:49152
	ds_read_b128 v[150:153], v241 offset:50176
	ds_read_b128 v[172:175], v241 offset:51200
	ds_read_b128 v[176:179], v241 offset:52224
	s_add_u32 s28, s28, 0x100000
	s_addc_u32 s29, s29, 0
	s_mov_b32 m0, s40
	ds_read_b128 v[180:183], v185 offset:32768
	ds_read_b128 v[188:191], v185 offset:33792
	ds_read_b128 v[192:195], v185 offset:34816
	ds_read_b128 v[196:199], v185 offset:35840
	ds_read_b128 v[200:203], v185 offset:36864
	ds_read_b128 v[204:207], v185 offset:37888
	ds_read_b128 v[208:211], v185 offset:38912
	ds_read_b128 v[212:215], v185 offset:39936
	global_load_lds_dwordx4 v154, s[28:29]
	s_mov_b32 m0, s41
	s_nop 0
	global_load_lds_dwordx4 v158, s[28:29]
	s_waitcnt vmcnt(8) lgkmcnt(0)
	s_barrier
	v_mfma_f32_16x16x32_bf16 v[114:117], v[130:133], v[180:183], v[114:117]
	v_mfma_f32_16x16x32_bf16 v[114:117], v[134:137], v[188:191], v[114:117]
	v_mfma_f32_16x16x32_bf16 v[106:109], v[134:137], v[196:199], v[106:109]
	v_mfma_f32_16x16x32_bf16 v[106:109], v[130:133], v[192:195], v[106:109]
	v_mfma_f32_16x16x32_bf16 v[90:93], v[130:133], v[200:203], v[90:93]
	v_mfma_f32_16x16x32_bf16 v[90:93], v[134:137], v[204:207], v[90:93]
	v_mfma_f32_16x16x32_bf16 v[74:77], v[134:137], v[212:215], v[74:77]
	v_mfma_f32_16x16x32_bf16 v[74:77], v[130:133], v[208:211], v[74:77]
	v_mfma_f32_16x16x32_bf16 v[66:69], v[138:141], v[208:211], v[66:69]
	v_mfma_f32_16x16x32_bf16 v[66:69], v[142:145], v[212:215], v[66:69]
	v_mfma_f32_16x16x32_bf16 v[82:85], v[142:145], v[204:207], v[82:85]
	v_mfma_f32_16x16x32_bf16 v[82:85], v[138:141], v[200:203], v[82:85]
	v_mfma_f32_16x16x32_bf16 v[98:101], v[138:141], v[192:195], v[98:101]
	v_mfma_f32_16x16x32_bf16 v[98:101], v[142:145], v[196:199], v[98:101]
	v_mfma_f32_16x16x32_bf16 v[118:121], v[142:145], v[188:191], v[118:121]
	v_mfma_f32_16x16x32_bf16 v[118:121], v[138:141], v[180:183], v[118:121]
	v_mfma_f32_16x16x32_bf16 v[122:125], v[146:149], v[180:183], v[122:125]
	v_mfma_f32_16x16x32_bf16 v[122:125], v[150:153], v[188:191], v[122:125]
	v_mfma_f32_16x16x32_bf16 v[110:113], v[150:153], v[196:199], v[110:113]
	v_mfma_f32_16x16x32_bf16 v[110:113], v[146:149], v[192:195], v[110:113]
	v_mfma_f32_16x16x32_bf16 v[94:97], v[146:149], v[200:203], v[94:97]
	v_mfma_f32_16x16x32_bf16 v[94:97], v[150:153], v[204:207], v[94:97]
	v_mfma_f32_16x16x32_bf16 v[78:81], v[150:153], v[212:215], v[78:81]
	v_mfma_f32_16x16x32_bf16 v[78:81], v[146:149], v[208:211], v[78:81]
	v_mfma_f32_16x16x32_bf16 v[70:73], v[172:175], v[208:211], v[70:73]
	v_mfma_f32_16x16x32_bf16 v[70:73], v[176:179], v[212:215], v[70:73]
	v_mfma_f32_16x16x32_bf16 v[86:89], v[176:179], v[204:207], v[86:89]
	v_mfma_f32_16x16x32_bf16 v[86:89], v[172:175], v[200:203], v[86:89]
	v_mfma_f32_16x16x32_bf16 v[102:105], v[172:175], v[192:195], v[102:105]
	v_mfma_f32_16x16x32_bf16 v[102:105], v[176:179], v[196:199], v[102:105]
	v_mfma_f32_16x16x32_bf16 v[126:129], v[176:179], v[188:191], v[126:129]
	v_mfma_f32_16x16x32_bf16 v[126:129], v[172:175], v[180:183], v[126:129]
	s_barrier
	s_add_i32 s28, s33, s36
	s_add_i32 m0, s28, 0xffffff80
	ds_read_b128 v[180:183], v185 offset:49152
	ds_read_b128 v[188:191], v185 offset:50176
	ds_read_b128 v[192:195], v185 offset:51200
	ds_read_b128 v[196:199], v185 offset:52224
	ds_read_b128 v[200:203], v185 offset:53248
	ds_read_b128 v[204:207], v185 offset:54272
	ds_read_b128 v[208:211], v185 offset:55296
	ds_read_b128 v[212:215], v185 offset:56320
	global_load_lds_dwordx4 v156, s[24:25] offset:128
	s_add_i32 m0, s28, 0x1f80
	s_add_i32 s28, s42, s36
	global_load_lds_dwordx4 v160, s[24:25] offset:128
	s_add_u32 s24, s24, 0x100080
	s_addc_u32 s25, s25, 0
	s_mov_b32 m0, s28
	s_nop 0
	global_load_lds_dwordx4 v156, s[24:25]
	s_add_i32 m0, s28, 0x2000
	s_nop 0
	global_load_lds_dwordx4 v160, s[24:25]
	s_mov_b32 m0, s46
	s_nop 0
	global_load_lds_dwordx4 v154, s[100:101]
	s_mov_b32 m0, s47
	s_nop 0
	global_load_lds_dwordx4 v158, s[100:101]
	s_waitcnt vmcnt(8) lgkmcnt(0)
	s_barrier
	v_mfma_f32_16x16x32_bf16 v[58:61], v[130:133], v[180:183], v[58:61]
	v_mfma_f32_16x16x32_bf16 v[58:61], v[134:137], v[188:191], v[58:61]
	v_mfma_f32_16x16x32_bf16 v[42:45], v[134:137], v[196:199], v[42:45]
	v_mfma_f32_16x16x32_bf16 v[42:45], v[130:133], v[192:195], v[42:45]
	v_mfma_f32_16x16x32_bf16 v[26:29], v[130:133], v[200:203], v[26:29]
	v_mfma_f32_16x16x32_bf16 v[26:29], v[134:137], v[204:207], v[26:29]
	v_mfma_f32_16x16x32_bf16 v[6:9], v[134:137], v[212:215], v[6:9]
	v_mfma_f32_16x16x32_bf16 v[6:9], v[130:133], v[208:211], v[6:9]
	v_mfma_f32_16x16x32_bf16 v[2:5], v[138:141], v[208:211], v[2:5]
	v_mfma_f32_16x16x32_bf16 v[2:5], v[142:145], v[212:215], v[2:5]
	v_mfma_f32_16x16x32_bf16 v[18:21], v[142:145], v[204:207], v[18:21]
	v_mfma_f32_16x16x32_bf16 v[18:21], v[138:141], v[200:203], v[18:21]
	v_mfma_f32_16x16x32_bf16 v[34:37], v[138:141], v[192:195], v[34:37]
	v_mfma_f32_16x16x32_bf16 v[34:37], v[142:145], v[196:199], v[34:37]
	v_mfma_f32_16x16x32_bf16 v[54:57], v[142:145], v[188:191], v[54:57]
	v_mfma_f32_16x16x32_bf16 v[54:57], v[138:141], v[180:183], v[54:57]
	v_mfma_f32_16x16x32_bf16 v[62:65], v[146:149], v[180:183], v[62:65]
	v_mfma_f32_16x16x32_bf16 v[62:65], v[150:153], v[188:191], v[62:65]
	v_mfma_f32_16x16x32_bf16 v[46:49], v[150:153], v[196:199], v[46:49]
	v_mfma_f32_16x16x32_bf16 v[46:49], v[146:149], v[192:195], v[46:49]
	v_mfma_f32_16x16x32_bf16 v[30:33], v[146:149], v[200:203], v[30:33]
	v_mfma_f32_16x16x32_bf16 v[30:33], v[150:153], v[204:207], v[30:33]
	v_mfma_f32_16x16x32_bf16 v[10:13], v[150:153], v[212:215], v[10:13]
	v_mfma_f32_16x16x32_bf16 v[10:13], v[146:149], v[208:211], v[10:13]
	v_mfma_f32_16x16x32_bf16 v[14:17], v[172:175], v[208:211], v[14:17]
	v_mfma_f32_16x16x32_bf16 v[14:17], v[176:179], v[212:215], v[14:17]
	v_mfma_f32_16x16x32_bf16 v[22:25], v[176:179], v[204:207], v[22:25]
	v_mfma_f32_16x16x32_bf16 v[22:25], v[172:175], v[200:203], v[22:25]
	v_mfma_f32_16x16x32_bf16 v[38:41], v[172:175], v[192:195], v[38:41]
	v_mfma_f32_16x16x32_bf16 v[38:41], v[176:179], v[196:199], v[38:41]
	v_mfma_f32_16x16x32_bf16 v[50:53], v[176:179], v[188:191], v[50:53]
	v_mfma_f32_16x16x32_bf16 v[50:53], v[172:175], v[180:183], v[50:53]
	s_barrier
	s_add_i32 s68, s68, 2
	s_add_u32 s26, s26, 0x100
	s_addc_u32 s27, s27, 0
	s_add_u32 s66, s66, 0x100
	s_addc_u32 s67, s67, 0
	s_cmp_gt_u32 s68, 61
	s_cbranch_scc0 .LBB0_1039
	s_and_b64 vcc, exec, s[10:11]
	s_cbranch_vccz .LBB0_1042
	s_barrier

; #define PG8_STAGE(bufoff, gbase, voff) do { _Pragma("unroll") for (int _i = 0; _i < 2; ++_i) \
;         __builtin_amdgcn_global_load_lds((const unsigned*)((const char*)(gbase) + (voff)[_i]), (PG8_LAS unsigned*)(lds + (bufoff) + ldsw + _i * 8192), 16, 0, 0); } while (0)
; #define PG8_LDA(dst, b, h) do { _Pragma("unroll") for (int m = 0; m < 4; ++m) _Pragma("unroll") for (int k = 0; k < 2; ++k) dst[m][k] = *(const PG8_LAS bf16x8*)(lds + PG8_SA(b, h) + aoff + m * 2048 + k * 1024); } while (0)
; #define PG8_LDB(dst, b, h) do { _Pragma("unroll") for (int n = 0; n < 2; ++n) _Pragma("unroll") for (int k = 0; k < 2; ++k) dst[n][k] = *(const PG8_LAS bf16x8*)(lds + PG8_SB(b, h) + boff + n * 2048 + k * 1024); } while (0)
; #define PG8_MMA(ai, bj, At, Bt) do { __builtin_amdgcn_s_setprio(1); _Pragma("unroll") for (int m = 0; m < 4; ++m) _Pragma("unroll") for (int n = 0; n < 2; ++n) _Pragma("unroll") for (int k = 0; k < 2; ++k) \
;         acc[ai][bj][m][n] = __builtin_amdgcn_mfma_f32_16x16x32_bf16(Bt[n][k], At[m][k], acc[ai][bj][m][n], 0, 0, 0); __builtin_amdgcn_s_setprio(0); } while (0)
; #define PG8_WAIT_V(n) asm volatile("s_waitcnt vmcnt(" #n ")" ::: "memory")
; #define PG8_WAIT_L(n) asm volatile("s_waitcnt lgkmcnt(" #n ")" ::: "memory")
; template <class Epi, class Sched, bool ALIGN_EPI = false, bool SP2 = false>
; __device__ __forceinline__ void gemm_phase(PG8_LAS unsigned char* lds, const Gemm g, const Sched& S, const Epi& E) {
;     ...
;             const bool last = (t == nt - 2);
;             const char* a1 = cA + (size_t)(t + 1) * kstep;
;             const char* a2 = last ? nA : cA + (size_t)(t + 2) * kstep; const char* b2 = last ? nB : cB + (size_t)(t + 2) * kstep;
;             const char* a3 = a2 + kstep; const char* b3 = b2 + kstep;
;             if (last && has_next) S.a_ready(nxt);
;             if constexpr (SP2) {
;             PG8_LDB(B0, 0, 0); PG8_LDB(B1, 0, 1); PG8_SCHED; PG8_LDA(At, 0, 0); PG8_STAGE(PG8_SA(1, 1), a1 + hstep, voffA);
;             PG8_WAIT_V(8); PG8_WAIT_L(0); PG8_BAR; PG8_MMA(0, 0, At, B0); PG8_MMA(0, 1, At, B1); PG8_BAR; PG8_SCHED;
;             PG8_LDA(At, 0, 1); PG8_STAGE(PG8_SB(0, 0), b2, voffB); PG8_STAGE(PG8_SB(0, 1), b2 + hstep, voffB); PG8_STAGE(PG8_SA(0, 0), a2, voffA);
;             PG8_WAIT_V(8); PG8_WAIT_L(0); PG8_BAR; PG8_MMA(1, 0, At, B0); PG8_MMA(1, 1, At, B1); PG8_BAR; PG8_SCHED;
.LBB0_1126:
	ds_read_b128 v[160:163], v241 offset:0
	ds_read_b128 v[166:169], v241 offset:1024
	ds_read_b128 v[170:173], v241 offset:2048
	ds_read_b128 v[174:177], v241 offset:3072
	ds_read_b128 v[178:181], v241 offset:16384
	ds_read_b128 v[182:185], v241 offset:17408
	ds_read_b128 v[186:189], v241 offset:18432
	ds_read_b128 v[190:193], v241 offset:19456
	s_add_u32 s22, s24, 0xfff00080
	s_addc_u32 s23, s25, -1
	s_cmp_eq_u32 s68, 60
	s_cselect_b32 s27, s15, s23
	s_cselect_b32 s26, s64, s22
	s_cselect_b32 s23, s13, s67
	s_cselect_b32 s22, s65, s66
	s_add_i32 m0, s21, 0xc000
	ds_read_b128 v[194:197], v155
	ds_read_b128 v[198:201], v155 offset:1024
	ds_read_b128 v[202:205], v155 offset:2048
	ds_read_b128 v[206:209], v155 offset:3072
	ds_read_b128 v[210:213], v155 offset:4096
	ds_read_b128 v[214:217], v155 offset:5120
	ds_read_b128 v[218:221], v155 offset:6144
	ds_read_b128 v[222:225], v155 offset:7168
	global_load_lds_dwordx4 v138, s[24:25]
	s_add_i32 m0, s21, 0xe000
	s_nop 0
	global_load_lds_dwordx4 v140, s[24:25]
	s_waitcnt vmcnt(8) lgkmcnt(0)
	s_barrier
	v_mfma_f32_16x16x32_bf16 v[122:125], v[160:163], v[194:197], v[122:125]
	v_mfma_f32_16x16x32_bf16 v[122:125], v[166:169], v[198:201], v[122:125]
	v_mfma_f32_16x16x32_bf16 v[106:109], v[166:169], v[206:209], v[106:109]
	v_mfma_f32_16x16x32_bf16 v[106:109], v[160:163], v[202:205], v[106:109]
	v_mfma_f32_16x16x32_bf16 v[90:93], v[160:163], v[210:213], v[90:93]
	v_mfma_f32_16x16x32_bf16 v[90:93], v[166:169], v[214:217], v[90:93]
	v_mfma_f32_16x16x32_bf16 v[74:77], v[166:169], v[222:225], v[74:77]
	v_mfma_f32_16x16x32_bf16 v[74:77], v[160:163], v[218:221], v[74:77]
	v_mfma_f32_16x16x32_bf16 v[62:65], v[170:173], v[218:221], v[62:65]
	v_mfma_f32_16x16x32_bf16 v[62:65], v[174:177], v[222:225], v[62:65]
	v_mfma_f32_16x16x32_bf16 v[82:85], v[174:177], v[214:217], v[82:85]
	v_mfma_f32_16x16x32_bf16 v[82:85], v[170:173], v[210:213], v[82:85]
	v_mfma_f32_16x16x32_bf16 v[98:101], v[170:173], v[202:205], v[98:101]
	v_mfma_f32_16x16x32_bf16 v[98:101], v[174:177], v[206:209], v[98:101]
	v_mfma_f32_16x16x32_bf16 v[114:117], v[174:177], v[198:201], v[114:117]
	v_mfma_f32_16x16x32_bf16 v[114:117], v[170:173], v[194:197], v[114:117]
	v_mfma_f32_16x16x32_bf16 v[126:129], v[178:181], v[194:197], v[126:129]
	v_mfma_f32_16x16x32_bf16 v[126:129], v[182:185], v[198:201], v[126:129]
	v_mfma_f32_16x16x32_bf16 v[110:113], v[182:185], v[206:209], v[110:113]
	v_mfma_f32_16x16x32_bf16 v[110:113], v[178:181], v[202:205], v[110:113]
	v_mfma_f32_16x16x32_bf16 v[94:97], v[178:181], v[210:213], v[94:97]
	v_mfma_f32_16x16x32_bf16 v[94:97], v[182:185], v[214:217], v[94:97]
	v_mfma_f32_16x16x32_bf16 v[78:81], v[182:185], v[222:225], v[78:81]
	v_mfma_f32_16x16x32_bf16 v[78:81], v[178:181], v[218:221], v[78:81]
	v_mfma_f32_16x16x32_bf16 v[70:73], v[186:189], v[218:221], v[70:73]
	v_mfma_f32_16x16x32_bf16 v[70:73], v[190:193], v[222:225], v[70:73]
	v_mfma_f32_16x16x32_bf16 v[86:89], v[190:193], v[214:217], v[86:89]
	v_mfma_f32_16x16x32_bf16 v[86:89], v[186:189], v[210:213], v[86:89]
	v_mfma_f32_16x16x32_bf16 v[102:105], v[186:189], v[202:205], v[102:105]
	v_mfma_f32_16x16x32_bf16 v[102:105], v[190:193], v[206:209], v[102:105]
	v_mfma_f32_16x16x32_bf16 v[118:121], v[190:193], v[198:201], v[118:121]
	v_mfma_f32_16x16x32_bf16 v[118:121], v[186:189], v[194:197], v[118:121]
	s_barrier
	s_add_i32 s33, s52, s29
	s_mov_b32 m0, s33
	ds_read_b128 v[194:197], v155 offset:16384
	ds_read_b128 v[198:201], v155 offset:17408
	ds_read_b128 v[202:205], v155 offset:18432
	ds_read_b128 v[206:209], v155 offset:19456
	ds_read_b128 v[210:213], v155 offset:20480
	ds_read_b128 v[214:217], v155 offset:21504
	ds_read_b128 v[218:221], v155 offset:22528
	ds_read_b128 v[222:225], v155 offset:23552
	global_load_lds_dwordx4 v132, s[22:23]
	s_add_i32 m0, s33, 0x2000
	s_add_u32 s72, s22, 0x100000
	s_addc_u32 s73, s23, 0
	s_add_i32 s33, s53, s29
	global_load_lds_dwordx4 v136, s[22:23]
	s_mov_b32 m0, s33
	s_add_u32 s100, s26, 0x80
	s_addc_u32 s101, s27, 0
	global_load_lds_dwordx4 v132, s[72:73]
	s_add_i32 m0, s33, 0x2000
	s_nop 0
	global_load_lds_dwordx4 v136, s[72:73]
	s_mov_b32 m0, s21
	s_nop 0
	global_load_lds_dwordx4 v130, s[26:27]
	s_mov_b32 m0, s36
	s_nop 0
	global_load_lds_dwordx4 v134, s[26:27]
	s_waitcnt vmcnt(8) lgkmcnt(0)
	s_barrier
	v_mfma_f32_16x16x32_bf16 v[58:61], v[160:163], v[194:197], v[58:61]
	v_mfma_f32_16x16x32_bf16 v[58:61], v[166:169], v[198:201], v[58:61]
	v_mfma_f32_16x16x32_bf16 v[42:45], v[166:169], v[206:209], v[42:45]
	v_mfma_f32_16x16x32_bf16 v[42:45], v[160:163], v[202:205], v[42:45]
	v_mfma_f32_16x16x32_bf16 v[26:29], v[160:163], v[210:213], v[26:29]
	v_mfma_f32_16x16x32_bf16 v[26:29], v[166:169], v[214:217], v[26:29]
	v_mfma_f32_16x16x32_bf16 v[10:13], v[166:169], v[222:225], v[10:13]
	v_mfma_f32_16x16x32_bf16 v[10:13], v[160:163], v[218:221], v[10:13]
	v_mfma_f32_16x16x32_bf16 v[2:5], v[170:173], v[218:221], v[2:5]
	v_mfma_f32_16x16x32_bf16 v[2:5], v[174:177], v[222:225], v[2:5]
	v_mfma_f32_16x16x32_bf16 v[18:21], v[174:177], v[214:217], v[18:21]
	v_mfma_f32_16x16x32_bf16 v[18:21], v[170:173], v[210:213], v[18:21]
	v_mfma_f32_16x16x32_bf16 v[34:37], v[170:173], v[202:205], v[34:37]
	v_mfma_f32_16x16x32_bf16 v[34:37], v[174:177], v[206:209], v[34:37]
	v_mfma_f32_16x16x32_bf16 v[50:53], v[174:177], v[198:201], v[50:53]
	v_mfma_f32_16x16x32_bf16 v[50:53], v[170:173], v[194:197], v[50:53]
	v_mfma_f32_16x16x32_bf16 v[66:69], v[178:181], v[194:197], v[66:69]
	v_mfma_f32_16x16x32_bf16 v[66:69], v[182:185], v[198:201], v[66:69]
	v_mfma_f32_16x16x32_bf16 v[46:49], v[182:185], v[206:209], v[46:49]
	v_mfma_f32_16x16x32_bf16 v[46:49], v[178:181], v[202:205], v[46:49]
	v_mfma_f32_16x16x32_bf16 v[30:33], v[178:181], v[210:213], v[30:33]
	v_mfma_f32_16x16x32_bf16 v[30:33], v[182:185], v[214:217], v[30:33]
	v_mfma_f32_16x16x32_bf16 v[14:17], v[182:185], v[222:225], v[14:17]
	v_mfma_f32_16x16x32_bf16 v[14:17], v[178:181], v[218:221], v[14:17]
	v_mfma_f32_16x16x32_bf16 v[6:9], v[186:189], v[218:221], v[6:9]
	v_mfma_f32_16x16x32_bf16 v[6:9], v[190:193], v[222:225], v[6:9]
	v_mfma_f32_16x16x32_bf16 v[22:25], v[190:193], v[214:217], v[22:25]
	v_mfma_f32_16x16x32_bf16 v[22:25], v[186:189], v[210:213], v[22:25]
	v_mfma_f32_16x16x32_bf16 v[38:41], v[186:189], v[202:205], v[38:41]
	v_mfma_f32_16x16x32_bf16 v[38:41], v[190:193], v[206:209], v[38:41]
	v_mfma_f32_16x16x32_bf16 v[54:57], v[190:193], v[198:201], v[54:57]
	v_mfma_f32_16x16x32_bf16 v[54:57], v[186:189], v[194:197], v[54:57]
	s_barrier
; #define PG8_STAGE(bufoff, gbase, voff) do { _Pragma("unroll") for (int _i = 0; _i < 2; ++_i) \
;         __builtin_amdgcn_global_load_lds((const unsigned*)((const char*)(gbase) + (voff)[_i]), (PG8_LAS unsigned*)(lds + (bufoff) + ldsw + _i * 8192), 16, 0, 0); } while (0)
; #define PG8_LDA(dst, b, h) do { _Pragma("unroll") for (int m = 0; m < 4; ++m) _Pragma("unroll") for (int k = 0; k < 2; ++k) dst[m][k] = *(const PG8_LAS bf16x8*)(lds + PG8_SA(b, h) + aoff + m * 2048 + k * 1024); } while (0)
; #define PG8_LDB(dst, b, h) do { _Pragma("unroll") for (int n = 0; n < 2; ++n) _Pragma("unroll") for (int k = 0; k < 2; ++k) dst[n][k] = *(const PG8_LAS bf16x8*)(lds + PG8_SB(b, h) + boff + n * 2048 + k * 1024); } while (0)
; #define PG8_MMA(ai, bj, At, Bt) do { __builtin_amdgcn_s_setprio(1); _Pragma("unroll") for (int m = 0; m < 4; ++m) _Pragma("unroll") for (int n = 0; n < 2; ++n) _Pragma("unroll") for (int k = 0; k < 2; ++k) \
;         acc[ai][bj][m][n] = __builtin_amdgcn_mfma_f32_16x16x32_bf16(Bt[n][k], At[m][k], acc[ai][bj][m][n], 0, 0, 0); __builtin_amdgcn_s_setprio(0); } while (0)
; #define PG8_WAIT_V(n) asm volatile("s_waitcnt vmcnt(" #n ")" ::: "memory")
; #define PG8_WAIT_L(n) asm volatile("s_waitcnt lgkmcnt(" #n ")" ::: "memory")
; #define PG8_BAR __builtin_amdgcn_s_barrier()
; #define PG8_SCHED __builtin_amdgcn_sched_barrier(0)
; template <class Epi, class Sched, bool ALIGN_EPI = false, bool SP2 = false>
; __device__ __forceinline__ void gemm_phase(PG8_LAS unsigned char* lds, const Gemm g, const Sched& S, const Epi& E) {
;     ...
;             PG8_LDB(B0, 1, 0); PG8_LDB(B1, 1, 1); PG8_SCHED; PG8_LDA(At, 1, 0); PG8_STAGE(PG8_SA(0, 1), a2 + hstep, voffA);
;             PG8_WAIT_V(8); PG8_WAIT_L(0); PG8_BAR; PG8_MMA(0, 0, At, B0); PG8_MMA(0, 1, At, B1); PG8_BAR; PG8_SCHED;
;             PG8_LDA(At, 1, 1); PG8_STAGE(PG8_SB(1, 0), b3, voffB); PG8_STAGE(PG8_SB(1, 1), b3 + hstep, voffB); PG8_STAGE(PG8_SA(1, 0), a3, voffA);
;             PG8_WAIT_V(8); PG8_WAIT_L(0); PG8_BAR; PG8_MMA(1, 0, At, B0); PG8_MMA(1, 1, At, B1); PG8_BAR; PG8_SCHED;
;     ...
;         if constexpr (ALIGN_EPI) { if (wr == 0) PG8_BAR; }
	s_add_i32 s33, 0, 0x18000
	s_add_i32 s42, 0, 0x1c000
	ds_read_b128 v[160:163], v241 offset:32768
	ds_read_b128 v[166:169], v241 offset:33792
	ds_read_b128 v[170:173], v241 offset:34816
	ds_read_b128 v[174:177], v241 offset:35840
	ds_read_b128 v[178:181], v241 offset:49152
	ds_read_b128 v[182:185], v241 offset:50176
	ds_read_b128 v[186:189], v241 offset:51200
	ds_read_b128 v[190:193], v241 offset:52224
	s_add_u32 s26, s26, 0x100000
	s_addc_u32 s27, s27, 0
	s_mov_b32 m0, s37
	ds_read_b128 v[194:197], v155 offset:32768
	ds_read_b128 v[198:201], v155 offset:33792
	ds_read_b128 v[202:205], v155 offset:34816
	ds_read_b128 v[206:209], v155 offset:35840
	ds_read_b128 v[210:213], v155 offset:36864
	ds_read_b128 v[214:217], v155 offset:37888
	ds_read_b128 v[218:221], v155 offset:38912
	ds_read_b128 v[222:225], v155 offset:39936
	global_load_lds_dwordx4 v130, s[26:27]
	s_mov_b32 m0, s40
	s_nop 0
	global_load_lds_dwordx4 v134, s[26:27]
	s_waitcnt vmcnt(8) lgkmcnt(0)
	s_barrier
	v_mfma_f32_16x16x32_bf16 v[122:125], v[160:163], v[194:197], v[122:125]
	v_mfma_f32_16x16x32_bf16 v[122:125], v[166:169], v[198:201], v[122:125]
	v_mfma_f32_16x16x32_bf16 v[106:109], v[166:169], v[206:209], v[106:109]
	v_mfma_f32_16x16x32_bf16 v[106:109], v[160:163], v[202:205], v[106:109]
	v_mfma_f32_16x16x32_bf16 v[90:93], v[160:163], v[210:213], v[90:93]
	v_mfma_f32_16x16x32_bf16 v[90:93], v[166:169], v[214:217], v[90:93]
	v_mfma_f32_16x16x32_bf16 v[74:77], v[166:169], v[222:225], v[74:77]
	v_mfma_f32_16x16x32_bf16 v[74:77], v[160:163], v[218:221], v[74:77]
	v_mfma_f32_16x16x32_bf16 v[62:65], v[170:173], v[218:221], v[62:65]
	v_mfma_f32_16x16x32_bf16 v[62:65], v[174:177], v[222:225], v[62:65]
	v_mfma_f32_16x16x32_bf16 v[82:85], v[174:177], v[214:217], v[82:85]
	v_mfma_f32_16x16x32_bf16 v[82:85], v[170:173], v[210:213], v[82:85]
	v_mfma_f32_16x16x32_bf16 v[98:101], v[170:173], v[202:205], v[98:101]
	v_mfma_f32_16x16x32_bf16 v[98:101], v[174:177], v[206:209], v[98:101]
	v_mfma_f32_16x16x32_bf16 v[114:117], v[174:177], v[198:201], v[114:117]
	v_mfma_f32_16x16x32_bf16 v[114:117], v[170:173], v[194:197], v[114:117]
	v_mfma_f32_16x16x32_bf16 v[126:129], v[178:181], v[194:197], v[126:129]
	v_mfma_f32_16x16x32_bf16 v[126:129], v[182:185], v[198:201], v[126:129]
	v_mfma_f32_16x16x32_bf16 v[110:113], v[182:185], v[206:209], v[110:113]
	v_mfma_f32_16x16x32_bf16 v[110:113], v[178:181], v[202:205], v[110:113]
	v_mfma_f32_16x16x32_bf16 v[94:97], v[178:181], v[210:213], v[94:97]
	v_mfma_f32_16x16x32_bf16 v[94:97], v[182:185], v[214:217], v[94:97]
	v_mfma_f32_16x16x32_bf16 v[78:81], v[182:185], v[222:225], v[78:81]
	v_mfma_f32_16x16x32_bf16 v[78:81], v[178:181], v[218:221], v[78:81]
	v_mfma_f32_16x16x32_bf16 v[70:73], v[186:189], v[218:221], v[70:73]
	v_mfma_f32_16x16x32_bf16 v[70:73], v[190:193], v[222:225], v[70:73]
	v_mfma_f32_16x16x32_bf16 v[86:89], v[190:193], v[214:217], v[86:89]
	v_mfma_f32_16x16x32_bf16 v[86:89], v[186:189], v[210:213], v[86:89]
	v_mfma_f32_16x16x32_bf16 v[102:105], v[186:189], v[202:205], v[102:105]
	v_mfma_f32_16x16x32_bf16 v[102:105], v[190:193], v[206:209], v[102:105]
	v_mfma_f32_16x16x32_bf16 v[118:121], v[190:193], v[198:201], v[118:121]
	v_mfma_f32_16x16x32_bf16 v[118:121], v[186:189], v[194:197], v[118:121]
	s_barrier
	s_add_i32 s26, s33, s29
	s_add_i32 m0, s26, 0xffffff80
	ds_read_b128 v[194:197], v155 offset:49152
	ds_read_b128 v[198:201], v155 offset:50176
	ds_read_b128 v[202:205], v155 offset:51200
	ds_read_b128 v[206:209], v155 offset:52224
	ds_read_b128 v[210:213], v155 offset:53248
	ds_read_b128 v[214:217], v155 offset:54272
	ds_read_b128 v[218:221], v155 offset:55296
	ds_read_b128 v[222:225], v155 offset:56320
	global_load_lds_dwordx4 v132, s[22:23] offset:128
	s_add_i32 m0, s26, 0x1f80
	s_add_i32 s26, s42, s29
	global_load_lds_dwordx4 v136, s[22:23] offset:128
	s_add_u32 s22, s22, 0x100080
	s_addc_u32 s23, s23, 0
	s_mov_b32 m0, s26
	s_nop 0
	global_load_lds_dwordx4 v132, s[22:23]
	s_add_i32 m0, s26, 0x2000
	s_nop 0
	global_load_lds_dwordx4 v136, s[22:23]
	s_mov_b32 m0, s46
	s_nop 0
	global_load_lds_dwordx4 v130, s[100:101]
	s_mov_b32 m0, s47
	s_nop 0
	global_load_lds_dwordx4 v134, s[100:101]
	s_waitcnt vmcnt(8) lgkmcnt(0)
	s_barrier
	v_mfma_f32_16x16x32_bf16 v[58:61], v[160:163], v[194:197], v[58:61]
	v_mfma_f32_16x16x32_bf16 v[58:61], v[166:169], v[198:201], v[58:61]
	v_mfma_f32_16x16x32_bf16 v[42:45], v[166:169], v[206:209], v[42:45]
	v_mfma_f32_16x16x32_bf16 v[42:45], v[160:163], v[202:205], v[42:45]
	v_mfma_f32_16x16x32_bf16 v[26:29], v[160:163], v[210:213], v[26:29]
	v_mfma_f32_16x16x32_bf16 v[26:29], v[166:169], v[214:217], v[26:29]
	v_mfma_f32_16x16x32_bf16 v[10:13], v[166:169], v[222:225], v[10:13]
	v_mfma_f32_16x16x32_bf16 v[10:13], v[160:163], v[218:221], v[10:13]
	v_mfma_f32_16x16x32_bf16 v[2:5], v[170:173], v[218:221], v[2:5]
	v_mfma_f32_16x16x32_bf16 v[2:5], v[174:177], v[222:225], v[2:5]
	v_mfma_f32_16x16x32_bf16 v[18:21], v[174:177], v[214:217], v[18:21]
	v_mfma_f32_16x16x32_bf16 v[18:21], v[170:173], v[210:213], v[18:21]
	v_mfma_f32_16x16x32_bf16 v[34:37], v[170:173], v[202:205], v[34:37]
	v_mfma_f32_16x16x32_bf16 v[34:37], v[174:177], v[206:209], v[34:37]
	v_mfma_f32_16x16x32_bf16 v[50:53], v[174:177], v[198:201], v[50:53]
	v_mfma_f32_16x16x32_bf16 v[50:53], v[170:173], v[194:197], v[50:53]
	v_mfma_f32_16x16x32_bf16 v[66:69], v[178:181], v[194:197], v[66:69]
	v_mfma_f32_16x16x32_bf16 v[66:69], v[182:185], v[198:201], v[66:69]
	v_mfma_f32_16x16x32_bf16 v[46:49], v[182:185], v[206:209], v[46:49]
	v_mfma_f32_16x16x32_bf16 v[46:49], v[178:181], v[202:205], v[46:49]
	v_mfma_f32_16x16x32_bf16 v[30:33], v[178:181], v[210:213], v[30:33]
	v_mfma_f32_16x16x32_bf16 v[30:33], v[182:185], v[214:217], v[30:33]
	v_mfma_f32_16x16x32_bf16 v[14:17], v[182:185], v[222:225], v[14:17]
	v_mfma_f32_16x16x32_bf16 v[14:17], v[178:181], v[218:221], v[14:17]
	v_mfma_f32_16x16x32_bf16 v[6:9], v[186:189], v[218:221], v[6:9]
	v_mfma_f32_16x16x32_bf16 v[6:9], v[190:193], v[222:225], v[6:9]
	v_mfma_f32_16x16x32_bf16 v[22:25], v[190:193], v[214:217], v[22:25]
	v_mfma_f32_16x16x32_bf16 v[22:25], v[186:189], v[210:213], v[22:25]
	v_mfma_f32_16x16x32_bf16 v[38:41], v[186:189], v[202:205], v[38:41]
	v_mfma_f32_16x16x32_bf16 v[38:41], v[190:193], v[206:209], v[38:41]
	v_mfma_f32_16x16x32_bf16 v[54:57], v[190:193], v[198:201], v[54:57]
	v_mfma_f32_16x16x32_bf16 v[54:57], v[186:189], v[194:197], v[54:57]
	s_barrier
	s_add_i32 s68, s68, 2
	s_add_u32 s24, s24, 0x100
	s_addc_u32 s25, s25, 0
	s_add_u32 s66, s66, 0x100
	s_addc_u32 s67, s67, 0
	s_cmp_gt_u32 s68, 61
	s_cbranch_scc0 .LBB0_1126
	s_and_b64 vcc, exec, s[8:9]
	s_cbranch_vccz .LBB0_1129
	s_barrier

; #define PG8_STAGE(bufoff, gbase, voff) do { _Pragma("unroll") for (int _i = 0; _i < 2; ++_i) \
;         __builtin_amdgcn_global_load_lds((const unsigned*)((const char*)(gbase) + (voff)[_i]), (PG8_LAS unsigned*)(lds + (bufoff) + ldsw + _i * 8192), 16, 0, 0); } while (0)
; #define PG8_LDA(dst, b, h) do { _Pragma("unroll") for (int m = 0; m < 4; ++m) _Pragma("unroll") for (int k = 0; k < 2; ++k) dst[m][k] = *(const PG8_LAS bf16x8*)(lds + PG8_SA(b, h) + aoff + m * 2048 + k * 1024); } while (0)
; #define PG8_LDB(dst, b, h) do { _Pragma("unroll") for (int n = 0; n < 2; ++n) _Pragma("unroll") for (int k = 0; k < 2; ++k) dst[n][k] = *(const PG8_LAS bf16x8*)(lds + PG8_SB(b, h) + boff + n * 2048 + k * 1024); } while (0)
; #define PG8_MMA(ai, bj, At, Bt) do { __builtin_amdgcn_s_setprio(1); _Pragma("unroll") for (int m = 0; m < 4; ++m) _Pragma("unroll") for (int n = 0; n < 2; ++n) _Pragma("unroll") for (int k = 0; k < 2; ++k) \
;         acc[ai][bj][m][n] = __builtin_amdgcn_mfma_f32_16x16x32_bf16(Bt[n][k], At[m][k], acc[ai][bj][m][n], 0, 0, 0); __builtin_amdgcn_s_setprio(0); } while (0)
; #define PG8_WAIT_V(n) asm volatile("s_waitcnt vmcnt(" #n ")" ::: "memory")
; #define PG8_WAIT_L(n) asm volatile("s_waitcnt lgkmcnt(" #n ")" ::: "memory")
; template <class Epi, class Sched, bool ALIGN_EPI = false, bool SP2 = false>
; __device__ __forceinline__ void gemm_phase(PG8_LAS unsigned char* lds, const Gemm g, const Sched& S, const Epi& E) {
;     ...
;             const bool last = (t == nt - 2);
;             const char* a1 = cA + (size_t)(t + 1) * kstep;
;             const char* a2 = last ? nA : cA + (size_t)(t + 2) * kstep; const char* b2 = last ? nB : cB + (size_t)(t + 2) * kstep;
;             const char* a3 = a2 + kstep; const char* b3 = b2 + kstep;
;             if (last && has_next) S.a_ready(nxt);
;             if constexpr (SP2) {
;             PG8_LDB(B0, 0, 0); PG8_LDB(B1, 0, 1); PG8_SCHED; PG8_LDA(At, 0, 0); PG8_STAGE(PG8_SA(1, 1), a1 + hstep, voffA);
;             PG8_WAIT_V(8); PG8_WAIT_L(0); PG8_BAR; PG8_MMA(0, 0, At, B0); PG8_MMA(0, 1, At, B1); PG8_BAR; PG8_SCHED;
;             PG8_LDA(At, 0, 1); PG8_STAGE(PG8_SB(0, 0), b2, voffB); PG8_STAGE(PG8_SB(0, 1), b2 + hstep, voffB); PG8_STAGE(PG8_SA(0, 0), a2, voffA);
;             PG8_WAIT_V(8); PG8_WAIT_L(0); PG8_BAR; PG8_MMA(1, 0, At, B0); PG8_MMA(1, 1, At, B1); PG8_BAR; PG8_SCHED;
.LBB0_1245:
	ds_read_b128 v[130:133], v241 offset:0
	ds_read_b128 v[134:137], v241 offset:1024
	ds_read_b128 v[138:141], v241 offset:2048
	ds_read_b128 v[142:145], v241 offset:3072
	ds_read_b128 v[146:149], v241 offset:16384
	ds_read_b128 v[150:153], v241 offset:17408
	ds_read_b128 v[172:175], v241 offset:18432
	ds_read_b128 v[176:179], v241 offset:19456
	s_add_u32 s16, s18, 0xffd50080
	s_addc_u32 s17, s19, -1
	s_cmpk_eq_i32 s64, 0xa8
	s_cselect_b32 s21, s5, s17
	s_cselect_b32 s20, s4, s16
	s_cselect_b32 s17, s15, s63
	s_cselect_b32 s16, s14, s62
	s_add_i32 m0, s25, 0xc000
	ds_read_b128 v[180:183], v185
	ds_read_b128 v[188:191], v185 offset:1024
	ds_read_b128 v[192:195], v185 offset:2048
	ds_read_b128 v[196:199], v185 offset:3072
	ds_read_b128 v[200:203], v185 offset:4096
	ds_read_b128 v[204:207], v185 offset:5120
	ds_read_b128 v[208:211], v185 offset:6144
	ds_read_b128 v[212:215], v185 offset:7168
	global_load_lds_dwordx4 v162, s[18:19]
	s_add_i32 m0, s25, 0xe000
	s_nop 0
	global_load_lds_dwordx4 v166, s[18:19]
	s_waitcnt vmcnt(8) lgkmcnt(0)
	s_barrier
	v_mfma_f32_16x16x32_bf16 v[114:117], v[130:133], v[180:183], v[114:117]
	v_mfma_f32_16x16x32_bf16 v[114:117], v[134:137], v[188:191], v[114:117]
	v_mfma_f32_16x16x32_bf16 v[106:109], v[134:137], v[196:199], v[106:109]
	v_mfma_f32_16x16x32_bf16 v[106:109], v[130:133], v[192:195], v[106:109]
	v_mfma_f32_16x16x32_bf16 v[90:93], v[130:133], v[200:203], v[90:93]
	v_mfma_f32_16x16x32_bf16 v[90:93], v[134:137], v[204:207], v[90:93]
	v_mfma_f32_16x16x32_bf16 v[74:77], v[134:137], v[212:215], v[74:77]
	v_mfma_f32_16x16x32_bf16 v[74:77], v[130:133], v[208:211], v[74:77]
	v_mfma_f32_16x16x32_bf16 v[66:69], v[138:141], v[208:211], v[66:69]
	v_mfma_f32_16x16x32_bf16 v[66:69], v[142:145], v[212:215], v[66:69]
	v_mfma_f32_16x16x32_bf16 v[82:85], v[142:145], v[204:207], v[82:85]
	v_mfma_f32_16x16x32_bf16 v[82:85], v[138:141], v[200:203], v[82:85]
	v_mfma_f32_16x16x32_bf16 v[98:101], v[138:141], v[192:195], v[98:101]
	v_mfma_f32_16x16x32_bf16 v[98:101], v[142:145], v[196:199], v[98:101]
	v_mfma_f32_16x16x32_bf16 v[118:121], v[142:145], v[188:191], v[118:121]
	v_mfma_f32_16x16x32_bf16 v[118:121], v[138:141], v[180:183], v[118:121]
	v_mfma_f32_16x16x32_bf16 v[122:125], v[146:149], v[180:183], v[122:125]
	v_mfma_f32_16x16x32_bf16 v[122:125], v[150:153], v[188:191], v[122:125]
	v_mfma_f32_16x16x32_bf16 v[110:113], v[150:153], v[196:199], v[110:113]
	v_mfma_f32_16x16x32_bf16 v[110:113], v[146:149], v[192:195], v[110:113]
	v_mfma_f32_16x16x32_bf16 v[94:97], v[146:149], v[200:203], v[94:97]
	v_mfma_f32_16x16x32_bf16 v[94:97], v[150:153], v[204:207], v[94:97]
	v_mfma_f32_16x16x32_bf16 v[78:81], v[150:153], v[212:215], v[78:81]
	v_mfma_f32_16x16x32_bf16 v[78:81], v[146:149], v[208:211], v[78:81]
	v_mfma_f32_16x16x32_bf16 v[70:73], v[172:175], v[208:211], v[70:73]
	v_mfma_f32_16x16x32_bf16 v[70:73], v[176:179], v[212:215], v[70:73]
	v_mfma_f32_16x16x32_bf16 v[86:89], v[176:179], v[204:207], v[86:89]
	v_mfma_f32_16x16x32_bf16 v[86:89], v[172:175], v[200:203], v[86:89]
	v_mfma_f32_16x16x32_bf16 v[102:105], v[172:175], v[192:195], v[102:105]
	v_mfma_f32_16x16x32_bf16 v[102:105], v[176:179], v[196:199], v[102:105]
	v_mfma_f32_16x16x32_bf16 v[126:129], v[176:179], v[188:191], v[126:129]
	v_mfma_f32_16x16x32_bf16 v[126:129], v[172:175], v[180:183], v[126:129]
	s_barrier
	s_add_i32 s33, s40, s24
	s_mov_b32 m0, s33
	ds_read_b128 v[180:183], v185 offset:16384
	ds_read_b128 v[188:191], v185 offset:17408
	ds_read_b128 v[192:195], v185 offset:18432
	ds_read_b128 v[196:199], v185 offset:19456
	ds_read_b128 v[200:203], v185 offset:20480
	ds_read_b128 v[204:207], v185 offset:21504
	ds_read_b128 v[208:211], v185 offset:22528
	ds_read_b128 v[212:215], v185 offset:23552
	global_load_lds_dwordx4 v156, s[16:17]
	s_add_i32 m0, s33, 0x2000
	s_add_u32 s66, s16, 0x2b0000
	s_addc_u32 s67, s17, 0
	s_add_i32 s33, s41, s24
	global_load_lds_dwordx4 v160, s[16:17]
	s_mov_b32 m0, s33
	s_add_u32 s100, s20, 0x80
	s_addc_u32 s101, s21, 0
	global_load_lds_dwordx4 v156, s[66:67]
	s_add_i32 m0, s33, 0x2000
	s_nop 0
	global_load_lds_dwordx4 v160, s[66:67]
	s_mov_b32 m0, s25
	s_nop 0
	global_load_lds_dwordx4 v154, s[20:21]
	s_mov_b32 m0, s26
	s_nop 0
	global_load_lds_dwordx4 v158, s[20:21]
	s_waitcnt vmcnt(8) lgkmcnt(0)
	s_barrier
	v_mfma_f32_16x16x32_bf16 v[58:61], v[130:133], v[180:183], v[58:61]
	v_mfma_f32_16x16x32_bf16 v[58:61], v[134:137], v[188:191], v[58:61]
	v_mfma_f32_16x16x32_bf16 v[42:45], v[134:137], v[196:199], v[42:45]
	v_mfma_f32_16x16x32_bf16 v[42:45], v[130:133], v[192:195], v[42:45]
	v_mfma_f32_16x16x32_bf16 v[26:29], v[130:133], v[200:203], v[26:29]
	v_mfma_f32_16x16x32_bf16 v[26:29], v[134:137], v[204:207], v[26:29]
	v_mfma_f32_16x16x32_bf16 v[6:9], v[134:137], v[212:215], v[6:9]
	v_mfma_f32_16x16x32_bf16 v[6:9], v[130:133], v[208:211], v[6:9]
	v_mfma_f32_16x16x32_bf16 v[2:5], v[138:141], v[208:211], v[2:5]
	v_mfma_f32_16x16x32_bf16 v[2:5], v[142:145], v[212:215], v[2:5]
	v_mfma_f32_16x16x32_bf16 v[18:21], v[142:145], v[204:207], v[18:21]
	v_mfma_f32_16x16x32_bf16 v[18:21], v[138:141], v[200:203], v[18:21]
	v_mfma_f32_16x16x32_bf16 v[34:37], v[138:141], v[192:195], v[34:37]
	v_mfma_f32_16x16x32_bf16 v[34:37], v[142:145], v[196:199], v[34:37]
	v_mfma_f32_16x16x32_bf16 v[54:57], v[142:145], v[188:191], v[54:57]
	v_mfma_f32_16x16x32_bf16 v[54:57], v[138:141], v[180:183], v[54:57]
	v_mfma_f32_16x16x32_bf16 v[62:65], v[146:149], v[180:183], v[62:65]
	v_mfma_f32_16x16x32_bf16 v[62:65], v[150:153], v[188:191], v[62:65]
	v_mfma_f32_16x16x32_bf16 v[46:49], v[150:153], v[196:199], v[46:49]
	v_mfma_f32_16x16x32_bf16 v[46:49], v[146:149], v[192:195], v[46:49]
	v_mfma_f32_16x16x32_bf16 v[30:33], v[146:149], v[200:203], v[30:33]
	v_mfma_f32_16x16x32_bf16 v[30:33], v[150:153], v[204:207], v[30:33]
	v_mfma_f32_16x16x32_bf16 v[10:13], v[150:153], v[212:215], v[10:13]
	v_mfma_f32_16x16x32_bf16 v[10:13], v[146:149], v[208:211], v[10:13]
	v_mfma_f32_16x16x32_bf16 v[14:17], v[172:175], v[208:211], v[14:17]
	v_mfma_f32_16x16x32_bf16 v[14:17], v[176:179], v[212:215], v[14:17]
	v_mfma_f32_16x16x32_bf16 v[22:25], v[176:179], v[204:207], v[22:25]
	v_mfma_f32_16x16x32_bf16 v[22:25], v[172:175], v[200:203], v[22:25]
	v_mfma_f32_16x16x32_bf16 v[38:41], v[172:175], v[192:195], v[38:41]
	v_mfma_f32_16x16x32_bf16 v[38:41], v[176:179], v[196:199], v[38:41]
	v_mfma_f32_16x16x32_bf16 v[50:53], v[176:179], v[188:191], v[50:53]
	v_mfma_f32_16x16x32_bf16 v[50:53], v[172:175], v[180:183], v[50:53]
	s_barrier
; #define PG8_STAGE(bufoff, gbase, voff) do { _Pragma("unroll") for (int _i = 0; _i < 2; ++_i) \
;         __builtin_amdgcn_global_load_lds((const unsigned*)((const char*)(gbase) + (voff)[_i]), (PG8_LAS unsigned*)(lds + (bufoff) + ldsw + _i * 8192), 16, 0, 0); } while (0)
; #define PG8_LDA(dst, b, h) do { _Pragma("unroll") for (int m = 0; m < 4; ++m) _Pragma("unroll") for (int k = 0; k < 2; ++k) dst[m][k] = *(const PG8_LAS bf16x8*)(lds + PG8_SA(b, h) + aoff + m * 2048 + k * 1024); } while (0)
; #define PG8_LDB(dst, b, h) do { _Pragma("unroll") for (int n = 0; n < 2; ++n) _Pragma("unroll") for (int k = 0; k < 2; ++k) dst[n][k] = *(const PG8_LAS bf16x8*)(lds + PG8_SB(b, h) + boff + n * 2048 + k * 1024); } while (0)
; #define PG8_MMA(ai, bj, At, Bt) do { __builtin_amdgcn_s_setprio(1); _Pragma("unroll") for (int m = 0; m < 4; ++m) _Pragma("unroll") for (int n = 0; n < 2; ++n) _Pragma("unroll") for (int k = 0; k < 2; ++k) \
;         acc[ai][bj][m][n] = __builtin_amdgcn_mfma_f32_16x16x32_bf16(Bt[n][k], At[m][k], acc[ai][bj][m][n], 0, 0, 0); __builtin_amdgcn_s_setprio(0); } while (0)
; #define PG8_WAIT_V(n) asm volatile("s_waitcnt vmcnt(" #n ")" ::: "memory")
; #define PG8_WAIT_L(n) asm volatile("s_waitcnt lgkmcnt(" #n ")" ::: "memory")
; #define PG8_BAR __builtin_amdgcn_s_barrier()
; #define PG8_SCHED __builtin_amdgcn_sched_barrier(0)
; template <class Epi, class Sched, bool ALIGN_EPI = false, bool SP2 = false>
; __device__ __forceinline__ void gemm_phase(PG8_LAS unsigned char* lds, const Gemm g, const Sched& S, const Epi& E) {
;     ...
;             PG8_LDB(B0, 1, 0); PG8_LDB(B1, 1, 1); PG8_SCHED; PG8_LDA(At, 1, 0); PG8_STAGE(PG8_SA(0, 1), a2 + hstep, voffA);
;             PG8_WAIT_V(8); PG8_WAIT_L(0); PG8_BAR; PG8_MMA(0, 0, At, B0); PG8_MMA(0, 1, At, B1); PG8_BAR; PG8_SCHED;
;             PG8_LDA(At, 1, 1); PG8_STAGE(PG8_SB(1, 0), b3, voffB); PG8_STAGE(PG8_SB(1, 1), b3 + hstep, voffB); PG8_STAGE(PG8_SA(1, 0), a3, voffA);
;             PG8_WAIT_V(8); PG8_WAIT_L(0); PG8_BAR; PG8_MMA(1, 0, At, B0); PG8_MMA(1, 1, At, B1); PG8_BAR; PG8_SCHED;
;     ...
;         if constexpr (ALIGN_EPI) { if (wr == 0) PG8_BAR; }
	s_add_i32 s33, 0, 0x18000
	s_add_i32 s42, 0, 0x1c000
	ds_read_b128 v[130:133], v241 offset:32768
	ds_read_b128 v[134:137], v241 offset:33792
	ds_read_b128 v[138:141], v241 offset:34816
	ds_read_b128 v[142:145], v241 offset:35840
	ds_read_b128 v[146:149], v241 offset:49152
	ds_read_b128 v[150:153], v241 offset:50176
	ds_read_b128 v[172:175], v241 offset:51200
	ds_read_b128 v[176:179], v241 offset:52224
	s_add_u32 s20, s20, 0x2b0000
	s_addc_u32 s21, s21, 0
	s_mov_b32 m0, s27
	ds_read_b128 v[180:183], v185 offset:32768
	ds_read_b128 v[188:191], v185 offset:33792
	ds_read_b128 v[192:195], v185 offset:34816
	ds_read_b128 v[196:199], v185 offset:35840
	ds_read_b128 v[200:203], v185 offset:36864
	ds_read_b128 v[204:207], v185 offset:37888
	ds_read_b128 v[208:211], v185 offset:38912
	ds_read_b128 v[212:215], v185 offset:39936
	global_load_lds_dwordx4 v154, s[20:21]
	s_mov_b32 m0, s28
	s_nop 0
	global_load_lds_dwordx4 v158, s[20:21]
	s_waitcnt vmcnt(8) lgkmcnt(0)
	s_barrier
	v_mfma_f32_16x16x32_bf16 v[114:117], v[130:133], v[180:183], v[114:117]
	v_mfma_f32_16x16x32_bf16 v[114:117], v[134:137], v[188:191], v[114:117]
	v_mfma_f32_16x16x32_bf16 v[106:109], v[134:137], v[196:199], v[106:109]
	v_mfma_f32_16x16x32_bf16 v[106:109], v[130:133], v[192:195], v[106:109]
	v_mfma_f32_16x16x32_bf16 v[90:93], v[130:133], v[200:203], v[90:93]
	v_mfma_f32_16x16x32_bf16 v[90:93], v[134:137], v[204:207], v[90:93]
	v_mfma_f32_16x16x32_bf16 v[74:77], v[134:137], v[212:215], v[74:77]
	v_mfma_f32_16x16x32_bf16 v[74:77], v[130:133], v[208:211], v[74:77]
	v_mfma_f32_16x16x32_bf16 v[66:69], v[138:141], v[208:211], v[66:69]
	v_mfma_f32_16x16x32_bf16 v[66:69], v[142:145], v[212:215], v[66:69]
	v_mfma_f32_16x16x32_bf16 v[82:85], v[142:145], v[204:207], v[82:85]
	v_mfma_f32_16x16x32_bf16 v[82:85], v[138:141], v[200:203], v[82:85]
	v_mfma_f32_16x16x32_bf16 v[98:101], v[138:141], v[192:195], v[98:101]
	v_mfma_f32_16x16x32_bf16 v[98:101], v[142:145], v[196:199], v[98:101]
	v_mfma_f32_16x16x32_bf16 v[118:121], v[142:145], v[188:191], v[118:121]
	v_mfma_f32_16x16x32_bf16 v[118:121], v[138:141], v[180:183], v[118:121]
	v_mfma_f32_16x16x32_bf16 v[122:125], v[146:149], v[180:183], v[122:125]
	v_mfma_f32_16x16x32_bf16 v[122:125], v[150:153], v[188:191], v[122:125]
	v_mfma_f32_16x16x32_bf16 v[110:113], v[150:153], v[196:199], v[110:113]
	v_mfma_f32_16x16x32_bf16 v[110:113], v[146:149], v[192:195], v[110:113]
	v_mfma_f32_16x16x32_bf16 v[94:97], v[146:149], v[200:203], v[94:97]
	v_mfma_f32_16x16x32_bf16 v[94:97], v[150:153], v[204:207], v[94:97]
	v_mfma_f32_16x16x32_bf16 v[78:81], v[150:153], v[212:215], v[78:81]
	v_mfma_f32_16x16x32_bf16 v[78:81], v[146:149], v[208:211], v[78:81]
	v_mfma_f32_16x16x32_bf16 v[70:73], v[172:175], v[208:211], v[70:73]
	v_mfma_f32_16x16x32_bf16 v[70:73], v[176:179], v[212:215], v[70:73]
	v_mfma_f32_16x16x32_bf16 v[86:89], v[176:179], v[204:207], v[86:89]
	v_mfma_f32_16x16x32_bf16 v[86:89], v[172:175], v[200:203], v[86:89]
	v_mfma_f32_16x16x32_bf16 v[102:105], v[172:175], v[192:195], v[102:105]
	v_mfma_f32_16x16x32_bf16 v[102:105], v[176:179], v[196:199], v[102:105]
	v_mfma_f32_16x16x32_bf16 v[126:129], v[176:179], v[188:191], v[126:129]
	v_mfma_f32_16x16x32_bf16 v[126:129], v[172:175], v[180:183], v[126:129]
	s_barrier
	s_add_i32 s20, s33, s24
	s_add_i32 m0, s20, 0xffffff80
	ds_read_b128 v[180:183], v185 offset:49152
	ds_read_b128 v[188:191], v185 offset:50176
	ds_read_b128 v[192:195], v185 offset:51200
	ds_read_b128 v[196:199], v185 offset:52224
	ds_read_b128 v[200:203], v185 offset:53248
	ds_read_b128 v[204:207], v185 offset:54272
	ds_read_b128 v[208:211], v185 offset:55296
	ds_read_b128 v[212:215], v185 offset:56320
	global_load_lds_dwordx4 v156, s[16:17] offset:128
	s_add_i32 m0, s20, 0x1f80
	s_add_i32 s20, s42, s24
	global_load_lds_dwordx4 v160, s[16:17] offset:128
	s_add_u32 s16, s16, 0x2b0080
	s_addc_u32 s17, s17, 0
	s_mov_b32 m0, s20
	s_nop 0
	global_load_lds_dwordx4 v156, s[16:17]
	s_add_i32 m0, s20, 0x2000
	s_nop 0
	global_load_lds_dwordx4 v160, s[16:17]
	s_mov_b32 m0, s34
	s_nop 0
	global_load_lds_dwordx4 v154, s[100:101]
	s_mov_b32 m0, s35
	s_nop 0
	global_load_lds_dwordx4 v158, s[100:101]
	s_waitcnt vmcnt(8) lgkmcnt(0)
	s_barrier
	v_mfma_f32_16x16x32_bf16 v[58:61], v[130:133], v[180:183], v[58:61]
	v_mfma_f32_16x16x32_bf16 v[58:61], v[134:137], v[188:191], v[58:61]
	v_mfma_f32_16x16x32_bf16 v[42:45], v[134:137], v[196:199], v[42:45]
	v_mfma_f32_16x16x32_bf16 v[42:45], v[130:133], v[192:195], v[42:45]
	v_mfma_f32_16x16x32_bf16 v[26:29], v[130:133], v[200:203], v[26:29]
	v_mfma_f32_16x16x32_bf16 v[26:29], v[134:137], v[204:207], v[26:29]
	v_mfma_f32_16x16x32_bf16 v[6:9], v[134:137], v[212:215], v[6:9]
	v_mfma_f32_16x16x32_bf16 v[6:9], v[130:133], v[208:211], v[6:9]
	v_mfma_f32_16x16x32_bf16 v[2:5], v[138:141], v[208:211], v[2:5]
	v_mfma_f32_16x16x32_bf16 v[2:5], v[142:145], v[212:215], v[2:5]
	v_mfma_f32_16x16x32_bf16 v[18:21], v[142:145], v[204:207], v[18:21]
	v_mfma_f32_16x16x32_bf16 v[18:21], v[138:141], v[200:203], v[18:21]
	v_mfma_f32_16x16x32_bf16 v[34:37], v[138:141], v[192:195], v[34:37]
	v_mfma_f32_16x16x32_bf16 v[34:37], v[142:145], v[196:199], v[34:37]
	v_mfma_f32_16x16x32_bf16 v[54:57], v[142:145], v[188:191], v[54:57]
	v_mfma_f32_16x16x32_bf16 v[54:57], v[138:141], v[180:183], v[54:57]
	v_mfma_f32_16x16x32_bf16 v[62:65], v[146:149], v[180:183], v[62:65]
	v_mfma_f32_16x16x32_bf16 v[62:65], v[150:153], v[188:191], v[62:65]
	v_mfma_f32_16x16x32_bf16 v[46:49], v[150:153], v[196:199], v[46:49]
	v_mfma_f32_16x16x32_bf16 v[46:49], v[146:149], v[192:195], v[46:49]
	v_mfma_f32_16x16x32_bf16 v[30:33], v[146:149], v[200:203], v[30:33]
	v_mfma_f32_16x16x32_bf16 v[30:33], v[150:153], v[204:207], v[30:33]
	v_mfma_f32_16x16x32_bf16 v[10:13], v[150:153], v[212:215], v[10:13]
	v_mfma_f32_16x16x32_bf16 v[10:13], v[146:149], v[208:211], v[10:13]
	v_mfma_f32_16x16x32_bf16 v[14:17], v[172:175], v[208:211], v[14:17]
	v_mfma_f32_16x16x32_bf16 v[14:17], v[176:179], v[212:215], v[14:17]
	v_mfma_f32_16x16x32_bf16 v[22:25], v[176:179], v[204:207], v[22:25]
	v_mfma_f32_16x16x32_bf16 v[22:25], v[172:175], v[200:203], v[22:25]
	v_mfma_f32_16x16x32_bf16 v[38:41], v[172:175], v[192:195], v[38:41]
	v_mfma_f32_16x16x32_bf16 v[38:41], v[176:179], v[196:199], v[38:41]
	v_mfma_f32_16x16x32_bf16 v[50:53], v[176:179], v[188:191], v[50:53]
	v_mfma_f32_16x16x32_bf16 v[50:53], v[172:175], v[180:183], v[50:53]
	s_barrier
	s_add_i32 s64, s64, 2
	s_add_u32 s18, s18, 0x100
	s_addc_u32 s19, s19, 0
	s_add_u32 s62, s62, 0x100
	s_addc_u32 s63, s63, 0
	s_cmpk_gt_u32 s64, 0xa9
	s_cbranch_scc0 .LBB0_1245
	s_and_b64 vcc, exec, s[12:13]
	s_cbranch_vccz .LBB0_1248
	s_barrier

; #define PG8_STAGE(bufoff, gbase, voff) do { _Pragma("unroll") for (int _i = 0; _i < 2; ++_i) \
;         __builtin_amdgcn_global_load_lds((const unsigned*)((const char*)(gbase) + (voff)[_i]), (PG8_LAS unsigned*)(lds + (bufoff) + ldsw + _i * 8192), 16, 0, 0); } while (0)
; #define PG8_LDA(dst, b, h) do { _Pragma("unroll") for (int m = 0; m < 4; ++m) _Pragma("unroll") for (int k = 0; k < 2; ++k) dst[m][k] = *(const PG8_LAS bf16x8*)(lds + PG8_SA(b, h) + aoff + m * 2048 + k * 1024); } while (0)
; #define PG8_LDB(dst, b, h) do { _Pragma("unroll") for (int n = 0; n < 2; ++n) _Pragma("unroll") for (int k = 0; k < 2; ++k) dst[n][k] = *(const PG8_LAS bf16x8*)(lds + PG8_SB(b, h) + boff + n * 2048 + k * 1024); } while (0)
; #define PG8_MMA(ai, bj, At, Bt) do { __builtin_amdgcn_s_setprio(1); _Pragma("unroll") for (int m = 0; m < 4; ++m) _Pragma("unroll") for (int n = 0; n < 2; ++n) _Pragma("unroll") for (int k = 0; k < 2; ++k) \
;         acc[ai][bj][m][n] = __builtin_amdgcn_mfma_f32_16x16x32_bf16(Bt[n][k], At[m][k], acc[ai][bj][m][n], 0, 0, 0); __builtin_amdgcn_s_setprio(0); } while (0)
; #define PG8_WAIT_V(n) asm volatile("s_waitcnt vmcnt(" #n ")" ::: "memory")
; #define PG8_WAIT_L(n) asm volatile("s_waitcnt lgkmcnt(" #n ")" ::: "memory")
; template <class Epi, class Sched, bool ALIGN_EPI = false, bool SP2 = false>
; __device__ __forceinline__ void gemm_phase(PG8_LAS unsigned char* lds, const Gemm g, const Sched& S, const Epi& E) {
;     ...
;             const bool last = (t == nt - 2);
;             const char* a1 = cA + (size_t)(t + 1) * kstep;
;             const char* a2 = last ? nA : cA + (size_t)(t + 2) * kstep; const char* b2 = last ? nB : cB + (size_t)(t + 2) * kstep;
;             const char* a3 = a2 + kstep; const char* b3 = b2 + kstep;
;             if (last && has_next) S.a_ready(nxt);
;             if constexpr (SP2) {
;             PG8_LDB(B0, 0, 0); PG8_LDB(B1, 0, 1); PG8_SCHED; PG8_LDA(At, 0, 0); PG8_STAGE(PG8_SA(1, 1), a1 + hstep, voffA);
;             PG8_WAIT_V(8); PG8_WAIT_L(0); PG8_BAR; PG8_MMA(0, 0, At, B0); PG8_MMA(0, 1, At, B1); PG8_BAR; PG8_SCHED;
;             PG8_LDA(At, 0, 1); PG8_STAGE(PG8_SB(0, 0), b2, voffB); PG8_STAGE(PG8_SB(0, 1), b2 + hstep, voffB); PG8_STAGE(PG8_SA(0, 0), a2, voffA);
;             PG8_WAIT_V(8); PG8_WAIT_L(0); PG8_BAR; PG8_MMA(1, 0, At, B0); PG8_MMA(1, 1, At, B1); PG8_BAR; PG8_SCHED;
.LBB0_1332:
	ds_read_b128 v[148:151], v241 offset:0
	ds_read_b128 v[156:159], v241 offset:1024
	ds_read_b128 v[166:169], v241 offset:2048
	ds_read_b128 v[170:173], v241 offset:3072
	ds_read_b128 v[174:177], v241 offset:16384
	ds_read_b128 v[178:181], v241 offset:17408
	ds_read_b128 v[182:185], v241 offset:18432
	ds_read_b128 v[186:189], v241 offset:19456
	s_add_u32 s20, s22, 0xfff00080
	s_addc_u32 s21, s23, -1
	s_cmp_eq_u32 s67, 60
	s_cselect_b32 s25, s13, s21
	s_cselect_b32 s24, s63, s20
	s_cselect_b32 s21, s11, s66
	s_cselect_b32 s20, s64, s65
	s_add_i32 m0, s19, 0xc000
	ds_read_b128 v[190:193], v155
	ds_read_b128 v[194:197], v155 offset:1024
	ds_read_b128 v[198:201], v155 offset:2048
	ds_read_b128 v[202:205], v155 offset:3072
	ds_read_b128 v[206:209], v155 offset:4096
	ds_read_b128 v[210:213], v155 offset:5120
	ds_read_b128 v[214:217], v155 offset:6144
	ds_read_b128 v[218:221], v155 offset:7168
	global_load_lds_dwordx4 v138, s[22:23]
	s_add_i32 m0, s19, 0xe000
	s_nop 0
	global_load_lds_dwordx4 v140, s[22:23]
	s_waitcnt vmcnt(8) lgkmcnt(0)
	s_barrier
	v_mfma_f32_16x16x32_bf16 v[118:121], v[148:151], v[190:193], v[118:121]
	v_mfma_f32_16x16x32_bf16 v[118:121], v[156:159], v[194:197], v[118:121]
	v_mfma_f32_16x16x32_bf16 v[102:105], v[156:159], v[202:205], v[102:105]
	v_mfma_f32_16x16x32_bf16 v[102:105], v[148:151], v[198:201], v[102:105]
	v_mfma_f32_16x16x32_bf16 v[86:89], v[148:151], v[206:209], v[86:89]
	v_mfma_f32_16x16x32_bf16 v[86:89], v[156:159], v[210:213], v[86:89]
	v_mfma_f32_16x16x32_bf16 v[70:73], v[156:159], v[218:221], v[70:73]
	v_mfma_f32_16x16x32_bf16 v[70:73], v[148:151], v[214:217], v[70:73]
	v_mfma_f32_16x16x32_bf16 v[66:69], v[166:169], v[214:217], v[66:69]
	v_mfma_f32_16x16x32_bf16 v[66:69], v[170:173], v[218:221], v[66:69]
	v_mfma_f32_16x16x32_bf16 v[82:85], v[170:173], v[210:213], v[82:85]
	v_mfma_f32_16x16x32_bf16 v[82:85], v[166:169], v[206:209], v[82:85]
	v_mfma_f32_16x16x32_bf16 v[98:101], v[166:169], v[198:201], v[98:101]
	v_mfma_f32_16x16x32_bf16 v[98:101], v[170:173], v[202:205], v[98:101]
	v_mfma_f32_16x16x32_bf16 v[114:117], v[170:173], v[194:197], v[114:117]
	v_mfma_f32_16x16x32_bf16 v[114:117], v[166:169], v[190:193], v[114:117]
	v_mfma_f32_16x16x32_bf16 v[126:129], v[174:177], v[190:193], v[126:129]
	v_mfma_f32_16x16x32_bf16 v[126:129], v[178:181], v[194:197], v[126:129]
	v_mfma_f32_16x16x32_bf16 v[110:113], v[178:181], v[202:205], v[110:113]
	v_mfma_f32_16x16x32_bf16 v[110:113], v[174:177], v[198:201], v[110:113]
	v_mfma_f32_16x16x32_bf16 v[94:97], v[174:177], v[206:209], v[94:97]
	v_mfma_f32_16x16x32_bf16 v[94:97], v[178:181], v[210:213], v[94:97]
	v_mfma_f32_16x16x32_bf16 v[78:81], v[178:181], v[218:221], v[78:81]
	v_mfma_f32_16x16x32_bf16 v[78:81], v[174:177], v[214:217], v[78:81]
	v_mfma_f32_16x16x32_bf16 v[74:77], v[182:185], v[214:217], v[74:77]
	v_mfma_f32_16x16x32_bf16 v[74:77], v[186:189], v[218:221], v[74:77]
	v_mfma_f32_16x16x32_bf16 v[90:93], v[186:189], v[210:213], v[90:93]
	v_mfma_f32_16x16x32_bf16 v[90:93], v[182:185], v[206:209], v[90:93]
	v_mfma_f32_16x16x32_bf16 v[106:109], v[182:185], v[198:201], v[106:109]
	v_mfma_f32_16x16x32_bf16 v[106:109], v[186:189], v[202:205], v[106:109]
	v_mfma_f32_16x16x32_bf16 v[122:125], v[186:189], v[194:197], v[122:125]
	v_mfma_f32_16x16x32_bf16 v[122:125], v[182:185], v[190:193], v[122:125]
	s_barrier
	s_add_i32 s33, s47, s28
	s_mov_b32 m0, s33
	ds_read_b128 v[190:193], v155 offset:16384
	ds_read_b128 v[194:197], v155 offset:17408
	ds_read_b128 v[198:201], v155 offset:18432
	ds_read_b128 v[202:205], v155 offset:19456
	ds_read_b128 v[206:209], v155 offset:20480
	ds_read_b128 v[210:213], v155 offset:21504
	ds_read_b128 v[214:217], v155 offset:22528
	ds_read_b128 v[218:221], v155 offset:23552
	global_load_lds_dwordx4 v132, s[20:21]
	s_add_i32 m0, s33, 0x2000
	s_add_u32 s68, s20, 0x100000
	s_addc_u32 s69, s21, 0
	s_add_i32 s33, s52, s28
	global_load_lds_dwordx4 v136, s[20:21]
	s_mov_b32 m0, s33
	s_add_u32 s100, s24, 0x80
	s_addc_u32 s101, s25, 0
	global_load_lds_dwordx4 v132, s[68:69]
	s_add_i32 m0, s33, 0x2000
	s_nop 0
	global_load_lds_dwordx4 v136, s[68:69]
	s_mov_b32 m0, s19
	s_nop 0
	global_load_lds_dwordx4 v130, s[24:25]
	s_mov_b32 m0, s35
	s_nop 0
	global_load_lds_dwordx4 v134, s[24:25]
	s_waitcnt vmcnt(8) lgkmcnt(0)
	s_barrier
	v_mfma_f32_16x16x32_bf16 v[54:57], v[148:151], v[190:193], v[54:57]
	v_mfma_f32_16x16x32_bf16 v[54:57], v[156:159], v[194:197], v[54:57]
	v_mfma_f32_16x16x32_bf16 v[38:41], v[156:159], v[202:205], v[38:41]
	v_mfma_f32_16x16x32_bf16 v[38:41], v[148:151], v[198:201], v[38:41]
	v_mfma_f32_16x16x32_bf16 v[22:25], v[148:151], v[206:209], v[22:25]
	v_mfma_f32_16x16x32_bf16 v[22:25], v[156:159], v[210:213], v[22:25]
	v_mfma_f32_16x16x32_bf16 v[6:9], v[156:159], v[218:221], v[6:9]
	v_mfma_f32_16x16x32_bf16 v[6:9], v[148:151], v[214:217], v[6:9]
	v_mfma_f32_16x16x32_bf16 v[2:5], v[166:169], v[214:217], v[2:5]
	v_mfma_f32_16x16x32_bf16 v[2:5], v[170:173], v[218:221], v[2:5]
	v_mfma_f32_16x16x32_bf16 v[18:21], v[170:173], v[210:213], v[18:21]
	v_mfma_f32_16x16x32_bf16 v[18:21], v[166:169], v[206:209], v[18:21]
	v_mfma_f32_16x16x32_bf16 v[34:37], v[166:169], v[198:201], v[34:37]
	v_mfma_f32_16x16x32_bf16 v[34:37], v[170:173], v[202:205], v[34:37]
	v_mfma_f32_16x16x32_bf16 v[50:53], v[170:173], v[194:197], v[50:53]
	v_mfma_f32_16x16x32_bf16 v[50:53], v[166:169], v[190:193], v[50:53]
	v_mfma_f32_16x16x32_bf16 v[62:65], v[174:177], v[190:193], v[62:65]
	v_mfma_f32_16x16x32_bf16 v[62:65], v[178:181], v[194:197], v[62:65]
	v_mfma_f32_16x16x32_bf16 v[46:49], v[178:181], v[202:205], v[46:49]
	v_mfma_f32_16x16x32_bf16 v[46:49], v[174:177], v[198:201], v[46:49]
	v_mfma_f32_16x16x32_bf16 v[30:33], v[174:177], v[206:209], v[30:33]
	v_mfma_f32_16x16x32_bf16 v[30:33], v[178:181], v[210:213], v[30:33]
	v_mfma_f32_16x16x32_bf16 v[10:13], v[178:181], v[218:221], v[10:13]
	v_mfma_f32_16x16x32_bf16 v[10:13], v[174:177], v[214:217], v[10:13]
	v_mfma_f32_16x16x32_bf16 v[14:17], v[182:185], v[214:217], v[14:17]
	v_mfma_f32_16x16x32_bf16 v[14:17], v[186:189], v[218:221], v[14:17]
	v_mfma_f32_16x16x32_bf16 v[26:29], v[186:189], v[210:213], v[26:29]
	v_mfma_f32_16x16x32_bf16 v[26:29], v[182:185], v[206:209], v[26:29]
	v_mfma_f32_16x16x32_bf16 v[42:45], v[182:185], v[198:201], v[42:45]
	v_mfma_f32_16x16x32_bf16 v[42:45], v[186:189], v[202:205], v[42:45]
	v_mfma_f32_16x16x32_bf16 v[58:61], v[186:189], v[194:197], v[58:61]
	v_mfma_f32_16x16x32_bf16 v[58:61], v[182:185], v[190:193], v[58:61]
	s_barrier
; #define PG8_STAGE(bufoff, gbase, voff) do { _Pragma("unroll") for (int _i = 0; _i < 2; ++_i) \
;         __builtin_amdgcn_global_load_lds((const unsigned*)((const char*)(gbase) + (voff)[_i]), (PG8_LAS unsigned*)(lds + (bufoff) + ldsw + _i * 8192), 16, 0, 0); } while (0)
; #define PG8_LDA(dst, b, h) do { _Pragma("unroll") for (int m = 0; m < 4; ++m) _Pragma("unroll") for (int k = 0; k < 2; ++k) dst[m][k] = *(const PG8_LAS bf16x8*)(lds + PG8_SA(b, h) + aoff + m * 2048 + k * 1024); } while (0)
; #define PG8_LDB(dst, b, h) do { _Pragma("unroll") for (int n = 0; n < 2; ++n) _Pragma("unroll") for (int k = 0; k < 2; ++k) dst[n][k] = *(const PG8_LAS bf16x8*)(lds + PG8_SB(b, h) + boff + n * 2048 + k * 1024); } while (0)
; #define PG8_MMA(ai, bj, At, Bt) do { __builtin_amdgcn_s_setprio(1); _Pragma("unroll") for (int m = 0; m < 4; ++m) _Pragma("unroll") for (int n = 0; n < 2; ++n) _Pragma("unroll") for (int k = 0; k < 2; ++k) \
;         acc[ai][bj][m][n] = __builtin_amdgcn_mfma_f32_16x16x32_bf16(Bt[n][k], At[m][k], acc[ai][bj][m][n], 0, 0, 0); __builtin_amdgcn_s_setprio(0); } while (0)
; #define PG8_WAIT_V(n) asm volatile("s_waitcnt vmcnt(" #n ")" ::: "memory")
; #define PG8_WAIT_L(n) asm volatile("s_waitcnt lgkmcnt(" #n ")" ::: "memory")
; #define PG8_BAR __builtin_amdgcn_s_barrier()
; #define PG8_SCHED __builtin_amdgcn_sched_barrier(0)
; template <class Epi, class Sched, bool ALIGN_EPI = false, bool SP2 = false>
; __device__ __forceinline__ void gemm_phase(PG8_LAS unsigned char* lds, const Gemm g, const Sched& S, const Epi& E) {
;     ...
;             PG8_LDB(B0, 1, 0); PG8_LDB(B1, 1, 1); PG8_SCHED; PG8_LDA(At, 1, 0); PG8_STAGE(PG8_SA(0, 1), a2 + hstep, voffA);
;             PG8_WAIT_V(8); PG8_WAIT_L(0); PG8_BAR; PG8_MMA(0, 0, At, B0); PG8_MMA(0, 1, At, B1); PG8_BAR; PG8_SCHED;
;             PG8_LDA(At, 1, 1); PG8_STAGE(PG8_SB(1, 0), b3, voffB); PG8_STAGE(PG8_SB(1, 1), b3 + hstep, voffB); PG8_STAGE(PG8_SA(1, 0), a3, voffA);
;             PG8_WAIT_V(8); PG8_WAIT_L(0); PG8_BAR; PG8_MMA(1, 0, At, B0); PG8_MMA(1, 1, At, B1); PG8_BAR; PG8_SCHED;
;     ...
;         if constexpr (ALIGN_EPI) { if (wr == 0) PG8_BAR; }
	s_add_i32 s33, 0, 0x18000
	s_add_i32 s42, 0, 0x1c000
	ds_read_b128 v[148:151], v241 offset:32768
	ds_read_b128 v[156:159], v241 offset:33792
	ds_read_b128 v[166:169], v241 offset:34816
	ds_read_b128 v[170:173], v241 offset:35840
	ds_read_b128 v[174:177], v241 offset:49152
	ds_read_b128 v[178:181], v241 offset:50176
	ds_read_b128 v[182:185], v241 offset:51200
	ds_read_b128 v[186:189], v241 offset:52224
	s_add_u32 s24, s24, 0x100000
	s_addc_u32 s25, s25, 0
	s_mov_b32 m0, s36
	ds_read_b128 v[190:193], v155 offset:32768
	ds_read_b128 v[194:197], v155 offset:33792
	ds_read_b128 v[198:201], v155 offset:34816
	ds_read_b128 v[202:205], v155 offset:35840
	ds_read_b128 v[206:209], v155 offset:36864
	ds_read_b128 v[210:213], v155 offset:37888
	ds_read_b128 v[214:217], v155 offset:38912
	ds_read_b128 v[218:221], v155 offset:39936
	global_load_lds_dwordx4 v130, s[24:25]
	s_mov_b32 m0, s37
	s_nop 0
	global_load_lds_dwordx4 v134, s[24:25]
	s_waitcnt vmcnt(8) lgkmcnt(0)
	s_barrier
	v_mfma_f32_16x16x32_bf16 v[118:121], v[148:151], v[190:193], v[118:121]
	v_mfma_f32_16x16x32_bf16 v[118:121], v[156:159], v[194:197], v[118:121]
	v_mfma_f32_16x16x32_bf16 v[102:105], v[156:159], v[202:205], v[102:105]
	v_mfma_f32_16x16x32_bf16 v[102:105], v[148:151], v[198:201], v[102:105]
	v_mfma_f32_16x16x32_bf16 v[86:89], v[148:151], v[206:209], v[86:89]
	v_mfma_f32_16x16x32_bf16 v[86:89], v[156:159], v[210:213], v[86:89]
	v_mfma_f32_16x16x32_bf16 v[70:73], v[156:159], v[218:221], v[70:73]
	v_mfma_f32_16x16x32_bf16 v[70:73], v[148:151], v[214:217], v[70:73]
	v_mfma_f32_16x16x32_bf16 v[66:69], v[166:169], v[214:217], v[66:69]
	v_mfma_f32_16x16x32_bf16 v[66:69], v[170:173], v[218:221], v[66:69]
	v_mfma_f32_16x16x32_bf16 v[82:85], v[170:173], v[210:213], v[82:85]
	v_mfma_f32_16x16x32_bf16 v[82:85], v[166:169], v[206:209], v[82:85]
	v_mfma_f32_16x16x32_bf16 v[98:101], v[166:169], v[198:201], v[98:101]
	v_mfma_f32_16x16x32_bf16 v[98:101], v[170:173], v[202:205], v[98:101]
	v_mfma_f32_16x16x32_bf16 v[114:117], v[170:173], v[194:197], v[114:117]
	v_mfma_f32_16x16x32_bf16 v[114:117], v[166:169], v[190:193], v[114:117]
	v_mfma_f32_16x16x32_bf16 v[126:129], v[174:177], v[190:193], v[126:129]
	v_mfma_f32_16x16x32_bf16 v[126:129], v[178:181], v[194:197], v[126:129]
	v_mfma_f32_16x16x32_bf16 v[110:113], v[178:181], v[202:205], v[110:113]
	v_mfma_f32_16x16x32_bf16 v[110:113], v[174:177], v[198:201], v[110:113]
	v_mfma_f32_16x16x32_bf16 v[94:97], v[174:177], v[206:209], v[94:97]
	v_mfma_f32_16x16x32_bf16 v[94:97], v[178:181], v[210:213], v[94:97]
	v_mfma_f32_16x16x32_bf16 v[78:81], v[178:181], v[218:221], v[78:81]
	v_mfma_f32_16x16x32_bf16 v[78:81], v[174:177], v[214:217], v[78:81]
	v_mfma_f32_16x16x32_bf16 v[74:77], v[182:185], v[214:217], v[74:77]
	v_mfma_f32_16x16x32_bf16 v[74:77], v[186:189], v[218:221], v[74:77]
	v_mfma_f32_16x16x32_bf16 v[90:93], v[186:189], v[210:213], v[90:93]
	v_mfma_f32_16x16x32_bf16 v[90:93], v[182:185], v[206:209], v[90:93]
	v_mfma_f32_16x16x32_bf16 v[106:109], v[182:185], v[198:201], v[106:109]
	v_mfma_f32_16x16x32_bf16 v[106:109], v[186:189], v[202:205], v[106:109]
	v_mfma_f32_16x16x32_bf16 v[122:125], v[186:189], v[194:197], v[122:125]
	v_mfma_f32_16x16x32_bf16 v[122:125], v[182:185], v[190:193], v[122:125]
	s_barrier
	s_add_i32 s24, s33, s28
	s_add_i32 m0, s24, 0xffffff80
	ds_read_b128 v[190:193], v155 offset:49152
	ds_read_b128 v[194:197], v155 offset:50176
	ds_read_b128 v[198:201], v155 offset:51200
	ds_read_b128 v[202:205], v155 offset:52224
	ds_read_b128 v[206:209], v155 offset:53248
	ds_read_b128 v[210:213], v155 offset:54272
	ds_read_b128 v[214:217], v155 offset:55296
	ds_read_b128 v[218:221], v155 offset:56320
	global_load_lds_dwordx4 v132, s[20:21] offset:128
	s_add_i32 m0, s24, 0x1f80
	s_add_i32 s24, s42, s28
	global_load_lds_dwordx4 v136, s[20:21] offset:128
	s_add_u32 s20, s20, 0x100080
	s_addc_u32 s21, s21, 0
	s_mov_b32 m0, s24
	s_nop 0
	global_load_lds_dwordx4 v132, s[20:21]
	s_add_i32 m0, s24, 0x2000
	s_nop 0
	global_load_lds_dwordx4 v136, s[20:21]
	s_mov_b32 m0, s43
	s_nop 0
	global_load_lds_dwordx4 v130, s[100:101]
	s_mov_b32 m0, s46
	s_nop 0
	global_load_lds_dwordx4 v134, s[100:101]
	s_waitcnt vmcnt(8) lgkmcnt(0)
	s_barrier
	v_mfma_f32_16x16x32_bf16 v[54:57], v[148:151], v[190:193], v[54:57]
	v_mfma_f32_16x16x32_bf16 v[54:57], v[156:159], v[194:197], v[54:57]
	v_mfma_f32_16x16x32_bf16 v[38:41], v[156:159], v[202:205], v[38:41]
	v_mfma_f32_16x16x32_bf16 v[38:41], v[148:151], v[198:201], v[38:41]
	v_mfma_f32_16x16x32_bf16 v[22:25], v[148:151], v[206:209], v[22:25]
	v_mfma_f32_16x16x32_bf16 v[22:25], v[156:159], v[210:213], v[22:25]
	v_mfma_f32_16x16x32_bf16 v[6:9], v[156:159], v[218:221], v[6:9]
	v_mfma_f32_16x16x32_bf16 v[6:9], v[148:151], v[214:217], v[6:9]
	v_mfma_f32_16x16x32_bf16 v[2:5], v[166:169], v[214:217], v[2:5]
	v_mfma_f32_16x16x32_bf16 v[2:5], v[170:173], v[218:221], v[2:5]
	v_mfma_f32_16x16x32_bf16 v[18:21], v[170:173], v[210:213], v[18:21]
	v_mfma_f32_16x16x32_bf16 v[18:21], v[166:169], v[206:209], v[18:21]
	v_mfma_f32_16x16x32_bf16 v[34:37], v[166:169], v[198:201], v[34:37]
	v_mfma_f32_16x16x32_bf16 v[34:37], v[170:173], v[202:205], v[34:37]
	v_mfma_f32_16x16x32_bf16 v[50:53], v[170:173], v[194:197], v[50:53]
	v_mfma_f32_16x16x32_bf16 v[50:53], v[166:169], v[190:193], v[50:53]
	v_mfma_f32_16x16x32_bf16 v[62:65], v[174:177], v[190:193], v[62:65]
	v_mfma_f32_16x16x32_bf16 v[62:65], v[178:181], v[194:197], v[62:65]
	v_mfma_f32_16x16x32_bf16 v[46:49], v[178:181], v[202:205], v[46:49]
	v_mfma_f32_16x16x32_bf16 v[46:49], v[174:177], v[198:201], v[46:49]
	v_mfma_f32_16x16x32_bf16 v[30:33], v[174:177], v[206:209], v[30:33]
	v_mfma_f32_16x16x32_bf16 v[30:33], v[178:181], v[210:213], v[30:33]
	v_mfma_f32_16x16x32_bf16 v[10:13], v[178:181], v[218:221], v[10:13]
	v_mfma_f32_16x16x32_bf16 v[10:13], v[174:177], v[214:217], v[10:13]
	v_mfma_f32_16x16x32_bf16 v[14:17], v[182:185], v[214:217], v[14:17]
	v_mfma_f32_16x16x32_bf16 v[14:17], v[186:189], v[218:221], v[14:17]
	v_mfma_f32_16x16x32_bf16 v[26:29], v[186:189], v[210:213], v[26:29]
	v_mfma_f32_16x16x32_bf16 v[26:29], v[182:185], v[206:209], v[26:29]
	v_mfma_f32_16x16x32_bf16 v[42:45], v[182:185], v[198:201], v[42:45]
	v_mfma_f32_16x16x32_bf16 v[42:45], v[186:189], v[202:205], v[42:45]
	v_mfma_f32_16x16x32_bf16 v[58:61], v[186:189], v[194:197], v[58:61]
	v_mfma_f32_16x16x32_bf16 v[58:61], v[182:185], v[190:193], v[58:61]
	s_barrier
	s_add_i32 s67, s67, 2
	s_add_u32 s22, s22, 0x100
	s_addc_u32 s23, s23, 0
	s_add_u32 s65, s65, 0x100
	s_addc_u32 s66, s66, 0
	s_cmp_gt_u32 s67, 61
	s_cbranch_scc0 .LBB0_1332
	s_and_b64 vcc, exec, s[8:9]
	s_cbranch_vccz .LBB0_1335
	s_barrier

; #define PG8_STAGE(bufoff, gbase, voff) do { _Pragma("unroll") for (int _i = 0; _i < 2; ++_i) \
;         __builtin_amdgcn_global_load_lds((const unsigned*)((const char*)(gbase) + (voff)[_i]), (PG8_LAS unsigned*)(lds + (bufoff) + ldsw + _i * 8192), 16, 0, 0); } while (0)
; #define PG8_LDA(dst, b, h) do { _Pragma("unroll") for (int m = 0; m < 4; ++m) _Pragma("unroll") for (int k = 0; k < 2; ++k) dst[m][k] = *(const PG8_LAS bf16x8*)(lds + PG8_SA(b, h) + aoff + m * 2048 + k * 1024); } while (0)
; #define PG8_LDB(dst, b, h) do { _Pragma("unroll") for (int n = 0; n < 2; ++n) _Pragma("unroll") for (int k = 0; k < 2; ++k) dst[n][k] = *(const PG8_LAS bf16x8*)(lds + PG8_SB(b, h) + boff + n * 2048 + k * 1024); } while (0)
; #define PG8_MMA(ai, bj, At, Bt) do { __builtin_amdgcn_s_setprio(1); _Pragma("unroll") for (int m = 0; m < 4; ++m) _Pragma("unroll") for (int n = 0; n < 2; ++n) _Pragma("unroll") for (int k = 0; k < 2; ++k) \
;         acc[ai][bj][m][n] = __builtin_amdgcn_mfma_f32_16x16x32_bf16(Bt[n][k], At[m][k], acc[ai][bj][m][n], 0, 0, 0); __builtin_amdgcn_s_setprio(0); } while (0)
; #define PG8_WAIT_V(n) asm volatile("s_waitcnt vmcnt(" #n ")" ::: "memory")
; #define PG8_WAIT_L(n) asm volatile("s_waitcnt lgkmcnt(" #n ")" ::: "memory")
; template <class Epi, class Sched, bool ALIGN_EPI = false, bool SP2 = false>
; __device__ __forceinline__ void gemm_phase(PG8_LAS unsigned char* lds, const Gemm g, const Sched& S, const Epi& E) {
;     ...
;             const bool last = (t == nt - 2);
;             const char* a1 = cA + (size_t)(t + 1) * kstep;
;             const char* a2 = last ? nA : cA + (size_t)(t + 2) * kstep; const char* b2 = last ? nB : cB + (size_t)(t + 2) * kstep;
;             const char* a3 = a2 + kstep; const char* b3 = b2 + kstep;
;             if (last && has_next) S.a_ready(nxt);
;             if constexpr (SP2) {
;             PG8_LDB(B0, 0, 0); PG8_LDB(B1, 0, 1); PG8_SCHED; PG8_LDA(At, 0, 0); PG8_STAGE(PG8_SA(1, 1), a1 + hstep, voffA);
;             PG8_WAIT_V(8); PG8_WAIT_L(0); PG8_BAR; PG8_MMA(0, 0, At, B0); PG8_MMA(0, 1, At, B1); PG8_BAR; PG8_SCHED;
;             PG8_LDA(At, 0, 1); PG8_STAGE(PG8_SB(0, 0), b2, voffB); PG8_STAGE(PG8_SB(0, 1), b2 + hstep, voffB); PG8_STAGE(PG8_SA(0, 0), a2, voffA);
;             PG8_WAIT_V(8); PG8_WAIT_L(0); PG8_BAR; PG8_MMA(1, 0, At, B0); PG8_MMA(1, 1, At, B1); PG8_BAR; PG8_SCHED;
.LBB0_1595:
	ds_read_b128 v[130:133], v241 offset:0
	ds_read_b128 v[134:137], v241 offset:1024
	ds_read_b128 v[138:141], v241 offset:2048
	ds_read_b128 v[142:145], v241 offset:3072
	ds_read_b128 v[146:149], v241 offset:16384
	ds_read_b128 v[150:153], v241 offset:17408
	ds_read_b128 v[172:175], v241 offset:18432
	ds_read_b128 v[176:179], v241 offset:19456
	s_add_u32 s24, s26, 0xfff00080
	s_addc_u32 s25, s27, -1
	s_cmp_eq_u32 s62, 60
	s_cselect_b32 s29, s15, s25
	s_cselect_b32 s28, s21, s24
	s_cselect_b32 s25, s13, s53
	s_cselect_b32 s24, s51, s52
	s_add_i32 m0, s23, 0xc000
	ds_read_b128 v[180:183], v185
	ds_read_b128 v[188:191], v185 offset:1024
	ds_read_b128 v[192:195], v185 offset:2048
	ds_read_b128 v[196:199], v185 offset:3072
	ds_read_b128 v[200:203], v185 offset:4096
	ds_read_b128 v[204:207], v185 offset:5120
	ds_read_b128 v[208:211], v185 offset:6144
	ds_read_b128 v[212:215], v185 offset:7168
	global_load_lds_dwordx4 v162, s[26:27]
	s_add_i32 m0, s23, 0xe000
	s_nop 0
	global_load_lds_dwordx4 v166, s[26:27]
	s_waitcnt vmcnt(8) lgkmcnt(0)
	s_barrier
	v_mfma_f32_16x16x32_bf16 v[114:117], v[130:133], v[180:183], v[114:117]
	v_mfma_f32_16x16x32_bf16 v[114:117], v[134:137], v[188:191], v[114:117]
	v_mfma_f32_16x16x32_bf16 v[106:109], v[134:137], v[196:199], v[106:109]
	v_mfma_f32_16x16x32_bf16 v[106:109], v[130:133], v[192:195], v[106:109]
	v_mfma_f32_16x16x32_bf16 v[90:93], v[130:133], v[200:203], v[90:93]
	v_mfma_f32_16x16x32_bf16 v[90:93], v[134:137], v[204:207], v[90:93]
	v_mfma_f32_16x16x32_bf16 v[74:77], v[134:137], v[212:215], v[74:77]
	v_mfma_f32_16x16x32_bf16 v[74:77], v[130:133], v[208:211], v[74:77]
	v_mfma_f32_16x16x32_bf16 v[66:69], v[138:141], v[208:211], v[66:69]
	v_mfma_f32_16x16x32_bf16 v[66:69], v[142:145], v[212:215], v[66:69]
	v_mfma_f32_16x16x32_bf16 v[82:85], v[142:145], v[204:207], v[82:85]
	v_mfma_f32_16x16x32_bf16 v[82:85], v[138:141], v[200:203], v[82:85]
	v_mfma_f32_16x16x32_bf16 v[98:101], v[138:141], v[192:195], v[98:101]
	v_mfma_f32_16x16x32_bf16 v[98:101], v[142:145], v[196:199], v[98:101]
	v_mfma_f32_16x16x32_bf16 v[118:121], v[142:145], v[188:191], v[118:121]
	v_mfma_f32_16x16x32_bf16 v[118:121], v[138:141], v[180:183], v[118:121]
	v_mfma_f32_16x16x32_bf16 v[122:125], v[146:149], v[180:183], v[122:125]
	v_mfma_f32_16x16x32_bf16 v[122:125], v[150:153], v[188:191], v[122:125]
	v_mfma_f32_16x16x32_bf16 v[110:113], v[150:153], v[196:199], v[110:113]
	v_mfma_f32_16x16x32_bf16 v[110:113], v[146:149], v[192:195], v[110:113]
	v_mfma_f32_16x16x32_bf16 v[94:97], v[146:149], v[200:203], v[94:97]
	v_mfma_f32_16x16x32_bf16 v[94:97], v[150:153], v[204:207], v[94:97]
	v_mfma_f32_16x16x32_bf16 v[78:81], v[150:153], v[212:215], v[78:81]
	v_mfma_f32_16x16x32_bf16 v[78:81], v[146:149], v[208:211], v[78:81]
	v_mfma_f32_16x16x32_bf16 v[70:73], v[172:175], v[208:211], v[70:73]
	v_mfma_f32_16x16x32_bf16 v[70:73], v[176:179], v[212:215], v[70:73]
	v_mfma_f32_16x16x32_bf16 v[86:89], v[176:179], v[204:207], v[86:89]
	v_mfma_f32_16x16x32_bf16 v[86:89], v[172:175], v[200:203], v[86:89]
	v_mfma_f32_16x16x32_bf16 v[102:105], v[172:175], v[192:195], v[102:105]
	v_mfma_f32_16x16x32_bf16 v[102:105], v[176:179], v[196:199], v[102:105]
	v_mfma_f32_16x16x32_bf16 v[126:129], v[176:179], v[188:191], v[126:129]
	v_mfma_f32_16x16x32_bf16 v[126:129], v[172:175], v[180:183], v[126:129]
	s_barrier
	s_add_i32 s33, s48, s36
	s_mov_b32 m0, s33
	ds_read_b128 v[180:183], v185 offset:16384
	ds_read_b128 v[188:191], v185 offset:17408
	ds_read_b128 v[192:195], v185 offset:18432
	ds_read_b128 v[196:199], v185 offset:19456
	ds_read_b128 v[200:203], v185 offset:20480
	ds_read_b128 v[204:207], v185 offset:21504
	ds_read_b128 v[208:211], v185 offset:22528
	ds_read_b128 v[212:215], v185 offset:23552
	global_load_lds_dwordx4 v156, s[24:25]
	s_add_i32 m0, s33, 0x2000
	s_add_u32 s64, s24, 0x100000
	s_addc_u32 s65, s25, 0
	s_add_i32 s33, s49, s36
	global_load_lds_dwordx4 v160, s[24:25]
	s_mov_b32 m0, s33
	s_add_u32 s100, s28, 0x80
	s_addc_u32 s101, s29, 0
	global_load_lds_dwordx4 v156, s[64:65]
	s_add_i32 m0, s33, 0x2000
	s_nop 0
	global_load_lds_dwordx4 v160, s[64:65]
	s_mov_b32 m0, s23
	s_nop 0
	global_load_lds_dwordx4 v154, s[28:29]
	s_mov_b32 m0, s37
	s_nop 0
	global_load_lds_dwordx4 v158, s[28:29]
	s_waitcnt vmcnt(8) lgkmcnt(0)
	s_barrier
	v_mfma_f32_16x16x32_bf16 v[58:61], v[130:133], v[180:183], v[58:61]
	v_mfma_f32_16x16x32_bf16 v[58:61], v[134:137], v[188:191], v[58:61]
	v_mfma_f32_16x16x32_bf16 v[42:45], v[134:137], v[196:199], v[42:45]
	v_mfma_f32_16x16x32_bf16 v[42:45], v[130:133], v[192:195], v[42:45]
	v_mfma_f32_16x16x32_bf16 v[26:29], v[130:133], v[200:203], v[26:29]
	v_mfma_f32_16x16x32_bf16 v[26:29], v[134:137], v[204:207], v[26:29]
	v_mfma_f32_16x16x32_bf16 v[6:9], v[134:137], v[212:215], v[6:9]
	v_mfma_f32_16x16x32_bf16 v[6:9], v[130:133], v[208:211], v[6:9]
	v_mfma_f32_16x16x32_bf16 v[2:5], v[138:141], v[208:211], v[2:5]
	v_mfma_f32_16x16x32_bf16 v[2:5], v[142:145], v[212:215], v[2:5]
	v_mfma_f32_16x16x32_bf16 v[18:21], v[142:145], v[204:207], v[18:21]
	v_mfma_f32_16x16x32_bf16 v[18:21], v[138:141], v[200:203], v[18:21]
	v_mfma_f32_16x16x32_bf16 v[34:37], v[138:141], v[192:195], v[34:37]
	v_mfma_f32_16x16x32_bf16 v[34:37], v[142:145], v[196:199], v[34:37]
	v_mfma_f32_16x16x32_bf16 v[54:57], v[142:145], v[188:191], v[54:57]
	v_mfma_f32_16x16x32_bf16 v[54:57], v[138:141], v[180:183], v[54:57]
	v_mfma_f32_16x16x32_bf16 v[62:65], v[146:149], v[180:183], v[62:65]
	v_mfma_f32_16x16x32_bf16 v[62:65], v[150:153], v[188:191], v[62:65]
	v_mfma_f32_16x16x32_bf16 v[46:49], v[150:153], v[196:199], v[46:49]
	v_mfma_f32_16x16x32_bf16 v[46:49], v[146:149], v[192:195], v[46:49]
	v_mfma_f32_16x16x32_bf16 v[30:33], v[146:149], v[200:203], v[30:33]
	v_mfma_f32_16x16x32_bf16 v[30:33], v[150:153], v[204:207], v[30:33]
	v_mfma_f32_16x16x32_bf16 v[10:13], v[150:153], v[212:215], v[10:13]
	v_mfma_f32_16x16x32_bf16 v[10:13], v[146:149], v[208:211], v[10:13]
	v_mfma_f32_16x16x32_bf16 v[14:17], v[172:175], v[208:211], v[14:17]
	v_mfma_f32_16x16x32_bf16 v[14:17], v[176:179], v[212:215], v[14:17]
	v_mfma_f32_16x16x32_bf16 v[22:25], v[176:179], v[204:207], v[22:25]
	v_mfma_f32_16x16x32_bf16 v[22:25], v[172:175], v[200:203], v[22:25]
	v_mfma_f32_16x16x32_bf16 v[38:41], v[172:175], v[192:195], v[38:41]
	v_mfma_f32_16x16x32_bf16 v[38:41], v[176:179], v[196:199], v[38:41]
	v_mfma_f32_16x16x32_bf16 v[50:53], v[176:179], v[188:191], v[50:53]
	v_mfma_f32_16x16x32_bf16 v[50:53], v[172:175], v[180:183], v[50:53]
	s_barrier
; #define PG8_STAGE(bufoff, gbase, voff) do { _Pragma("unroll") for (int _i = 0; _i < 2; ++_i) \
;         __builtin_amdgcn_global_load_lds((const unsigned*)((const char*)(gbase) + (voff)[_i]), (PG8_LAS unsigned*)(lds + (bufoff) + ldsw + _i * 8192), 16, 0, 0); } while (0)
; #define PG8_LDA(dst, b, h) do { _Pragma("unroll") for (int m = 0; m < 4; ++m) _Pragma("unroll") for (int k = 0; k < 2; ++k) dst[m][k] = *(const PG8_LAS bf16x8*)(lds + PG8_SA(b, h) + aoff + m * 2048 + k * 1024); } while (0)
; #define PG8_LDB(dst, b, h) do { _Pragma("unroll") for (int n = 0; n < 2; ++n) _Pragma("unroll") for (int k = 0; k < 2; ++k) dst[n][k] = *(const PG8_LAS bf16x8*)(lds + PG8_SB(b, h) + boff + n * 2048 + k * 1024); } while (0)
; #define PG8_MMA(ai, bj, At, Bt) do { __builtin_amdgcn_s_setprio(1); _Pragma("unroll") for (int m = 0; m < 4; ++m) _Pragma("unroll") for (int n = 0; n < 2; ++n) _Pragma("unroll") for (int k = 0; k < 2; ++k) \
;         acc[ai][bj][m][n] = __builtin_amdgcn_mfma_f32_16x16x32_bf16(Bt[n][k], At[m][k], acc[ai][bj][m][n], 0, 0, 0); __builtin_amdgcn_s_setprio(0); } while (0)
; #define PG8_WAIT_V(n) asm volatile("s_waitcnt vmcnt(" #n ")" ::: "memory")
; #define PG8_WAIT_L(n) asm volatile("s_waitcnt lgkmcnt(" #n ")" ::: "memory")
; #define PG8_BAR __builtin_amdgcn_s_barrier()
; #define PG8_SCHED __builtin_amdgcn_sched_barrier(0)
; template <class Epi, class Sched, bool ALIGN_EPI = false, bool SP2 = false>
; __device__ __forceinline__ void gemm_phase(PG8_LAS unsigned char* lds, const Gemm g, const Sched& S, const Epi& E) {
;     ...
;             PG8_LDB(B0, 1, 0); PG8_LDB(B1, 1, 1); PG8_SCHED; PG8_LDA(At, 1, 0); PG8_STAGE(PG8_SA(0, 1), a2 + hstep, voffA);
;             PG8_WAIT_V(8); PG8_WAIT_L(0); PG8_BAR; PG8_MMA(0, 0, At, B0); PG8_MMA(0, 1, At, B1); PG8_BAR; PG8_SCHED;
;             PG8_LDA(At, 1, 1); PG8_STAGE(PG8_SB(1, 0), b3, voffB); PG8_STAGE(PG8_SB(1, 1), b3 + hstep, voffB); PG8_STAGE(PG8_SA(1, 0), a3, voffA);
;             PG8_WAIT_V(8); PG8_WAIT_L(0); PG8_BAR; PG8_MMA(1, 0, At, B0); PG8_MMA(1, 1, At, B1); PG8_BAR; PG8_SCHED;
;     ...
;         if constexpr (ALIGN_EPI) { if (wr == 0) PG8_BAR; }
	s_add_i32 s33, 0, 0x18000
	s_add_i32 s42, 0, 0x1c000
	ds_read_b128 v[130:133], v241 offset:32768
	ds_read_b128 v[134:137], v241 offset:33792
	ds_read_b128 v[138:141], v241 offset:34816
	ds_read_b128 v[142:145], v241 offset:35840
	ds_read_b128 v[146:149], v241 offset:49152
	ds_read_b128 v[150:153], v241 offset:50176
	ds_read_b128 v[172:175], v241 offset:51200
	ds_read_b128 v[176:179], v241 offset:52224
	s_add_u32 s28, s28, 0x100000
	s_addc_u32 s29, s29, 0
	s_mov_b32 m0, s40
	ds_read_b128 v[180:183], v185 offset:32768
	ds_read_b128 v[188:191], v185 offset:33792
	ds_read_b128 v[192:195], v185 offset:34816
	ds_read_b128 v[196:199], v185 offset:35840
	ds_read_b128 v[200:203], v185 offset:36864
	ds_read_b128 v[204:207], v185 offset:37888
	ds_read_b128 v[208:211], v185 offset:38912
	ds_read_b128 v[212:215], v185 offset:39936
	global_load_lds_dwordx4 v154, s[28:29]
	s_mov_b32 m0, s41
	s_nop 0
	global_load_lds_dwordx4 v158, s[28:29]
	s_waitcnt vmcnt(8) lgkmcnt(0)
	s_barrier
	v_mfma_f32_16x16x32_bf16 v[114:117], v[130:133], v[180:183], v[114:117]
	v_mfma_f32_16x16x32_bf16 v[114:117], v[134:137], v[188:191], v[114:117]
	v_mfma_f32_16x16x32_bf16 v[106:109], v[134:137], v[196:199], v[106:109]
	v_mfma_f32_16x16x32_bf16 v[106:109], v[130:133], v[192:195], v[106:109]
	v_mfma_f32_16x16x32_bf16 v[90:93], v[130:133], v[200:203], v[90:93]
	v_mfma_f32_16x16x32_bf16 v[90:93], v[134:137], v[204:207], v[90:93]
	v_mfma_f32_16x16x32_bf16 v[74:77], v[134:137], v[212:215], v[74:77]
	v_mfma_f32_16x16x32_bf16 v[74:77], v[130:133], v[208:211], v[74:77]
	v_mfma_f32_16x16x32_bf16 v[66:69], v[138:141], v[208:211], v[66:69]
	v_mfma_f32_16x16x32_bf16 v[66:69], v[142:145], v[212:215], v[66:69]
	v_mfma_f32_16x16x32_bf16 v[82:85], v[142:145], v[204:207], v[82:85]
	v_mfma_f32_16x16x32_bf16 v[82:85], v[138:141], v[200:203], v[82:85]
	v_mfma_f32_16x16x32_bf16 v[98:101], v[138:141], v[192:195], v[98:101]
	v_mfma_f32_16x16x32_bf16 v[98:101], v[142:145], v[196:199], v[98:101]
	v_mfma_f32_16x16x32_bf16 v[118:121], v[142:145], v[188:191], v[118:121]
	v_mfma_f32_16x16x32_bf16 v[118:121], v[138:141], v[180:183], v[118:121]
	v_mfma_f32_16x16x32_bf16 v[122:125], v[146:149], v[180:183], v[122:125]
	v_mfma_f32_16x16x32_bf16 v[122:125], v[150:153], v[188:191], v[122:125]
	v_mfma_f32_16x16x32_bf16 v[110:113], v[150:153], v[196:199], v[110:113]
	v_mfma_f32_16x16x32_bf16 v[110:113], v[146:149], v[192:195], v[110:113]
	v_mfma_f32_16x16x32_bf16 v[94:97], v[146:149], v[200:203], v[94:97]
	v_mfma_f32_16x16x32_bf16 v[94:97], v[150:153], v[204:207], v[94:97]
	v_mfma_f32_16x16x32_bf16 v[78:81], v[150:153], v[212:215], v[78:81]
	v_mfma_f32_16x16x32_bf16 v[78:81], v[146:149], v[208:211], v[78:81]
	v_mfma_f32_16x16x32_bf16 v[70:73], v[172:175], v[208:211], v[70:73]
	v_mfma_f32_16x16x32_bf16 v[70:73], v[176:179], v[212:215], v[70:73]
	v_mfma_f32_16x16x32_bf16 v[86:89], v[176:179], v[204:207], v[86:89]
	v_mfma_f32_16x16x32_bf16 v[86:89], v[172:175], v[200:203], v[86:89]
	v_mfma_f32_16x16x32_bf16 v[102:105], v[172:175], v[192:195], v[102:105]
	v_mfma_f32_16x16x32_bf16 v[102:105], v[176:179], v[196:199], v[102:105]
	v_mfma_f32_16x16x32_bf16 v[126:129], v[176:179], v[188:191], v[126:129]
	v_mfma_f32_16x16x32_bf16 v[126:129], v[172:175], v[180:183], v[126:129]
	s_barrier
	s_add_i32 s28, s33, s36
	s_add_i32 m0, s28, 0xffffff80
	ds_read_b128 v[180:183], v185 offset:49152
	ds_read_b128 v[188:191], v185 offset:50176
	ds_read_b128 v[192:195], v185 offset:51200
	ds_read_b128 v[196:199], v185 offset:52224
	ds_read_b128 v[200:203], v185 offset:53248
	ds_read_b128 v[204:207], v185 offset:54272
	ds_read_b128 v[208:211], v185 offset:55296
	ds_read_b128 v[212:215], v185 offset:56320
	global_load_lds_dwordx4 v156, s[24:25] offset:128
	s_add_i32 m0, s28, 0x1f80
	s_add_i32 s28, s42, s36
	global_load_lds_dwordx4 v160, s[24:25] offset:128
	s_add_u32 s24, s24, 0x100080
	s_addc_u32 s25, s25, 0
	s_mov_b32 m0, s28
	s_nop 0
	global_load_lds_dwordx4 v156, s[24:25]
	s_add_i32 m0, s28, 0x2000
	s_nop 0
	global_load_lds_dwordx4 v160, s[24:25]
	s_mov_b32 m0, s44
	s_nop 0
	global_load_lds_dwordx4 v154, s[100:101]
	s_mov_b32 m0, s45
	s_nop 0
	global_load_lds_dwordx4 v158, s[100:101]
	s_waitcnt vmcnt(8) lgkmcnt(0)
	s_barrier
	v_mfma_f32_16x16x32_bf16 v[58:61], v[130:133], v[180:183], v[58:61]
	v_mfma_f32_16x16x32_bf16 v[58:61], v[134:137], v[188:191], v[58:61]
	v_mfma_f32_16x16x32_bf16 v[42:45], v[134:137], v[196:199], v[42:45]
	v_mfma_f32_16x16x32_bf16 v[42:45], v[130:133], v[192:195], v[42:45]
	v_mfma_f32_16x16x32_bf16 v[26:29], v[130:133], v[200:203], v[26:29]
	v_mfma_f32_16x16x32_bf16 v[26:29], v[134:137], v[204:207], v[26:29]
	v_mfma_f32_16x16x32_bf16 v[6:9], v[134:137], v[212:215], v[6:9]
	v_mfma_f32_16x16x32_bf16 v[6:9], v[130:133], v[208:211], v[6:9]
	v_mfma_f32_16x16x32_bf16 v[2:5], v[138:141], v[208:211], v[2:5]
	v_mfma_f32_16x16x32_bf16 v[2:5], v[142:145], v[212:215], v[2:5]
	v_mfma_f32_16x16x32_bf16 v[18:21], v[142:145], v[204:207], v[18:21]
	v_mfma_f32_16x16x32_bf16 v[18:21], v[138:141], v[200:203], v[18:21]
	v_mfma_f32_16x16x32_bf16 v[34:37], v[138:141], v[192:195], v[34:37]
	v_mfma_f32_16x16x32_bf16 v[34:37], v[142:145], v[196:199], v[34:37]
	v_mfma_f32_16x16x32_bf16 v[54:57], v[142:145], v[188:191], v[54:57]
	v_mfma_f32_16x16x32_bf16 v[54:57], v[138:141], v[180:183], v[54:57]
	v_mfma_f32_16x16x32_bf16 v[62:65], v[146:149], v[180:183], v[62:65]
	v_mfma_f32_16x16x32_bf16 v[62:65], v[150:153], v[188:191], v[62:65]
	v_mfma_f32_16x16x32_bf16 v[46:49], v[150:153], v[196:199], v[46:49]
	v_mfma_f32_16x16x32_bf16 v[46:49], v[146:149], v[192:195], v[46:49]
	v_mfma_f32_16x16x32_bf16 v[30:33], v[146:149], v[200:203], v[30:33]
	v_mfma_f32_16x16x32_bf16 v[30:33], v[150:153], v[204:207], v[30:33]
	v_mfma_f32_16x16x32_bf16 v[10:13], v[150:153], v[212:215], v[10:13]
	v_mfma_f32_16x16x32_bf16 v[10:13], v[146:149], v[208:211], v[10:13]
	v_mfma_f32_16x16x32_bf16 v[14:17], v[172:175], v[208:211], v[14:17]
	v_mfma_f32_16x16x32_bf16 v[14:17], v[176:179], v[212:215], v[14:17]
	v_mfma_f32_16x16x32_bf16 v[22:25], v[176:179], v[204:207], v[22:25]
	v_mfma_f32_16x16x32_bf16 v[22:25], v[172:175], v[200:203], v[22:25]
	v_mfma_f32_16x16x32_bf16 v[38:41], v[172:175], v[192:195], v[38:41]
	v_mfma_f32_16x16x32_bf16 v[38:41], v[176:179], v[196:199], v[38:41]
	v_mfma_f32_16x16x32_bf16 v[50:53], v[176:179], v[188:191], v[50:53]
	v_mfma_f32_16x16x32_bf16 v[50:53], v[172:175], v[180:183], v[50:53]
	s_barrier
	s_add_i32 s62, s62, 2
	s_add_u32 s26, s26, 0x100
	s_addc_u32 s27, s27, 0
	s_add_u32 s52, s52, 0x100
	s_addc_u32 s53, s53, 0
	s_cmp_gt_u32 s62, 61
	s_cbranch_scc0 .LBB0_1595
	s_and_b64 vcc, exec, s[10:11]
	s_cbranch_vccz .LBB0_1598
	s_barrier

; #define PG8_STAGE(bufoff, gbase, voff) do { _Pragma("unroll") for (int _i = 0; _i < 2; ++_i) \
;         __builtin_amdgcn_global_load_lds((const unsigned*)((const char*)(gbase) + (voff)[_i]), (PG8_LAS unsigned*)(lds + (bufoff) + ldsw + _i * 8192), 16, 0, 0); } while (0)
; #define PG8_LDA(dst, b, h) do { _Pragma("unroll") for (int m = 0; m < 4; ++m) _Pragma("unroll") for (int k = 0; k < 2; ++k) dst[m][k] = *(const PG8_LAS bf16x8*)(lds + PG8_SA(b, h) + aoff + m * 2048 + k * 1024); } while (0)
; #define PG8_LDB(dst, b, h) do { _Pragma("unroll") for (int n = 0; n < 2; ++n) _Pragma("unroll") for (int k = 0; k < 2; ++k) dst[n][k] = *(const PG8_LAS bf16x8*)(lds + PG8_SB(b, h) + boff + n * 2048 + k * 1024); } while (0)
; #define PG8_MMA(ai, bj, At, Bt) do { __builtin_amdgcn_s_setprio(1); _Pragma("unroll") for (int m = 0; m < 4; ++m) _Pragma("unroll") for (int n = 0; n < 2; ++n) _Pragma("unroll") for (int k = 0; k < 2; ++k) \
;         acc[ai][bj][m][n] = __builtin_amdgcn_mfma_f32_16x16x32_bf16(Bt[n][k], At[m][k], acc[ai][bj][m][n], 0, 0, 0); __builtin_amdgcn_s_setprio(0); } while (0)
; #define PG8_WAIT_V(n) asm volatile("s_waitcnt vmcnt(" #n ")" ::: "memory")
; #define PG8_WAIT_L(n) asm volatile("s_waitcnt lgkmcnt(" #n ")" ::: "memory")
; template <class Epi, class Sched, bool ALIGN_EPI = false, bool SP2 = false>
; __device__ __forceinline__ void gemm_phase(PG8_LAS unsigned char* lds, const Gemm g, const Sched& S, const Epi& E) {
;     ...
;             const bool last = (t == nt - 2);
;             const char* a1 = cA + (size_t)(t + 1) * kstep;
;             const char* a2 = last ? nA : cA + (size_t)(t + 2) * kstep; const char* b2 = last ? nB : cB + (size_t)(t + 2) * kstep;
;             const char* a3 = a2 + kstep; const char* b3 = b2 + kstep;
;             if (last && has_next) S.a_ready(nxt);
;             if constexpr (SP2) {
;             PG8_LDB(B0, 0, 0); PG8_LDB(B1, 0, 1); PG8_SCHED; PG8_LDA(At, 0, 0); PG8_STAGE(PG8_SA(1, 1), a1 + hstep, voffA);
;             PG8_WAIT_V(8); PG8_WAIT_L(0); PG8_BAR; PG8_MMA(0, 0, At, B0); PG8_MMA(0, 1, At, B1); PG8_BAR; PG8_SCHED;
;             PG8_LDA(At, 0, 1); PG8_STAGE(PG8_SB(0, 0), b2, voffB); PG8_STAGE(PG8_SB(0, 1), b2 + hstep, voffB); PG8_STAGE(PG8_SA(0, 0), a2, voffA);
;             PG8_WAIT_V(8); PG8_WAIT_L(0); PG8_BAR; PG8_MMA(1, 0, At, B0); PG8_MMA(1, 1, At, B1); PG8_BAR; PG8_SCHED;
.LBB0_1681:
	ds_read_b128 v[160:163], v241 offset:0
	ds_read_b128 v[166:169], v241 offset:1024
	ds_read_b128 v[170:173], v241 offset:2048
	ds_read_b128 v[174:177], v241 offset:3072
	ds_read_b128 v[178:181], v241 offset:16384
	ds_read_b128 v[182:185], v241 offset:17408
	ds_read_b128 v[186:189], v241 offset:18432
	ds_read_b128 v[190:193], v241 offset:19456
	s_add_u32 s22, s24, 0xfff00080
	s_addc_u32 s23, s25, -1
	s_cmp_eq_u32 s52, 60
	s_cselect_b32 s27, s15, s23
	s_cselect_b32 s26, s48, s22
	s_cselect_b32 s23, s13, s51
	s_cselect_b32 s22, s49, s50
	s_add_i32 m0, s21, 0xc000
	ds_read_b128 v[194:197], v155
	ds_read_b128 v[198:201], v155 offset:1024
	ds_read_b128 v[202:205], v155 offset:2048
	ds_read_b128 v[206:209], v155 offset:3072
	ds_read_b128 v[210:213], v155 offset:4096
	ds_read_b128 v[214:217], v155 offset:5120
	ds_read_b128 v[218:221], v155 offset:6144
	ds_read_b128 v[222:225], v155 offset:7168
	global_load_lds_dwordx4 v138, s[24:25]
	s_add_i32 m0, s21, 0xe000
	s_nop 0
	global_load_lds_dwordx4 v140, s[24:25]
	s_waitcnt vmcnt(8) lgkmcnt(0)
	s_barrier
	v_mfma_f32_16x16x32_bf16 v[122:125], v[160:163], v[194:197], v[122:125]
	v_mfma_f32_16x16x32_bf16 v[122:125], v[166:169], v[198:201], v[122:125]
	v_mfma_f32_16x16x32_bf16 v[106:109], v[166:169], v[206:209], v[106:109]
	v_mfma_f32_16x16x32_bf16 v[106:109], v[160:163], v[202:205], v[106:109]
	v_mfma_f32_16x16x32_bf16 v[90:93], v[160:163], v[210:213], v[90:93]
	v_mfma_f32_16x16x32_bf16 v[90:93], v[166:169], v[214:217], v[90:93]
	v_mfma_f32_16x16x32_bf16 v[74:77], v[166:169], v[222:225], v[74:77]
	v_mfma_f32_16x16x32_bf16 v[74:77], v[160:163], v[218:221], v[74:77]
	v_mfma_f32_16x16x32_bf16 v[62:65], v[170:173], v[218:221], v[62:65]
	v_mfma_f32_16x16x32_bf16 v[62:65], v[174:177], v[222:225], v[62:65]
	v_mfma_f32_16x16x32_bf16 v[82:85], v[174:177], v[214:217], v[82:85]
	v_mfma_f32_16x16x32_bf16 v[82:85], v[170:173], v[210:213], v[82:85]
	v_mfma_f32_16x16x32_bf16 v[98:101], v[170:173], v[202:205], v[98:101]
	v_mfma_f32_16x16x32_bf16 v[98:101], v[174:177], v[206:209], v[98:101]
	v_mfma_f32_16x16x32_bf16 v[114:117], v[174:177], v[198:201], v[114:117]
	v_mfma_f32_16x16x32_bf16 v[114:117], v[170:173], v[194:197], v[114:117]
	v_mfma_f32_16x16x32_bf16 v[126:129], v[178:181], v[194:197], v[126:129]
	v_mfma_f32_16x16x32_bf16 v[126:129], v[182:185], v[198:201], v[126:129]
	v_mfma_f32_16x16x32_bf16 v[110:113], v[182:185], v[206:209], v[110:113]
	v_mfma_f32_16x16x32_bf16 v[110:113], v[178:181], v[202:205], v[110:113]
	v_mfma_f32_16x16x32_bf16 v[94:97], v[178:181], v[210:213], v[94:97]
	v_mfma_f32_16x16x32_bf16 v[94:97], v[182:185], v[214:217], v[94:97]
	v_mfma_f32_16x16x32_bf16 v[78:81], v[182:185], v[222:225], v[78:81]
	v_mfma_f32_16x16x32_bf16 v[78:81], v[178:181], v[218:221], v[78:81]
	v_mfma_f32_16x16x32_bf16 v[70:73], v[186:189], v[218:221], v[70:73]
	v_mfma_f32_16x16x32_bf16 v[70:73], v[190:193], v[222:225], v[70:73]
	v_mfma_f32_16x16x32_bf16 v[86:89], v[190:193], v[214:217], v[86:89]
	v_mfma_f32_16x16x32_bf16 v[86:89], v[186:189], v[210:213], v[86:89]
	v_mfma_f32_16x16x32_bf16 v[102:105], v[186:189], v[202:205], v[102:105]
	v_mfma_f32_16x16x32_bf16 v[102:105], v[190:193], v[206:209], v[102:105]
	v_mfma_f32_16x16x32_bf16 v[118:121], v[190:193], v[198:201], v[118:121]
	v_mfma_f32_16x16x32_bf16 v[118:121], v[186:189], v[194:197], v[118:121]
	s_barrier
	s_add_i32 s33, s44, s29
	s_mov_b32 m0, s33
	ds_read_b128 v[194:197], v155 offset:16384
	ds_read_b128 v[198:201], v155 offset:17408
	ds_read_b128 v[202:205], v155 offset:18432
	ds_read_b128 v[206:209], v155 offset:19456
	ds_read_b128 v[210:213], v155 offset:20480
	ds_read_b128 v[214:217], v155 offset:21504
	ds_read_b128 v[218:221], v155 offset:22528
	ds_read_b128 v[222:225], v155 offset:23552
	global_load_lds_dwordx4 v132, s[22:23]
	s_add_i32 m0, s33, 0x2000
	s_add_u32 s62, s22, 0x100000
	s_addc_u32 s63, s23, 0
	s_add_i32 s33, s45, s29
	global_load_lds_dwordx4 v136, s[22:23]
	s_mov_b32 m0, s33
	s_add_u32 s100, s26, 0x80
	s_addc_u32 s101, s27, 0
	global_load_lds_dwordx4 v132, s[62:63]
	s_add_i32 m0, s33, 0x2000
	s_nop 0
	global_load_lds_dwordx4 v136, s[62:63]
	s_mov_b32 m0, s21
	s_nop 0
	global_load_lds_dwordx4 v130, s[26:27]
	s_mov_b32 m0, s34
	s_nop 0
	global_load_lds_dwordx4 v134, s[26:27]
	s_waitcnt vmcnt(8) lgkmcnt(0)
	s_barrier
	v_mfma_f32_16x16x32_bf16 v[58:61], v[160:163], v[194:197], v[58:61]
	v_mfma_f32_16x16x32_bf16 v[58:61], v[166:169], v[198:201], v[58:61]
	v_mfma_f32_16x16x32_bf16 v[42:45], v[166:169], v[206:209], v[42:45]
	v_mfma_f32_16x16x32_bf16 v[42:45], v[160:163], v[202:205], v[42:45]
	v_mfma_f32_16x16x32_bf16 v[26:29], v[160:163], v[210:213], v[26:29]
	v_mfma_f32_16x16x32_bf16 v[26:29], v[166:169], v[214:217], v[26:29]
	v_mfma_f32_16x16x32_bf16 v[10:13], v[166:169], v[222:225], v[10:13]
	v_mfma_f32_16x16x32_bf16 v[10:13], v[160:163], v[218:221], v[10:13]
	v_mfma_f32_16x16x32_bf16 v[2:5], v[170:173], v[218:221], v[2:5]
	v_mfma_f32_16x16x32_bf16 v[2:5], v[174:177], v[222:225], v[2:5]
	v_mfma_f32_16x16x32_bf16 v[18:21], v[174:177], v[214:217], v[18:21]
	v_mfma_f32_16x16x32_bf16 v[18:21], v[170:173], v[210:213], v[18:21]
	v_mfma_f32_16x16x32_bf16 v[34:37], v[170:173], v[202:205], v[34:37]
	v_mfma_f32_16x16x32_bf16 v[34:37], v[174:177], v[206:209], v[34:37]
	v_mfma_f32_16x16x32_bf16 v[50:53], v[174:177], v[198:201], v[50:53]
	v_mfma_f32_16x16x32_bf16 v[50:53], v[170:173], v[194:197], v[50:53]
	v_mfma_f32_16x16x32_bf16 v[66:69], v[178:181], v[194:197], v[66:69]
	v_mfma_f32_16x16x32_bf16 v[66:69], v[182:185], v[198:201], v[66:69]
	v_mfma_f32_16x16x32_bf16 v[46:49], v[182:185], v[206:209], v[46:49]
	v_mfma_f32_16x16x32_bf16 v[46:49], v[178:181], v[202:205], v[46:49]
	v_mfma_f32_16x16x32_bf16 v[30:33], v[178:181], v[210:213], v[30:33]
	v_mfma_f32_16x16x32_bf16 v[30:33], v[182:185], v[214:217], v[30:33]
	v_mfma_f32_16x16x32_bf16 v[14:17], v[182:185], v[222:225], v[14:17]
	v_mfma_f32_16x16x32_bf16 v[14:17], v[178:181], v[218:221], v[14:17]
	v_mfma_f32_16x16x32_bf16 v[6:9], v[186:189], v[218:221], v[6:9]
	v_mfma_f32_16x16x32_bf16 v[6:9], v[190:193], v[222:225], v[6:9]
	v_mfma_f32_16x16x32_bf16 v[22:25], v[190:193], v[214:217], v[22:25]
	v_mfma_f32_16x16x32_bf16 v[22:25], v[186:189], v[210:213], v[22:25]
	v_mfma_f32_16x16x32_bf16 v[38:41], v[186:189], v[202:205], v[38:41]
	v_mfma_f32_16x16x32_bf16 v[38:41], v[190:193], v[206:209], v[38:41]
	v_mfma_f32_16x16x32_bf16 v[54:57], v[190:193], v[198:201], v[54:57]
	v_mfma_f32_16x16x32_bf16 v[54:57], v[186:189], v[194:197], v[54:57]
	s_barrier
; #define PG8_STAGE(bufoff, gbase, voff) do { _Pragma("unroll") for (int _i = 0; _i < 2; ++_i) \
;         __builtin_amdgcn_global_load_lds((const unsigned*)((const char*)(gbase) + (voff)[_i]), (PG8_LAS unsigned*)(lds + (bufoff) + ldsw + _i * 8192), 16, 0, 0); } while (0)
; #define PG8_LDA(dst, b, h) do { _Pragma("unroll") for (int m = 0; m < 4; ++m) _Pragma("unroll") for (int k = 0; k < 2; ++k) dst[m][k] = *(const PG8_LAS bf16x8*)(lds + PG8_SA(b, h) + aoff + m * 2048 + k * 1024); } while (0)
; #define PG8_LDB(dst, b, h) do { _Pragma("unroll") for (int n = 0; n < 2; ++n) _Pragma("unroll") for (int k = 0; k < 2; ++k) dst[n][k] = *(const PG8_LAS bf16x8*)(lds + PG8_SB(b, h) + boff + n * 2048 + k * 1024); } while (0)
; #define PG8_MMA(ai, bj, At, Bt) do { __builtin_amdgcn_s_setprio(1); _Pragma("unroll") for (int m = 0; m < 4; ++m) _Pragma("unroll") for (int n = 0; n < 2; ++n) _Pragma("unroll") for (int k = 0; k < 2; ++k) \
;         acc[ai][bj][m][n] = __builtin_amdgcn_mfma_f32_16x16x32_bf16(Bt[n][k], At[m][k], acc[ai][bj][m][n], 0, 0, 0); __builtin_amdgcn_s_setprio(0); } while (0)
; #define PG8_WAIT_V(n) asm volatile("s_waitcnt vmcnt(" #n ")" ::: "memory")
; #define PG8_WAIT_L(n) asm volatile("s_waitcnt lgkmcnt(" #n ")" ::: "memory")
; #define PG8_BAR __builtin_amdgcn_s_barrier()
; #define PG8_SCHED __builtin_amdgcn_sched_barrier(0)
; template <class Epi, class Sched, bool ALIGN_EPI = false, bool SP2 = false>
; __device__ __forceinline__ void gemm_phase(PG8_LAS unsigned char* lds, const Gemm g, const Sched& S, const Epi& E) {
;     ...
;             PG8_LDB(B0, 1, 0); PG8_LDB(B1, 1, 1); PG8_SCHED; PG8_LDA(At, 1, 0); PG8_STAGE(PG8_SA(0, 1), a2 + hstep, voffA);
;             PG8_WAIT_V(8); PG8_WAIT_L(0); PG8_BAR; PG8_MMA(0, 0, At, B0); PG8_MMA(0, 1, At, B1); PG8_BAR; PG8_SCHED;
;             PG8_LDA(At, 1, 1); PG8_STAGE(PG8_SB(1, 0), b3, voffB); PG8_STAGE(PG8_SB(1, 1), b3 + hstep, voffB); PG8_STAGE(PG8_SA(1, 0), a3, voffA);
;             PG8_WAIT_V(8); PG8_WAIT_L(0); PG8_BAR; PG8_MMA(1, 0, At, B0); PG8_MMA(1, 1, At, B1); PG8_BAR; PG8_SCHED;
;     ...
;         if constexpr (ALIGN_EPI) { if (wr == 0) PG8_BAR; }
	s_add_i32 s33, 0, 0x18000
	s_add_i32 s42, 0, 0x1c000
	ds_read_b128 v[160:163], v241 offset:32768
	ds_read_b128 v[166:169], v241 offset:33792
	ds_read_b128 v[170:173], v241 offset:34816
	ds_read_b128 v[174:177], v241 offset:35840
	ds_read_b128 v[178:181], v241 offset:49152
	ds_read_b128 v[182:185], v241 offset:50176
	ds_read_b128 v[186:189], v241 offset:51200
	ds_read_b128 v[190:193], v241 offset:52224
	s_add_u32 s26, s26, 0x100000
	s_addc_u32 s27, s27, 0
	s_mov_b32 m0, s35
	ds_read_b128 v[194:197], v155 offset:32768
	ds_read_b128 v[198:201], v155 offset:33792
	ds_read_b128 v[202:205], v155 offset:34816
	ds_read_b128 v[206:209], v155 offset:35840
	ds_read_b128 v[210:213], v155 offset:36864
	ds_read_b128 v[214:217], v155 offset:37888
	ds_read_b128 v[218:221], v155 offset:38912
	ds_read_b128 v[222:225], v155 offset:39936
	global_load_lds_dwordx4 v130, s[26:27]
	s_mov_b32 m0, s36
	s_nop 0
	global_load_lds_dwordx4 v134, s[26:27]
	s_waitcnt vmcnt(8) lgkmcnt(0)
	s_barrier
	v_mfma_f32_16x16x32_bf16 v[122:125], v[160:163], v[194:197], v[122:125]
	v_mfma_f32_16x16x32_bf16 v[122:125], v[166:169], v[198:201], v[122:125]
	v_mfma_f32_16x16x32_bf16 v[106:109], v[166:169], v[206:209], v[106:109]
	v_mfma_f32_16x16x32_bf16 v[106:109], v[160:163], v[202:205], v[106:109]
	v_mfma_f32_16x16x32_bf16 v[90:93], v[160:163], v[210:213], v[90:93]
	v_mfma_f32_16x16x32_bf16 v[90:93], v[166:169], v[214:217], v[90:93]
	v_mfma_f32_16x16x32_bf16 v[74:77], v[166:169], v[222:225], v[74:77]
	v_mfma_f32_16x16x32_bf16 v[74:77], v[160:163], v[218:221], v[74:77]
	v_mfma_f32_16x16x32_bf16 v[62:65], v[170:173], v[218:221], v[62:65]
	v_mfma_f32_16x16x32_bf16 v[62:65], v[174:177], v[222:225], v[62:65]
	v_mfma_f32_16x16x32_bf16 v[82:85], v[174:177], v[214:217], v[82:85]
	v_mfma_f32_16x16x32_bf16 v[82:85], v[170:173], v[210:213], v[82:85]
	v_mfma_f32_16x16x32_bf16 v[98:101], v[170:173], v[202:205], v[98:101]
	v_mfma_f32_16x16x32_bf16 v[98:101], v[174:177], v[206:209], v[98:101]
	v_mfma_f32_16x16x32_bf16 v[114:117], v[174:177], v[198:201], v[114:117]
	v_mfma_f32_16x16x32_bf16 v[114:117], v[170:173], v[194:197], v[114:117]
	v_mfma_f32_16x16x32_bf16 v[126:129], v[178:181], v[194:197], v[126:129]
	v_mfma_f32_16x16x32_bf16 v[126:129], v[182:185], v[198:201], v[126:129]
	v_mfma_f32_16x16x32_bf16 v[110:113], v[182:185], v[206:209], v[110:113]
	v_mfma_f32_16x16x32_bf16 v[110:113], v[178:181], v[202:205], v[110:113]
	v_mfma_f32_16x16x32_bf16 v[94:97], v[178:181], v[210:213], v[94:97]
	v_mfma_f32_16x16x32_bf16 v[94:97], v[182:185], v[214:217], v[94:97]
	v_mfma_f32_16x16x32_bf16 v[78:81], v[182:185], v[222:225], v[78:81]
	v_mfma_f32_16x16x32_bf16 v[78:81], v[178:181], v[218:221], v[78:81]
	v_mfma_f32_16x16x32_bf16 v[70:73], v[186:189], v[218:221], v[70:73]
	v_mfma_f32_16x16x32_bf16 v[70:73], v[190:193], v[222:225], v[70:73]
	v_mfma_f32_16x16x32_bf16 v[86:89], v[190:193], v[214:217], v[86:89]
	v_mfma_f32_16x16x32_bf16 v[86:89], v[186:189], v[210:213], v[86:89]
	v_mfma_f32_16x16x32_bf16 v[102:105], v[186:189], v[202:205], v[102:105]
	v_mfma_f32_16x16x32_bf16 v[102:105], v[190:193], v[206:209], v[102:105]
	v_mfma_f32_16x16x32_bf16 v[118:121], v[190:193], v[198:201], v[118:121]
	v_mfma_f32_16x16x32_bf16 v[118:121], v[186:189], v[194:197], v[118:121]
	s_barrier
	s_add_i32 s26, s33, s29
	s_add_i32 m0, s26, 0xffffff80
	ds_read_b128 v[194:197], v155 offset:49152
	ds_read_b128 v[198:201], v155 offset:50176
	ds_read_b128 v[202:205], v155 offset:51200
	ds_read_b128 v[206:209], v155 offset:52224
	ds_read_b128 v[210:213], v155 offset:53248
	ds_read_b128 v[214:217], v155 offset:54272
	ds_read_b128 v[218:221], v155 offset:55296
	ds_read_b128 v[222:225], v155 offset:56320
	global_load_lds_dwordx4 v132, s[22:23] offset:128
	s_add_i32 m0, s26, 0x1f80
	s_add_i32 s26, s42, s29
	global_load_lds_dwordx4 v136, s[22:23] offset:128
	s_add_u32 s22, s22, 0x100080
	s_addc_u32 s23, s23, 0
	s_mov_b32 m0, s26
	s_nop 0
	global_load_lds_dwordx4 v132, s[22:23]
	s_add_i32 m0, s26, 0x2000
	s_nop 0
	global_load_lds_dwordx4 v136, s[22:23]
	s_mov_b32 m0, s41
	s_nop 0
	global_load_lds_dwordx4 v130, s[100:101]
	s_mov_b32 m0, s43
	s_nop 0
	global_load_lds_dwordx4 v134, s[100:101]
	s_waitcnt vmcnt(8) lgkmcnt(0)
	s_barrier
	v_mfma_f32_16x16x32_bf16 v[58:61], v[160:163], v[194:197], v[58:61]
	v_mfma_f32_16x16x32_bf16 v[58:61], v[166:169], v[198:201], v[58:61]
	v_mfma_f32_16x16x32_bf16 v[42:45], v[166:169], v[206:209], v[42:45]
	v_mfma_f32_16x16x32_bf16 v[42:45], v[160:163], v[202:205], v[42:45]
	v_mfma_f32_16x16x32_bf16 v[26:29], v[160:163], v[210:213], v[26:29]
	v_mfma_f32_16x16x32_bf16 v[26:29], v[166:169], v[214:217], v[26:29]
	v_mfma_f32_16x16x32_bf16 v[10:13], v[166:169], v[222:225], v[10:13]
	v_mfma_f32_16x16x32_bf16 v[10:13], v[160:163], v[218:221], v[10:13]
	v_mfma_f32_16x16x32_bf16 v[2:5], v[170:173], v[218:221], v[2:5]
	v_mfma_f32_16x16x32_bf16 v[2:5], v[174:177], v[222:225], v[2:5]
	v_mfma_f32_16x16x32_bf16 v[18:21], v[174:177], v[214:217], v[18:21]
	v_mfma_f32_16x16x32_bf16 v[18:21], v[170:173], v[210:213], v[18:21]
	v_mfma_f32_16x16x32_bf16 v[34:37], v[170:173], v[202:205], v[34:37]
	v_mfma_f32_16x16x32_bf16 v[34:37], v[174:177], v[206:209], v[34:37]
	v_mfma_f32_16x16x32_bf16 v[50:53], v[174:177], v[198:201], v[50:53]
	v_mfma_f32_16x16x32_bf16 v[50:53], v[170:173], v[194:197], v[50:53]
	v_mfma_f32_16x16x32_bf16 v[66:69], v[178:181], v[194:197], v[66:69]
	v_mfma_f32_16x16x32_bf16 v[66:69], v[182:185], v[198:201], v[66:69]
	v_mfma_f32_16x16x32_bf16 v[46:49], v[182:185], v[206:209], v[46:49]
	v_mfma_f32_16x16x32_bf16 v[46:49], v[178:181], v[202:205], v[46:49]
	v_mfma_f32_16x16x32_bf16 v[30:33], v[178:181], v[210:213], v[30:33]
	v_mfma_f32_16x16x32_bf16 v[30:33], v[182:185], v[214:217], v[30:33]
	v_mfma_f32_16x16x32_bf16 v[14:17], v[182:185], v[222:225], v[14:17]
	v_mfma_f32_16x16x32_bf16 v[14:17], v[178:181], v[218:221], v[14:17]
	v_mfma_f32_16x16x32_bf16 v[6:9], v[186:189], v[218:221], v[6:9]
	v_mfma_f32_16x16x32_bf16 v[6:9], v[190:193], v[222:225], v[6:9]
	v_mfma_f32_16x16x32_bf16 v[22:25], v[190:193], v[214:217], v[22:25]
	v_mfma_f32_16x16x32_bf16 v[22:25], v[186:189], v[210:213], v[22:25]
	v_mfma_f32_16x16x32_bf16 v[38:41], v[186:189], v[202:205], v[38:41]
	v_mfma_f32_16x16x32_bf16 v[38:41], v[190:193], v[206:209], v[38:41]
	v_mfma_f32_16x16x32_bf16 v[54:57], v[190:193], v[198:201], v[54:57]
	v_mfma_f32_16x16x32_bf16 v[54:57], v[186:189], v[194:197], v[54:57]
	s_barrier
	s_add_i32 s52, s52, 2
	s_add_u32 s24, s24, 0x100
	s_addc_u32 s25, s25, 0
	s_add_u32 s50, s50, 0x100
	s_addc_u32 s51, s51, 0
	s_cmp_gt_u32 s52, 61
	s_cbranch_scc0 .LBB0_1681
	s_and_b64 vcc, exec, s[8:9]
	s_cbranch_vccz .LBB0_1684
	s_barrier

; #define PG8_STAGE(bufoff, gbase, voff) do { _Pragma("unroll") for (int _i = 0; _i < 2; ++_i) \
;         __builtin_amdgcn_global_load_lds((const unsigned*)((const char*)(gbase) + (voff)[_i]), (PG8_LAS unsigned*)(lds + (bufoff) + ldsw + _i * 8192), 16, 0, 0); } while (0)
; #define PG8_LDA(dst, b, h) do { _Pragma("unroll") for (int m = 0; m < 4; ++m) _Pragma("unroll") for (int k = 0; k < 2; ++k) dst[m][k] = *(const PG8_LAS bf16x8*)(lds + PG8_SA(b, h) + aoff + m * 2048 + k * 1024); } while (0)
; #define PG8_LDB(dst, b, h) do { _Pragma("unroll") for (int n = 0; n < 2; ++n) _Pragma("unroll") for (int k = 0; k < 2; ++k) dst[n][k] = *(const PG8_LAS bf16x8*)(lds + PG8_SB(b, h) + boff + n * 2048 + k * 1024); } while (0)
; #define PG8_MMA(ai, bj, At, Bt) do { __builtin_amdgcn_s_setprio(1); _Pragma("unroll") for (int m = 0; m < 4; ++m) _Pragma("unroll") for (int n = 0; n < 2; ++n) _Pragma("unroll") for (int k = 0; k < 2; ++k) \
;         acc[ai][bj][m][n] = __builtin_amdgcn_mfma_f32_16x16x32_bf16(Bt[n][k], At[m][k], acc[ai][bj][m][n], 0, 0, 0); __builtin_amdgcn_s_setprio(0); } while (0)
; #define PG8_WAIT_V(n) asm volatile("s_waitcnt vmcnt(" #n ")" ::: "memory")
; #define PG8_WAIT_L(n) asm volatile("s_waitcnt lgkmcnt(" #n ")" ::: "memory")
; template <class Epi, class Sched, bool ALIGN_EPI = false, bool SP2 = false>
; __device__ __forceinline__ void gemm_phase(PG8_LAS unsigned char* lds, const Gemm g, const Sched& S, const Epi& E) {
;     ...
;             const bool last = (t == nt - 2);
;             const char* a1 = cA + (size_t)(t + 1) * kstep;
;             const char* a2 = last ? nA : cA + (size_t)(t + 2) * kstep; const char* b2 = last ? nB : cB + (size_t)(t + 2) * kstep;
;             const char* a3 = a2 + kstep; const char* b3 = b2 + kstep;
;             if (last && has_next) S.a_ready(nxt);
;             if constexpr (SP2) {
;             PG8_LDB(B0, 0, 0); PG8_LDB(B1, 0, 1); PG8_SCHED; PG8_LDA(At, 0, 0); PG8_STAGE(PG8_SA(1, 1), a1 + hstep, voffA);
;             PG8_WAIT_V(8); PG8_WAIT_L(0); PG8_BAR; PG8_MMA(0, 0, At, B0); PG8_MMA(0, 1, At, B1); PG8_BAR; PG8_SCHED;
;             PG8_LDA(At, 0, 1); PG8_STAGE(PG8_SB(0, 0), b2, voffB); PG8_STAGE(PG8_SB(0, 1), b2 + hstep, voffB); PG8_STAGE(PG8_SA(0, 0), a2, voffA);
;             PG8_WAIT_V(8); PG8_WAIT_L(0); PG8_BAR; PG8_MMA(1, 0, At, B0); PG8_MMA(1, 1, At, B1); PG8_BAR; PG8_SCHED;
.LBB0_1801:
	ds_read_b128 v[130:133], v241 offset:0
	ds_read_b128 v[134:137], v241 offset:1024
	ds_read_b128 v[138:141], v241 offset:2048
	ds_read_b128 v[142:145], v241 offset:3072
	ds_read_b128 v[146:149], v241 offset:16384
	ds_read_b128 v[150:153], v241 offset:17408
	ds_read_b128 v[170:173], v241 offset:18432
	ds_read_b128 v[174:177], v241 offset:19456
	s_add_u32 s16, s18, 0xffd50080
	s_addc_u32 s17, s19, -1
	s_cmpk_eq_i32 s48, 0xa8
	s_cselect_b32 s21, s5, s17
	s_cselect_b32 s20, s4, s16
	s_cselect_b32 s17, s15, s47
	s_cselect_b32 s16, s14, s46
	s_add_i32 m0, s25, 0xc000
	ds_read_b128 v[178:181], v184
	ds_read_b128 v[186:189], v184 offset:1024
	ds_read_b128 v[190:193], v184 offset:2048
	ds_read_b128 v[194:197], v184 offset:3072
	ds_read_b128 v[198:201], v184 offset:4096
	ds_read_b128 v[202:205], v184 offset:5120
	ds_read_b128 v[206:209], v184 offset:6144
	ds_read_b128 v[210:213], v184 offset:7168
	global_load_lds_dwordx4 v0, s[18:19]
	s_add_i32 m0, s25, 0xe000
	s_nop 0
	global_load_lds_dwordx4 v162, s[18:19]
	s_waitcnt vmcnt(8) lgkmcnt(0)
	s_barrier
	v_mfma_f32_16x16x32_bf16 v[114:117], v[130:133], v[178:181], v[114:117]
	v_mfma_f32_16x16x32_bf16 v[114:117], v[134:137], v[186:189], v[114:117]
	v_mfma_f32_16x16x32_bf16 v[106:109], v[134:137], v[194:197], v[106:109]
	v_mfma_f32_16x16x32_bf16 v[106:109], v[130:133], v[190:193], v[106:109]
	v_mfma_f32_16x16x32_bf16 v[90:93], v[130:133], v[198:201], v[90:93]
	v_mfma_f32_16x16x32_bf16 v[90:93], v[134:137], v[202:205], v[90:93]
	v_mfma_f32_16x16x32_bf16 v[74:77], v[134:137], v[210:213], v[74:77]
	v_mfma_f32_16x16x32_bf16 v[74:77], v[130:133], v[206:209], v[74:77]
	v_mfma_f32_16x16x32_bf16 v[66:69], v[138:141], v[206:209], v[66:69]
	v_mfma_f32_16x16x32_bf16 v[66:69], v[142:145], v[210:213], v[66:69]
	v_mfma_f32_16x16x32_bf16 v[82:85], v[142:145], v[202:205], v[82:85]
	v_mfma_f32_16x16x32_bf16 v[82:85], v[138:141], v[198:201], v[82:85]
	v_mfma_f32_16x16x32_bf16 v[98:101], v[138:141], v[190:193], v[98:101]
	v_mfma_f32_16x16x32_bf16 v[98:101], v[142:145], v[194:197], v[98:101]
	v_mfma_f32_16x16x32_bf16 v[118:121], v[142:145], v[186:189], v[118:121]
	v_mfma_f32_16x16x32_bf16 v[118:121], v[138:141], v[178:181], v[118:121]
	v_mfma_f32_16x16x32_bf16 v[122:125], v[146:149], v[178:181], v[122:125]
	v_mfma_f32_16x16x32_bf16 v[122:125], v[150:153], v[186:189], v[122:125]
	v_mfma_f32_16x16x32_bf16 v[110:113], v[150:153], v[194:197], v[110:113]
	v_mfma_f32_16x16x32_bf16 v[110:113], v[146:149], v[190:193], v[110:113]
	v_mfma_f32_16x16x32_bf16 v[94:97], v[146:149], v[198:201], v[94:97]
	v_mfma_f32_16x16x32_bf16 v[94:97], v[150:153], v[202:205], v[94:97]
	v_mfma_f32_16x16x32_bf16 v[78:81], v[150:153], v[210:213], v[78:81]
	v_mfma_f32_16x16x32_bf16 v[78:81], v[146:149], v[206:209], v[78:81]
	v_mfma_f32_16x16x32_bf16 v[70:73], v[170:173], v[206:209], v[70:73]
	v_mfma_f32_16x16x32_bf16 v[70:73], v[174:177], v[210:213], v[70:73]
	v_mfma_f32_16x16x32_bf16 v[86:89], v[174:177], v[202:205], v[86:89]
	v_mfma_f32_16x16x32_bf16 v[86:89], v[170:173], v[198:201], v[86:89]
	v_mfma_f32_16x16x32_bf16 v[102:105], v[170:173], v[190:193], v[102:105]
	v_mfma_f32_16x16x32_bf16 v[102:105], v[174:177], v[194:197], v[102:105]
	v_mfma_f32_16x16x32_bf16 v[126:129], v[174:177], v[186:189], v[126:129]
	v_mfma_f32_16x16x32_bf16 v[126:129], v[170:173], v[178:181], v[126:129]
	s_barrier
	s_add_i32 s33, s36, s24
	s_mov_b32 m0, s33
	ds_read_b128 v[178:181], v184 offset:16384
	ds_read_b128 v[186:189], v184 offset:17408
	ds_read_b128 v[190:193], v184 offset:18432
	ds_read_b128 v[194:197], v184 offset:19456
	ds_read_b128 v[198:201], v184 offset:20480
	ds_read_b128 v[202:205], v184 offset:21504
	ds_read_b128 v[206:209], v184 offset:22528
	ds_read_b128 v[210:213], v184 offset:23552
	global_load_lds_dwordx4 v156, s[16:17]
	s_add_i32 m0, s33, 0x2000
	s_add_u32 s50, s16, 0x2b0000
	s_addc_u32 s51, s17, 0
	s_add_i32 s33, s37, s24
	global_load_lds_dwordx4 v160, s[16:17]
	s_mov_b32 m0, s33
	s_add_u32 s100, s20, 0x80
	s_addc_u32 s101, s21, 0
	global_load_lds_dwordx4 v156, s[50:51]
	s_add_i32 m0, s33, 0x2000
	s_nop 0
	global_load_lds_dwordx4 v160, s[50:51]
	s_mov_b32 m0, s25
	s_nop 0
	global_load_lds_dwordx4 v154, s[20:21]
	s_mov_b32 m0, s26
	s_nop 0
	global_load_lds_dwordx4 v158, s[20:21]
	s_waitcnt vmcnt(8) lgkmcnt(0)
	s_barrier
	v_mfma_f32_16x16x32_bf16 v[58:61], v[130:133], v[178:181], v[58:61]
	v_mfma_f32_16x16x32_bf16 v[58:61], v[134:137], v[186:189], v[58:61]
	v_mfma_f32_16x16x32_bf16 v[42:45], v[134:137], v[194:197], v[42:45]
	v_mfma_f32_16x16x32_bf16 v[42:45], v[130:133], v[190:193], v[42:45]
	v_mfma_f32_16x16x32_bf16 v[26:29], v[130:133], v[198:201], v[26:29]
	v_mfma_f32_16x16x32_bf16 v[26:29], v[134:137], v[202:205], v[26:29]
	v_mfma_f32_16x16x32_bf16 v[6:9], v[134:137], v[210:213], v[6:9]
	v_mfma_f32_16x16x32_bf16 v[6:9], v[130:133], v[206:209], v[6:9]
	v_mfma_f32_16x16x32_bf16 v[2:5], v[138:141], v[206:209], v[2:5]
	v_mfma_f32_16x16x32_bf16 v[2:5], v[142:145], v[210:213], v[2:5]
	v_mfma_f32_16x16x32_bf16 v[18:21], v[142:145], v[202:205], v[18:21]
	v_mfma_f32_16x16x32_bf16 v[18:21], v[138:141], v[198:201], v[18:21]
	v_mfma_f32_16x16x32_bf16 v[34:37], v[138:141], v[190:193], v[34:37]
	v_mfma_f32_16x16x32_bf16 v[34:37], v[142:145], v[194:197], v[34:37]
	v_mfma_f32_16x16x32_bf16 v[54:57], v[142:145], v[186:189], v[54:57]
	v_mfma_f32_16x16x32_bf16 v[54:57], v[138:141], v[178:181], v[54:57]
	v_mfma_f32_16x16x32_bf16 v[62:65], v[146:149], v[178:181], v[62:65]
	v_mfma_f32_16x16x32_bf16 v[62:65], v[150:153], v[186:189], v[62:65]
	v_mfma_f32_16x16x32_bf16 v[46:49], v[150:153], v[194:197], v[46:49]
	v_mfma_f32_16x16x32_bf16 v[46:49], v[146:149], v[190:193], v[46:49]
	v_mfma_f32_16x16x32_bf16 v[30:33], v[146:149], v[198:201], v[30:33]
	v_mfma_f32_16x16x32_bf16 v[30:33], v[150:153], v[202:205], v[30:33]
	v_mfma_f32_16x16x32_bf16 v[10:13], v[150:153], v[210:213], v[10:13]
	v_mfma_f32_16x16x32_bf16 v[10:13], v[146:149], v[206:209], v[10:13]
	v_mfma_f32_16x16x32_bf16 v[14:17], v[170:173], v[206:209], v[14:17]
	v_mfma_f32_16x16x32_bf16 v[14:17], v[174:177], v[210:213], v[14:17]
	v_mfma_f32_16x16x32_bf16 v[22:25], v[174:177], v[202:205], v[22:25]
	v_mfma_f32_16x16x32_bf16 v[22:25], v[170:173], v[198:201], v[22:25]
	v_mfma_f32_16x16x32_bf16 v[38:41], v[170:173], v[190:193], v[38:41]
	v_mfma_f32_16x16x32_bf16 v[38:41], v[174:177], v[194:197], v[38:41]
	v_mfma_f32_16x16x32_bf16 v[50:53], v[174:177], v[186:189], v[50:53]
	v_mfma_f32_16x16x32_bf16 v[50:53], v[170:173], v[178:181], v[50:53]
	s_barrier
; #define PG8_STAGE(bufoff, gbase, voff) do { _Pragma("unroll") for (int _i = 0; _i < 2; ++_i) \
;         __builtin_amdgcn_global_load_lds((const unsigned*)((const char*)(gbase) + (voff)[_i]), (PG8_LAS unsigned*)(lds + (bufoff) + ldsw + _i * 8192), 16, 0, 0); } while (0)
; #define PG8_LDA(dst, b, h) do { _Pragma("unroll") for (int m = 0; m < 4; ++m) _Pragma("unroll") for (int k = 0; k < 2; ++k) dst[m][k] = *(const PG8_LAS bf16x8*)(lds + PG8_SA(b, h) + aoff + m * 2048 + k * 1024); } while (0)
; #define PG8_LDB(dst, b, h) do { _Pragma("unroll") for (int n = 0; n < 2; ++n) _Pragma("unroll") for (int k = 0; k < 2; ++k) dst[n][k] = *(const PG8_LAS bf16x8*)(lds + PG8_SB(b, h) + boff + n * 2048 + k * 1024); } while (0)
; #define PG8_MMA(ai, bj, At, Bt) do { __builtin_amdgcn_s_setprio(1); _Pragma("unroll") for (int m = 0; m < 4; ++m) _Pragma("unroll") for (int n = 0; n < 2; ++n) _Pragma("unroll") for (int k = 0; k < 2; ++k) \
;         acc[ai][bj][m][n] = __builtin_amdgcn_mfma_f32_16x16x32_bf16(Bt[n][k], At[m][k], acc[ai][bj][m][n], 0, 0, 0); __builtin_amdgcn_s_setprio(0); } while (0)
; #define PG8_WAIT_V(n) asm volatile("s_waitcnt vmcnt(" #n ")" ::: "memory")
; #define PG8_WAIT_L(n) asm volatile("s_waitcnt lgkmcnt(" #n ")" ::: "memory")
; #define PG8_BAR __builtin_amdgcn_s_barrier()
; #define PG8_SCHED __builtin_amdgcn_sched_barrier(0)
; template <class Epi, class Sched, bool ALIGN_EPI = false, bool SP2 = false>
; __device__ __forceinline__ void gemm_phase(PG8_LAS unsigned char* lds, const Gemm g, const Sched& S, const Epi& E) {
;     ...
;             PG8_LDB(B0, 1, 0); PG8_LDB(B1, 1, 1); PG8_SCHED; PG8_LDA(At, 1, 0); PG8_STAGE(PG8_SA(0, 1), a2 + hstep, voffA);
;             PG8_WAIT_V(8); PG8_WAIT_L(0); PG8_BAR; PG8_MMA(0, 0, At, B0); PG8_MMA(0, 1, At, B1); PG8_BAR; PG8_SCHED;
;             PG8_LDA(At, 1, 1); PG8_STAGE(PG8_SB(1, 0), b3, voffB); PG8_STAGE(PG8_SB(1, 1), b3 + hstep, voffB); PG8_STAGE(PG8_SA(1, 0), a3, voffA);
;             PG8_WAIT_V(8); PG8_WAIT_L(0); PG8_BAR; PG8_MMA(1, 0, At, B0); PG8_MMA(1, 1, At, B1); PG8_BAR; PG8_SCHED;
;     ...
;         if constexpr (ALIGN_EPI) { if (wr == 0) PG8_BAR; }
	s_add_i32 s33, 0, 0x18000
	s_add_i32 s42, 0, 0x1c000
	ds_read_b128 v[130:133], v241 offset:32768
	ds_read_b128 v[134:137], v241 offset:33792
	ds_read_b128 v[138:141], v241 offset:34816
	ds_read_b128 v[142:145], v241 offset:35840
	ds_read_b128 v[146:149], v241 offset:49152
	ds_read_b128 v[150:153], v241 offset:50176
	ds_read_b128 v[170:173], v241 offset:51200
	ds_read_b128 v[174:177], v241 offset:52224
	s_add_u32 s20, s20, 0x2b0000
	s_addc_u32 s21, s21, 0
	s_mov_b32 m0, s27
	ds_read_b128 v[178:181], v184 offset:32768
	ds_read_b128 v[186:189], v184 offset:33792
	ds_read_b128 v[190:193], v184 offset:34816
	ds_read_b128 v[194:197], v184 offset:35840
	ds_read_b128 v[198:201], v184 offset:36864
	ds_read_b128 v[202:205], v184 offset:37888
	ds_read_b128 v[206:209], v184 offset:38912
	ds_read_b128 v[210:213], v184 offset:39936
	global_load_lds_dwordx4 v154, s[20:21]
	s_mov_b32 m0, s28
	s_nop 0
	global_load_lds_dwordx4 v158, s[20:21]
	s_waitcnt vmcnt(8) lgkmcnt(0)
	s_barrier
	v_mfma_f32_16x16x32_bf16 v[114:117], v[130:133], v[178:181], v[114:117]
	v_mfma_f32_16x16x32_bf16 v[114:117], v[134:137], v[186:189], v[114:117]
	v_mfma_f32_16x16x32_bf16 v[106:109], v[134:137], v[194:197], v[106:109]
	v_mfma_f32_16x16x32_bf16 v[106:109], v[130:133], v[190:193], v[106:109]
	v_mfma_f32_16x16x32_bf16 v[90:93], v[130:133], v[198:201], v[90:93]
	v_mfma_f32_16x16x32_bf16 v[90:93], v[134:137], v[202:205], v[90:93]
	v_mfma_f32_16x16x32_bf16 v[74:77], v[134:137], v[210:213], v[74:77]
	v_mfma_f32_16x16x32_bf16 v[74:77], v[130:133], v[206:209], v[74:77]
	v_mfma_f32_16x16x32_bf16 v[66:69], v[138:141], v[206:209], v[66:69]
	v_mfma_f32_16x16x32_bf16 v[66:69], v[142:145], v[210:213], v[66:69]
	v_mfma_f32_16x16x32_bf16 v[82:85], v[142:145], v[202:205], v[82:85]
	v_mfma_f32_16x16x32_bf16 v[82:85], v[138:141], v[198:201], v[82:85]
	v_mfma_f32_16x16x32_bf16 v[98:101], v[138:141], v[190:193], v[98:101]
	v_mfma_f32_16x16x32_bf16 v[98:101], v[142:145], v[194:197], v[98:101]
	v_mfma_f32_16x16x32_bf16 v[118:121], v[142:145], v[186:189], v[118:121]
	v_mfma_f32_16x16x32_bf16 v[118:121], v[138:141], v[178:181], v[118:121]
	v_mfma_f32_16x16x32_bf16 v[122:125], v[146:149], v[178:181], v[122:125]
	v_mfma_f32_16x16x32_bf16 v[122:125], v[150:153], v[186:189], v[122:125]
	v_mfma_f32_16x16x32_bf16 v[110:113], v[150:153], v[194:197], v[110:113]
	v_mfma_f32_16x16x32_bf16 v[110:113], v[146:149], v[190:193], v[110:113]
	v_mfma_f32_16x16x32_bf16 v[94:97], v[146:149], v[198:201], v[94:97]
	v_mfma_f32_16x16x32_bf16 v[94:97], v[150:153], v[202:205], v[94:97]
	v_mfma_f32_16x16x32_bf16 v[78:81], v[150:153], v[210:213], v[78:81]
	v_mfma_f32_16x16x32_bf16 v[78:81], v[146:149], v[206:209], v[78:81]
	v_mfma_f32_16x16x32_bf16 v[70:73], v[170:173], v[206:209], v[70:73]
	v_mfma_f32_16x16x32_bf16 v[70:73], v[174:177], v[210:213], v[70:73]
	v_mfma_f32_16x16x32_bf16 v[86:89], v[174:177], v[202:205], v[86:89]
	v_mfma_f32_16x16x32_bf16 v[86:89], v[170:173], v[198:201], v[86:89]
	v_mfma_f32_16x16x32_bf16 v[102:105], v[170:173], v[190:193], v[102:105]
	v_mfma_f32_16x16x32_bf16 v[102:105], v[174:177], v[194:197], v[102:105]
	v_mfma_f32_16x16x32_bf16 v[126:129], v[174:177], v[186:189], v[126:129]
	v_mfma_f32_16x16x32_bf16 v[126:129], v[170:173], v[178:181], v[126:129]
	s_barrier
	s_add_i32 s20, s33, s24
	s_add_i32 m0, s20, 0xffffff80
	ds_read_b128 v[178:181], v184 offset:49152
	ds_read_b128 v[186:189], v184 offset:50176
	ds_read_b128 v[190:193], v184 offset:51200
	ds_read_b128 v[194:197], v184 offset:52224
	ds_read_b128 v[198:201], v184 offset:53248
	ds_read_b128 v[202:205], v184 offset:54272
	ds_read_b128 v[206:209], v184 offset:55296
	ds_read_b128 v[210:213], v184 offset:56320
	global_load_lds_dwordx4 v156, s[16:17] offset:128
	s_add_i32 m0, s20, 0x1f80
	s_add_i32 s20, s42, s24
	global_load_lds_dwordx4 v160, s[16:17] offset:128
	s_add_u32 s16, s16, 0x2b0080
	s_addc_u32 s17, s17, 0
	s_mov_b32 m0, s20
	s_nop 0
	global_load_lds_dwordx4 v156, s[16:17]
	s_add_i32 m0, s20, 0x2000
	s_nop 0
	global_load_lds_dwordx4 v160, s[16:17]
	s_mov_b32 m0, s30
	s_nop 0
	global_load_lds_dwordx4 v154, s[100:101]
	s_mov_b32 m0, s31
	s_nop 0
	global_load_lds_dwordx4 v158, s[100:101]
	s_waitcnt vmcnt(8) lgkmcnt(0)
	s_barrier
	v_mfma_f32_16x16x32_bf16 v[58:61], v[130:133], v[178:181], v[58:61]
	v_mfma_f32_16x16x32_bf16 v[58:61], v[134:137], v[186:189], v[58:61]
	v_mfma_f32_16x16x32_bf16 v[42:45], v[134:137], v[194:197], v[42:45]
	v_mfma_f32_16x16x32_bf16 v[42:45], v[130:133], v[190:193], v[42:45]
	v_mfma_f32_16x16x32_bf16 v[26:29], v[130:133], v[198:201], v[26:29]
	v_mfma_f32_16x16x32_bf16 v[26:29], v[134:137], v[202:205], v[26:29]
	v_mfma_f32_16x16x32_bf16 v[6:9], v[134:137], v[210:213], v[6:9]
	v_mfma_f32_16x16x32_bf16 v[6:9], v[130:133], v[206:209], v[6:9]
	v_mfma_f32_16x16x32_bf16 v[2:5], v[138:141], v[206:209], v[2:5]
	v_mfma_f32_16x16x32_bf16 v[2:5], v[142:145], v[210:213], v[2:5]
	v_mfma_f32_16x16x32_bf16 v[18:21], v[142:145], v[202:205], v[18:21]
	v_mfma_f32_16x16x32_bf16 v[18:21], v[138:141], v[198:201], v[18:21]
	v_mfma_f32_16x16x32_bf16 v[34:37], v[138:141], v[190:193], v[34:37]
	v_mfma_f32_16x16x32_bf16 v[34:37], v[142:145], v[194:197], v[34:37]
	v_mfma_f32_16x16x32_bf16 v[54:57], v[142:145], v[186:189], v[54:57]
	v_mfma_f32_16x16x32_bf16 v[54:57], v[138:141], v[178:181], v[54:57]
	v_mfma_f32_16x16x32_bf16 v[62:65], v[146:149], v[178:181], v[62:65]
	v_mfma_f32_16x16x32_bf16 v[62:65], v[150:153], v[186:189], v[62:65]
	v_mfma_f32_16x16x32_bf16 v[46:49], v[150:153], v[194:197], v[46:49]
	v_mfma_f32_16x16x32_bf16 v[46:49], v[146:149], v[190:193], v[46:49]
	v_mfma_f32_16x16x32_bf16 v[30:33], v[146:149], v[198:201], v[30:33]
	v_mfma_f32_16x16x32_bf16 v[30:33], v[150:153], v[202:205], v[30:33]
	v_mfma_f32_16x16x32_bf16 v[10:13], v[150:153], v[210:213], v[10:13]
	v_mfma_f32_16x16x32_bf16 v[10:13], v[146:149], v[206:209], v[10:13]
	v_mfma_f32_16x16x32_bf16 v[14:17], v[170:173], v[206:209], v[14:17]
	v_mfma_f32_16x16x32_bf16 v[14:17], v[174:177], v[210:213], v[14:17]
	v_mfma_f32_16x16x32_bf16 v[22:25], v[174:177], v[202:205], v[22:25]
	v_mfma_f32_16x16x32_bf16 v[22:25], v[170:173], v[198:201], v[22:25]
	v_mfma_f32_16x16x32_bf16 v[38:41], v[170:173], v[190:193], v[38:41]
	v_mfma_f32_16x16x32_bf16 v[38:41], v[174:177], v[194:197], v[38:41]
	v_mfma_f32_16x16x32_bf16 v[50:53], v[174:177], v[186:189], v[50:53]
	v_mfma_f32_16x16x32_bf16 v[50:53], v[170:173], v[178:181], v[50:53]
	s_barrier
	s_add_i32 s48, s48, 2
	s_add_u32 s18, s18, 0x100
	s_addc_u32 s19, s19, 0
	s_add_u32 s46, s46, 0x100
	s_addc_u32 s47, s47, 0
	s_cmpk_gt_u32 s48, 0xa9
	s_cbranch_scc0 .LBB0_1801
	s_and_b64 vcc, exec, s[12:13]
	s_cbranch_vccz .LBB0_1804
	s_barrier
